# GEMM K-loops: first iteration peeled with C=0 MFMAs, accumulator clearing (128 v_mov per unit) removed
# speedup vs baseline: 1.0154x; 1.0087x over previous
; #define PG8_STAGE(bufoff, gbase, voff) do { _Pragma("unroll") for (int _i = 0; _i < 2; ++_i) \
;         __builtin_amdgcn_global_load_lds((const unsigned*)((const char*)(gbase) + (voff)[_i]), (PG8_LAS unsigned*)(lds + (bufoff) + ldsw + _i * 8192), 16, 0, 0); } while (0)
; #define PG8_LDA(dst, b, h) do { _Pragma("unroll") for (int m = 0; m < 4; ++m) _Pragma("unroll") for (int k = 0; k < 2; ++k) dst[m][k] = *(const PG8_LAS bf16x8*)(lds + PG8_SA(b, h) + aoff + m * 2048 + k * 1024); } while (0)
; #define PG8_LDB(dst, b, h) do { _Pragma("unroll") for (int n = 0; n < 2; ++n) _Pragma("unroll") for (int k = 0; k < 2; ++k) dst[n][k] = *(const PG8_LAS bf16x8*)(lds + PG8_SB(b, h) + boff + n * 2048 + k * 1024); } while (0)
; #define PG8_MMA(ai, bj, At, Bt) do { __builtin_amdgcn_s_setprio(1); _Pragma("unroll") for (int m = 0; m < 4; ++m) _Pragma("unroll") for (int n = 0; n < 2; ++n) _Pragma("unroll") for (int k = 0; k < 2; ++k) \
;         acc[ai][bj][m][n] = __builtin_amdgcn_mfma_f32_16x16x32_bf16(Bt[n][k], At[m][k], acc[ai][bj][m][n], 0, 0, 0); __builtin_amdgcn_s_setprio(0); } while (0)
; #define PG8_WAIT_V(n) asm volatile("s_waitcnt vmcnt(" #n ")" ::: "memory")
; #define PG8_WAIT_L(n) asm volatile("s_waitcnt lgkmcnt(" #n ")" ::: "memory")
; #define PG8_BAR __builtin_amdgcn_s_barrier()
; #define PG8_SCHED __builtin_amdgcn_sched_barrier(0)
; template <class Epi, class Sched, bool ALIGN_EPI = false, bool SP2 = false>
; __device__ __forceinline__ void gemm_phase(PG8_LAS unsigned char* lds, const Gemm g, const Sched& S, const Epi& E) {
;     ...
;     f32x4 acc[2][2][4][2];
; #pragma unroll
;     for (int a = 0; a < 2; ++a)
; #pragma unroll
;         for (int b = 0; b < 2; ++b)
; #pragma unroll
;             for (int m = 0; m < 4; ++m)
; #pragma unroll
;                 for (int n = 0; n < 2; ++n) acc[a][b][m][n] = (f32x4){0.f, 0.f, 0.f, 0.f};
;     ...
;             PG8_LDB(B0, 0, 0); PG8_LDB(B1, 0, 1); PG8_SCHED; PG8_LDA(At, 0, 0); PG8_STAGE(PG8_SA(1, 1), a1 + hstep, voffA);
;             PG8_WAIT_V(8); PG8_WAIT_L(0); PG8_BAR; PG8_MMA(0, 0, At, B0); PG8_MMA(0, 1, At, B1); PG8_BAR; PG8_SCHED;
;             PG8_LDA(At, 0, 1); PG8_STAGE(PG8_SB(0, 0), b2, voffB); PG8_STAGE(PG8_SB(0, 1), b2 + hstep, voffB); PG8_STAGE(PG8_SA(0, 0), a2, voffA);
;             PG8_WAIT_V(8); PG8_WAIT_L(0); PG8_BAR; PG8_MMA(1, 0, At, B0); PG8_MMA(1, 1, At, B1); PG8_BAR; PG8_SCHED;
.LBB0_188:
	s_ashr_i32 s51, s50, 31
	s_lshl_b64 s[52:53], s[50:51], 19
	s_add_u32 s52, s46, s52
	s_addc_u32 s53, s47, s53
	s_and_b64 s[54:55], s[4:5], exec
	s_cselect_b32 s51, s53, s59
	s_cselect_b32 s83, s52, s58
	s_ashr_i32 s49, s48, 31
	s_lshl_b64 s[54:55], s[48:49], 19
	s_add_u32 s54, s30, s54
	s_addc_u32 s55, s31, s55
	s_and_b64 s[66:67], s[4:5], exec
	s_cselect_b32 s49, s55, s65
	s_cselect_b32 s84, s54, s64
	s_add_u32 s58, s58, 0x40080
	s_addc_u32 s59, s59, 0
	s_add_u32 s85, s64, 0x100
	s_addc_u32 s86, s65, 0
	s_mov_b32 s87, -2
	ds_read_b128 v[168:171], v150
	ds_read_b128 v[172:175], v151
	ds_read_b128 v[176:179], v152
	ds_read_b128 v[180:183], v153
	ds_read_b128 v[184:187], v154
	ds_read_b128 v[188:191], v155
	ds_read_b128 v[192:195], v156
	ds_read_b128 v[196:199], v157
	s_add_u32 s64, s58, 0xfffc0080
	s_addc_u32 s65, s59, -1
	s_cmp_eq_u32 s87, 12
	s_cselect_b32 s67, s51, s65
	s_cselect_b32 s66, s83, s64
	s_cselect_b32 s65, s49, s86
	s_cselect_b32 s64, s84, s85
	s_mov_b32 m0, s79
	v_lshl_add_u64 v[146:147], s[58:59], 0, v[136:137]
	ds_read_b128 v[200:203], v148
	ds_read_b128 v[204:207], v148 offset:1024
	ds_read_b128 v[208:211], v148 offset:2048
	ds_read_b128 v[212:215], v148 offset:3072
	ds_read_b128 v[216:219], v148 offset:4096
	ds_read_b128 v[224:227], v148 offset:5120
	ds_read_b128 v[228:231], v148 offset:6144
	ds_read_b128 v[232:235], v148 offset:7168
	global_load_lds_dwordx4 v[146:147], off
	v_lshl_add_u64 v[146:147], s[58:59], 0, v[138:139]
	s_mov_b32 m0, s80
	s_nop 0
	global_load_lds_dwordx4 v[146:147], off
	s_waitcnt vmcnt(8)
	s_waitcnt lgkmcnt(0)
	s_barrier
	s_setprio 1
	s_waitcnt lgkmcnt(0)
	v_mfma_f32_16x16x32_bf16 v[124:127], v[168:171], v[200:203], 0
	v_mfma_f32_16x16x32_bf16 v[120:123], v[176:179], v[200:203], 0
	v_mfma_f32_16x16x32_bf16 v[112:115], v[168:171], v[208:211], 0
	v_mfma_f32_16x16x32_bf16 v[104:107], v[176:179], v[208:211], 0
	v_mfma_f32_16x16x32_bf16 v[96:99], v[168:171], v[216:219], 0
	v_mfma_f32_16x16x32_bf16 v[88:91], v[176:179], v[216:219], 0
	v_mfma_f32_16x16x32_bf16 v[80:83], v[168:171], v[228:231], 0
	v_mfma_f32_16x16x32_bf16 v[72:75], v[176:179], v[228:231], 0
	v_mfma_f32_16x16x32_bf16 v[124:127], v[172:175], v[204:207], v[124:127]
	v_mfma_f32_16x16x32_bf16 v[120:123], v[180:183], v[204:207], v[120:123]
	v_mfma_f32_16x16x32_bf16 v[112:115], v[172:175], v[212:215], v[112:115]
	v_mfma_f32_16x16x32_bf16 v[104:107], v[180:183], v[212:215], v[104:107]
	v_mfma_f32_16x16x32_bf16 v[96:99], v[172:175], v[224:227], v[96:99]
	v_mfma_f32_16x16x32_bf16 v[88:91], v[180:183], v[224:227], v[88:91]
	v_mfma_f32_16x16x32_bf16 v[80:83], v[172:175], v[232:235], v[80:83]
	v_mfma_f32_16x16x32_bf16 v[72:75], v[180:183], v[232:235], v[72:75]
	s_setprio 0
	s_setprio 1
	v_mfma_f32_16x16x32_bf16 v[116:119], v[184:187], v[200:203], 0
	v_mfma_f32_16x16x32_bf16 v[108:111], v[192:195], v[200:203], 0
	v_mfma_f32_16x16x32_bf16 v[100:103], v[184:187], v[208:211], 0
	v_mfma_f32_16x16x32_bf16 v[92:95], v[192:195], v[208:211], 0
	v_mfma_f32_16x16x32_bf16 v[84:87], v[184:187], v[216:219], 0
	v_mfma_f32_16x16x32_bf16 v[76:79], v[192:195], v[216:219], 0
	v_mfma_f32_16x16x32_bf16 v[68:71], v[184:187], v[228:231], 0
	v_mfma_f32_16x16x32_bf16 v[64:67], v[192:195], v[228:231], 0
	v_mfma_f32_16x16x32_bf16 v[116:119], v[188:191], v[204:207], v[116:119]
	v_mfma_f32_16x16x32_bf16 v[108:111], v[196:199], v[204:207], v[108:111]
	v_mfma_f32_16x16x32_bf16 v[100:103], v[188:191], v[212:215], v[100:103]
	v_mfma_f32_16x16x32_bf16 v[92:95], v[196:199], v[212:215], v[92:95]
	v_mfma_f32_16x16x32_bf16 v[84:87], v[188:191], v[224:227], v[84:87]
	v_mfma_f32_16x16x32_bf16 v[76:79], v[196:199], v[224:227], v[76:79]
	v_mfma_f32_16x16x32_bf16 v[68:71], v[188:191], v[232:235], v[68:71]
	v_mfma_f32_16x16x32_bf16 v[64:67], v[196:199], v[232:235], v[64:67]
	s_setprio 0
	s_barrier
	s_mov_b32 m0, s3
	v_lshl_add_u64 v[146:147], s[64:65], 0, v[130:131]
	s_add_u32 s88, s64, 0x40000
	ds_read_b128 v[200:203], v148 offset:16384
	ds_read_b128 v[204:207], v148 offset:17408
	ds_read_b128 v[208:211], v148 offset:18432
	ds_read_b128 v[212:215], v148 offset:19456
	ds_read_b128 v[216:219], v148 offset:20480
	ds_read_b128 v[224:227], v148 offset:21504
	ds_read_b128 v[228:231], v148 offset:22528
	ds_read_b128 v[232:235], v148 offset:23552
	global_load_lds_dwordx4 v[146:147], off
	v_lshl_add_u64 v[220:221], s[64:65], 0, v[134:135]
	s_mov_b32 m0, s14
	s_addc_u32 s89, s65, 0
	global_load_lds_dwordx4 v[220:221], off
	v_lshl_add_u64 v[236:237], s[88:89], 0, v[130:131]
	s_mov_b32 m0, s15
	v_lshl_add_u64 v[238:239], s[66:67], 0, v[132:133]
	global_load_lds_dwordx4 v[236:237], off
	v_lshl_add_u64 v[236:237], s[88:89], 0, v[134:135]
	s_mov_b32 m0, s33
	s_nop 0
	global_load_lds_dwordx4 v[236:237], off
	v_lshl_add_u64 v[236:237], s[66:67], 0, v[128:129]
	s_mov_b32 m0, s1
	s_nop 0
	global_load_lds_dwordx4 v[236:237], off
	s_mov_b32 m0, s39
	s_nop 0
	global_load_lds_dwordx4 v[238:239], off
	s_waitcnt vmcnt(8)
	s_waitcnt lgkmcnt(0)
	s_barrier
; #define PG8_STAGE(bufoff, gbase, voff) do { _Pragma("unroll") for (int _i = 0; _i < 2; ++_i) \
;         __builtin_amdgcn_global_load_lds((const unsigned*)((const char*)(gbase) + (voff)[_i]), (PG8_LAS unsigned*)(lds + (bufoff) + ldsw + _i * 8192), 16, 0, 0); } while (0)
; #define PG8_LDA(dst, b, h) do { _Pragma("unroll") for (int m = 0; m < 4; ++m) _Pragma("unroll") for (int k = 0; k < 2; ++k) dst[m][k] = *(const PG8_LAS bf16x8*)(lds + PG8_SA(b, h) + aoff + m * 2048 + k * 1024); } while (0)
; #define PG8_LDB(dst, b, h) do { _Pragma("unroll") for (int n = 0; n < 2; ++n) _Pragma("unroll") for (int k = 0; k < 2; ++k) dst[n][k] = *(const PG8_LAS bf16x8*)(lds + PG8_SB(b, h) + boff + n * 2048 + k * 1024); } while (0)
; #define PG8_MMA(ai, bj, At, Bt) do { __builtin_amdgcn_s_setprio(1); _Pragma("unroll") for (int m = 0; m < 4; ++m) _Pragma("unroll") for (int n = 0; n < 2; ++n) _Pragma("unroll") for (int k = 0; k < 2; ++k) \
;         acc[ai][bj][m][n] = __builtin_amdgcn_mfma_f32_16x16x32_bf16(Bt[n][k], At[m][k], acc[ai][bj][m][n], 0, 0, 0); __builtin_amdgcn_s_setprio(0); } while (0)
; #define PG8_WAIT_V(n) asm volatile("s_waitcnt vmcnt(" #n ")" ::: "memory")
; #define PG8_WAIT_L(n) asm volatile("s_waitcnt lgkmcnt(" #n ")" ::: "memory")
; #define PG8_BAR __builtin_amdgcn_s_barrier()
; #define PG8_SCHED __builtin_amdgcn_sched_barrier(0)
; template <class Epi, class Sched, bool ALIGN_EPI = false, bool SP2 = false>
; __device__ __forceinline__ void gemm_phase(PG8_LAS unsigned char* lds, const Gemm g, const Sched& S, const Epi& E) {
;     ...
;             PG8_WAIT_V(8); PG8_WAIT_L(0); PG8_BAR; PG8_MMA(1, 0, At, B0); PG8_MMA(1, 1, At, B1); PG8_BAR; PG8_SCHED;
;             PG8_LDB(B0, 1, 0); PG8_LDB(B1, 1, 1); PG8_SCHED; PG8_LDA(At, 1, 0); PG8_STAGE(PG8_SA(0, 1), a2 + hstep, voffA);
;             PG8_WAIT_V(8); PG8_WAIT_L(0); PG8_BAR; PG8_MMA(0, 0, At, B0); PG8_MMA(0, 1, At, B1); PG8_BAR; PG8_SCHED;
	s_setprio 1
	s_waitcnt lgkmcnt(0)
	v_mfma_f32_16x16x32_bf16 v[60:63], v[168:171], v[200:203], 0
	v_mfma_f32_16x16x32_bf16 v[56:59], v[176:179], v[200:203], 0
	v_mfma_f32_16x16x32_bf16 v[48:51], v[168:171], v[208:211], 0
	v_mfma_f32_16x16x32_bf16 v[40:43], v[176:179], v[208:211], 0
	v_mfma_f32_16x16x32_bf16 v[32:35], v[168:171], v[216:219], 0
	v_mfma_f32_16x16x32_bf16 v[24:27], v[176:179], v[216:219], 0
	v_mfma_f32_16x16x32_bf16 v[16:19], v[168:171], v[228:231], 0
	v_mfma_f32_16x16x32_bf16 v[8:11], v[176:179], v[228:231], 0
	v_mfma_f32_16x16x32_bf16 v[60:63], v[172:175], v[204:207], v[60:63]
	v_mfma_f32_16x16x32_bf16 v[56:59], v[180:183], v[204:207], v[56:59]
	v_mfma_f32_16x16x32_bf16 v[48:51], v[172:175], v[212:215], v[48:51]
	v_mfma_f32_16x16x32_bf16 v[40:43], v[180:183], v[212:215], v[40:43]
	v_mfma_f32_16x16x32_bf16 v[32:35], v[172:175], v[224:227], v[32:35]
	v_mfma_f32_16x16x32_bf16 v[24:27], v[180:183], v[224:227], v[24:27]
	v_mfma_f32_16x16x32_bf16 v[16:19], v[172:175], v[232:235], v[16:19]
	v_mfma_f32_16x16x32_bf16 v[8:11], v[180:183], v[232:235], v[8:11]
	s_setprio 0
	s_setprio 1
	v_mfma_f32_16x16x32_bf16 v[52:55], v[184:187], v[200:203], 0
	v_mfma_f32_16x16x32_bf16 v[44:47], v[192:195], v[200:203], 0
	v_mfma_f32_16x16x32_bf16 v[36:39], v[184:187], v[208:211], 0
	v_mfma_f32_16x16x32_bf16 v[28:31], v[192:195], v[208:211], 0
	v_mfma_f32_16x16x32_bf16 v[20:23], v[184:187], v[216:219], 0
	v_mfma_f32_16x16x32_bf16 v[12:15], v[192:195], v[216:219], 0
	v_mfma_f32_16x16x32_bf16 v[4:7], v[184:187], v[228:231], 0
	v_mfma_f32_16x16x32_bf16 v[0:3], v[192:195], v[228:231], 0
	v_mfma_f32_16x16x32_bf16 v[52:55], v[188:191], v[204:207], v[52:55]
	v_mfma_f32_16x16x32_bf16 v[44:47], v[196:199], v[204:207], v[44:47]
	v_mfma_f32_16x16x32_bf16 v[36:39], v[188:191], v[212:215], v[36:39]
	v_mfma_f32_16x16x32_bf16 v[28:31], v[196:199], v[212:215], v[28:31]
	v_mfma_f32_16x16x32_bf16 v[20:23], v[188:191], v[224:227], v[20:23]
	v_mfma_f32_16x16x32_bf16 v[12:15], v[196:199], v[224:227], v[12:15]
	v_mfma_f32_16x16x32_bf16 v[4:7], v[188:191], v[232:235], v[4:7]
	v_mfma_f32_16x16x32_bf16 v[0:3], v[196:199], v[232:235], v[0:3]
	s_setprio 0
	s_barrier
	ds_read_b128 v[168:171], v158
	ds_read_b128 v[172:175], v159
	ds_read_b128 v[176:179], v160
	ds_read_b128 v[180:183], v161
	ds_read_b128 v[184:187], v162
	ds_read_b128 v[188:191], v163
	ds_read_b128 v[192:195], v164
	ds_read_b128 v[196:199], v165
	s_add_u32 s66, s66, 0x40000
	s_addc_u32 s67, s67, 0
	s_mov_b32 m0, s43
	v_lshl_add_u64 v[240:241], s[66:67], 0, v[128:129]
	ds_read_b128 v[200:203], v148 offset:32768
	ds_read_b128 v[204:207], v148 offset:33792
	ds_read_b128 v[208:211], v148 offset:34816
	ds_read_b128 v[212:215], v148 offset:35840
	ds_read_b128 v[216:219], v148 offset:36864
	ds_read_b128 v[224:227], v148 offset:37888
	ds_read_b128 v[228:231], v148 offset:38912
	ds_read_b128 v[232:235], v148 offset:39936
	global_load_lds_dwordx4 v[240:241], off
	v_lshl_add_u64 v[240:241], s[66:67], 0, v[132:133]
	s_mov_b32 m0, s57
	s_nop 0
	global_load_lds_dwordx4 v[240:241], off
	s_waitcnt vmcnt(8)
	s_waitcnt lgkmcnt(0)
	s_barrier
	s_setprio 1
	s_waitcnt lgkmcnt(0)
	v_mfma_f32_16x16x32_bf16 v[124:127], v[168:171], v[200:203], v[124:127]
	v_mfma_f32_16x16x32_bf16 v[120:123], v[176:179], v[200:203], v[120:123]
	v_mfma_f32_16x16x32_bf16 v[112:115], v[168:171], v[208:211], v[112:115]
	v_mfma_f32_16x16x32_bf16 v[104:107], v[176:179], v[208:211], v[104:107]
	v_mfma_f32_16x16x32_bf16 v[96:99], v[168:171], v[216:219], v[96:99]
	v_mfma_f32_16x16x32_bf16 v[88:91], v[176:179], v[216:219], v[88:91]
	v_mfma_f32_16x16x32_bf16 v[80:83], v[168:171], v[228:231], v[80:83]
	v_mfma_f32_16x16x32_bf16 v[72:75], v[176:179], v[228:231], v[72:75]
	v_mfma_f32_16x16x32_bf16 v[124:127], v[172:175], v[204:207], v[124:127]
	v_mfma_f32_16x16x32_bf16 v[120:123], v[180:183], v[204:207], v[120:123]
	v_mfma_f32_16x16x32_bf16 v[112:115], v[172:175], v[212:215], v[112:115]
	v_mfma_f32_16x16x32_bf16 v[104:107], v[180:183], v[212:215], v[104:107]
	v_mfma_f32_16x16x32_bf16 v[96:99], v[172:175], v[224:227], v[96:99]
	v_mfma_f32_16x16x32_bf16 v[88:91], v[180:183], v[224:227], v[88:91]
	v_mfma_f32_16x16x32_bf16 v[80:83], v[172:175], v[232:235], v[80:83]
	v_mfma_f32_16x16x32_bf16 v[72:75], v[180:183], v[232:235], v[72:75]
	s_setprio 0
	s_setprio 1
	v_mfma_f32_16x16x32_bf16 v[116:119], v[184:187], v[200:203], v[116:119]
	v_mfma_f32_16x16x32_bf16 v[108:111], v[192:195], v[200:203], v[108:111]
	v_mfma_f32_16x16x32_bf16 v[100:103], v[184:187], v[208:211], v[100:103]
	v_mfma_f32_16x16x32_bf16 v[92:95], v[192:195], v[208:211], v[92:95]
	v_mfma_f32_16x16x32_bf16 v[84:87], v[184:187], v[216:219], v[84:87]
	v_mfma_f32_16x16x32_bf16 v[76:79], v[192:195], v[216:219], v[76:79]
	v_mfma_f32_16x16x32_bf16 v[68:71], v[184:187], v[228:231], v[68:71]
	v_mfma_f32_16x16x32_bf16 v[64:67], v[192:195], v[228:231], v[64:67]
	v_mfma_f32_16x16x32_bf16 v[116:119], v[188:191], v[204:207], v[116:119]
	v_mfma_f32_16x16x32_bf16 v[108:111], v[196:199], v[204:207], v[108:111]
	v_mfma_f32_16x16x32_bf16 v[100:103], v[188:191], v[212:215], v[100:103]
	v_mfma_f32_16x16x32_bf16 v[92:95], v[196:199], v[212:215], v[92:95]
	v_mfma_f32_16x16x32_bf16 v[84:87], v[188:191], v[224:227], v[84:87]
	v_mfma_f32_16x16x32_bf16 v[76:79], v[196:199], v[224:227], v[76:79]
	v_mfma_f32_16x16x32_bf16 v[68:71], v[188:191], v[232:235], v[68:71]
	v_mfma_f32_16x16x32_bf16 v[64:67], v[196:199], v[232:235], v[64:67]
	s_setprio 0
	s_barrier
; #define PG8_STAGE(bufoff, gbase, voff) do { _Pragma("unroll") for (int _i = 0; _i < 2; ++_i) \
;         __builtin_amdgcn_global_load_lds((const unsigned*)((const char*)(gbase) + (voff)[_i]), (PG8_LAS unsigned*)(lds + (bufoff) + ldsw + _i * 8192), 16, 0, 0); } while (0)
; #define PG8_LDA(dst, b, h) do { _Pragma("unroll") for (int m = 0; m < 4; ++m) _Pragma("unroll") for (int k = 0; k < 2; ++k) dst[m][k] = *(const PG8_LAS bf16x8*)(lds + PG8_SA(b, h) + aoff + m * 2048 + k * 1024); } while (0)
; #define PG8_LDB(dst, b, h) do { _Pragma("unroll") for (int n = 0; n < 2; ++n) _Pragma("unroll") for (int k = 0; k < 2; ++k) dst[n][k] = *(const PG8_LAS bf16x8*)(lds + PG8_SB(b, h) + boff + n * 2048 + k * 1024); } while (0)
; template <class Epi, class Sched, bool ALIGN_EPI = false, bool SP2 = false>
; __device__ __forceinline__ void gemm_phase(PG8_LAS unsigned char* lds, const Gemm g, const Sched& S, const Epi& E) {
;     ...
;         for (int t = 0; t < nt; t += 2) {
;             const bool last = (t == nt - 2);
;             const char* a1 = cA + (size_t)(t + 1) * kstep;
;             const char* a2 = last ? nA : cA + (size_t)(t + 2) * kstep; const char* b2 = last ? nB : cB + (size_t)(t + 2) * kstep;
;             const char* a3 = a2 + kstep; const char* b3 = b2 + kstep;
;             if (last && has_next) S.a_ready(nxt);
;             if constexpr (SP2) {
;             PG8_LDB(B0, 0, 0); PG8_LDB(B1, 0, 1); PG8_SCHED; PG8_LDA(At, 0, 0); PG8_STAGE(PG8_SA(1, 1), a1 + hstep, voffA);
;             PG8_WAIT_V(8); PG8_WAIT_L(0); PG8_BAR; PG8_MMA(0, 0, At, B0); PG8_MMA(0, 1, At, B1); PG8_BAR; PG8_SCHED;
;             PG8_LDA(At, 0, 1); PG8_STAGE(PG8_SB(0, 0), b2, voffB); PG8_STAGE(PG8_SB(0, 1), b2 + hstep, voffB); PG8_STAGE(PG8_SA(0, 0), a2, voffA);
;             PG8_WAIT_V(8); PG8_WAIT_L(0); PG8_BAR; PG8_MMA(1, 0, At, B0); PG8_MMA(1, 1, At, B1); PG8_BAR; PG8_SCHED;
;             PG8_LDB(B0, 1, 0); PG8_LDB(B1, 1, 1); PG8_SCHED; PG8_LDA(At, 1, 0); PG8_STAGE(PG8_SA(0, 1), a2 + hstep, voffA);
;             PG8_WAIT_V(8); PG8_WAIT_L(0); PG8_BAR; PG8_MMA(0, 0, At, B0); PG8_MMA(0, 1, At, B1); PG8_BAR; PG8_SCHED;
;             PG8_LDA(At, 1, 1); PG8_STAGE(PG8_SB(1, 0), b3, voffB); PG8_STAGE(PG8_SB(1, 1), b3 + hstep, voffB); PG8_STAGE(PG8_SA(1, 0), a3, voffA);
;             PG8_WAIT_V(8); PG8_WAIT_L(0); PG8_BAR; PG8_MMA(1, 0, At, B0); PG8_MMA(1, 1, At, B1); PG8_BAR; PG8_SCHED;
	s_mov_b32 m0, s71
	v_lshl_add_u64 v[146:147], v[146:147], 0, s[10:11]
	s_add_u32 s64, s64, 0x40080
	ds_read_b128 v[200:203], v148 offset:49152
	ds_read_b128 v[204:207], v148 offset:50176
	ds_read_b128 v[208:211], v148 offset:51200
	ds_read_b128 v[212:215], v148 offset:52224
	ds_read_b128 v[216:219], v148 offset:53248
	ds_read_b128 v[224:227], v148 offset:54272
	ds_read_b128 v[228:231], v148 offset:55296
	ds_read_b128 v[232:235], v148 offset:56320
	global_load_lds_dwordx4 v[146:147], off
	v_lshl_add_u64 v[146:147], v[220:221], 0, s[10:11]
	s_mov_b32 m0, s72
	s_addc_u32 s65, s65, 0
	global_load_lds_dwordx4 v[146:147], off
	v_lshl_add_u64 v[146:147], s[64:65], 0, v[130:131]
	s_mov_b32 m0, s75
	s_nop 0
	global_load_lds_dwordx4 v[146:147], off
	v_lshl_add_u64 v[146:147], s[64:65], 0, v[134:135]
	s_mov_b32 m0, s76
	s_nop 0
	global_load_lds_dwordx4 v[146:147], off
	v_lshl_add_u64 v[146:147], v[236:237], 0, s[10:11]
	s_mov_b32 m0, s73
	s_nop 0
	global_load_lds_dwordx4 v[146:147], off
	v_lshl_add_u64 v[146:147], v[238:239], 0, s[10:11]
	s_mov_b32 m0, s74
	s_nop 0
	global_load_lds_dwordx4 v[146:147], off
	s_waitcnt vmcnt(8)
	s_waitcnt lgkmcnt(0)
	s_barrier
	s_setprio 1
	s_waitcnt lgkmcnt(0)
	v_mfma_f32_16x16x32_bf16 v[60:63], v[168:171], v[200:203], v[60:63]
	v_mfma_f32_16x16x32_bf16 v[56:59], v[176:179], v[200:203], v[56:59]
	v_mfma_f32_16x16x32_bf16 v[48:51], v[168:171], v[208:211], v[48:51]
	v_mfma_f32_16x16x32_bf16 v[40:43], v[176:179], v[208:211], v[40:43]
	v_mfma_f32_16x16x32_bf16 v[32:35], v[168:171], v[216:219], v[32:35]
	v_mfma_f32_16x16x32_bf16 v[24:27], v[176:179], v[216:219], v[24:27]
	v_mfma_f32_16x16x32_bf16 v[16:19], v[168:171], v[228:231], v[16:19]
	v_mfma_f32_16x16x32_bf16 v[8:11], v[176:179], v[228:231], v[8:11]
	v_mfma_f32_16x16x32_bf16 v[60:63], v[172:175], v[204:207], v[60:63]
	v_mfma_f32_16x16x32_bf16 v[56:59], v[180:183], v[204:207], v[56:59]
	v_mfma_f32_16x16x32_bf16 v[48:51], v[172:175], v[212:215], v[48:51]
	v_mfma_f32_16x16x32_bf16 v[40:43], v[180:183], v[212:215], v[40:43]
	v_mfma_f32_16x16x32_bf16 v[32:35], v[172:175], v[224:227], v[32:35]
	v_mfma_f32_16x16x32_bf16 v[24:27], v[180:183], v[224:227], v[24:27]
	v_mfma_f32_16x16x32_bf16 v[16:19], v[172:175], v[232:235], v[16:19]
	v_mfma_f32_16x16x32_bf16 v[8:11], v[180:183], v[232:235], v[8:11]
	s_setprio 0
	s_setprio 1
	v_mfma_f32_16x16x32_bf16 v[52:55], v[184:187], v[200:203], v[52:55]
	v_mfma_f32_16x16x32_bf16 v[44:47], v[192:195], v[200:203], v[44:47]
	v_mfma_f32_16x16x32_bf16 v[36:39], v[184:187], v[208:211], v[36:39]
	v_mfma_f32_16x16x32_bf16 v[28:31], v[192:195], v[208:211], v[28:31]
	v_mfma_f32_16x16x32_bf16 v[20:23], v[184:187], v[216:219], v[20:23]
	v_mfma_f32_16x16x32_bf16 v[12:15], v[192:195], v[216:219], v[12:15]
	v_mfma_f32_16x16x32_bf16 v[4:7], v[184:187], v[228:231], v[4:7]
	v_mfma_f32_16x16x32_bf16 v[0:3], v[192:195], v[228:231], v[0:3]
	v_mfma_f32_16x16x32_bf16 v[52:55], v[188:191], v[204:207], v[52:55]
	v_mfma_f32_16x16x32_bf16 v[44:47], v[196:199], v[204:207], v[44:47]
	v_mfma_f32_16x16x32_bf16 v[36:39], v[188:191], v[212:215], v[36:39]
	v_mfma_f32_16x16x32_bf16 v[28:31], v[196:199], v[212:215], v[28:31]
	v_mfma_f32_16x16x32_bf16 v[20:23], v[188:191], v[224:227], v[20:23]
	v_mfma_f32_16x16x32_bf16 v[12:15], v[196:199], v[224:227], v[12:15]
	v_mfma_f32_16x16x32_bf16 v[4:7], v[188:191], v[232:235], v[4:7]
	v_mfma_f32_16x16x32_bf16 v[0:3], v[196:199], v[232:235], v[0:3]
	s_setprio 0
	s_barrier
	s_add_i32 s87, s87, 2
	s_add_u32 s58, s58, 0x100
	s_addc_u32 s59, s59, 0
	s_add_u32 s85, s85, 0x100
	s_addc_u32 s86, s86, 0

;     __host__ __device__ bool next(int i, Unit& u) const { const int L = i * G + c; if (L >= 16 * nkc) return false; u.kc = L % nkc; const int t = L / nkc; u.pn = t & 3; u.pm = 33 * (t >> 2); return true; }
; #define PG8_STAGE(bufoff, gbase, voff) do { _Pragma("unroll") for (int _i = 0; _i < 2; ++_i) \
;         __builtin_amdgcn_global_load_lds((const unsigned*)((const char*)(gbase) + (voff)[_i]), (PG8_LAS unsigned*)(lds + (bufoff) + ldsw + _i * 8192), 16, 0, 0); } while (0)
; #define PG8_LDA(dst, b, h) do { _Pragma("unroll") for (int m = 0; m < 4; ++m) _Pragma("unroll") for (int k = 0; k < 2; ++k) dst[m][k] = *(const PG8_LAS bf16x8*)(lds + PG8_SA(b, h) + aoff + m * 2048 + k * 1024); } while (0)
; #define PG8_LDB(dst, b, h) do { _Pragma("unroll") for (int n = 0; n < 2; ++n) _Pragma("unroll") for (int k = 0; k < 2; ++k) dst[n][k] = *(const PG8_LAS bf16x8*)(lds + PG8_SB(b, h) + boff + n * 2048 + k * 1024); } while (0)
; #define PG8_BAR __builtin_amdgcn_s_barrier()
; template <class Epi, class Sched, bool ALIGN_EPI = false, bool SP2 = false>
; __device__ __forceinline__ void gemm_phase(PG8_LAS unsigned char* lds, const Gemm g, const Sched& S, const Epi& E) {
;     ...
;         const bool has_next = S.next(ui + 1, nxt);
;         const char* nA = has_next ? (const char*)g.A + (size_t)nxt.pm * tstep + (size_t)nxt.kc * cstep : cA; const char* nB = has_next ? (const char*)g.Bt + (size_t)nxt.pn * tstep + (size_t)nxt.kc * cstep : cB;
;         for (int t = 0; t < nt; t += 2) {
;             const bool last = (t == nt - 2);
;             const char* a1 = cA + (size_t)(t + 1) * kstep;
;             const char* a2 = last ? nA : cA + (size_t)(t + 2) * kstep; const char* b2 = last ? nB : cB + (size_t)(t + 2) * kstep;
;             const char* a3 = a2 + kstep; const char* b3 = b2 + kstep;
;             if (last && has_next) S.a_ready(nxt);
;             if constexpr (SP2) {
;             PG8_LDB(B0, 0, 0); PG8_LDB(B1, 0, 1); PG8_SCHED; PG8_LDA(At, 0, 0); PG8_STAGE(PG8_SA(1, 1), a1 + hstep, voffA);
;             PG8_WAIT_V(8); PG8_WAIT_L(0); PG8_BAR; PG8_MMA(0, 0, At, B0); PG8_MMA(0, 1, At, B1); PG8_BAR; PG8_SCHED;
;             PG8_LDA(At, 0, 1); PG8_STAGE(PG8_SB(0, 0), b2, voffB); PG8_STAGE(PG8_SB(0, 1), b2 + hstep, voffB); PG8_STAGE(PG8_SA(0, 0), a2, voffA);
;             PG8_WAIT_V(8); PG8_WAIT_L(0); PG8_BAR; PG8_MMA(1, 0, At, B0); PG8_MMA(1, 1, At, B1); PG8_BAR; PG8_SCHED;
.LBB0_633:
	s_ashr_i32 s57, s56, 31
	s_lshl_b64 s[6:7], s[56:57], 19
	s_add_u32 s58, s46, s6
	s_addc_u32 s59, s47, s7
	s_and_b64 s[6:7], s[4:5], exec
	s_cselect_b32 s57, s59, s65
	s_cselect_b32 vcc_lo, s58, s64
	s_ashr_i32 s55, s54, 31
	s_lshl_b64 s[6:7], s[54:55], 19
	s_add_u32 s60, s0, s6
	s_addc_u32 s61, s1, s7
	s_and_b64 s[6:7], s[4:5], exec
	s_cselect_b32 s55, s61, s67
	s_cselect_b32 vcc_hi, s60, s66
	s_add_u32 s90, s66, 0x100
	s_addc_u32 s92, s67, 0
	s_mov_b32 s6, -2
	s_waitcnt vmcnt(0)
	ds_read_b128 v[142:145], v174
	ds_read_b128 v[146:149], v175
	ds_read_b128 v[150:153], v176
	ds_read_b128 v[154:157], v177
	ds_read_b128 v[158:161], v178
	ds_read_b128 v[162:165], v179
	ds_read_b128 v[166:169], v180
	ds_read_b128 v[190:193], v181
	s_add_u32 s66, s64, 0x100
	s_addc_u32 s67, s65, 0
	s_cmp_eq_u32 s6, 12
	s_cselect_b32 s73, s57, s67
	s_cselect_b32 s72, vcc_lo, s66
	s_cselect_b32 s71, s55, s92
	s_cselect_b32 s70, vcc_hi, s90
	s_mov_b32 m0, s86
	v_lshl_add_u64 v[170:171], s[64:65], 0, v[134:135]
	ds_read_b128 v[194:197], v172
	ds_read_b128 v[198:201], v172 offset:1024
	ds_read_b128 v[202:205], v172 offset:2048
	ds_read_b128 v[206:209], v172 offset:3072
	ds_read_b128 v[210:213], v172 offset:4096
	ds_read_b128 v[214:217], v172 offset:5120
	ds_read_b128 v[218:221], v172 offset:6144
	ds_read_b128 v[224:227], v172 offset:7168
	global_load_lds_dwordx4 v[170:171], off
	v_lshl_add_u64 v[170:171], s[64:65], 0, v[136:137]
	s_mov_b32 m0, s87
	s_nop 0
	global_load_lds_dwordx4 v[170:171], off
	s_waitcnt vmcnt(8)
	s_waitcnt lgkmcnt(0)
	s_barrier
	s_setprio 1
	s_waitcnt lgkmcnt(0)
	v_mfma_f32_16x16x32_bf16 v[124:127], v[142:145], v[194:197], 0
	v_mfma_f32_16x16x32_bf16 v[108:111], v[150:153], v[194:197], 0
	v_mfma_f32_16x16x32_bf16 v[120:123], v[142:145], v[202:205], 0
	v_mfma_f32_16x16x32_bf16 v[96:99], v[150:153], v[202:205], 0
	v_mfma_f32_16x16x32_bf16 v[116:119], v[142:145], v[210:213], 0
	v_mfma_f32_16x16x32_bf16 v[88:91], v[150:153], v[210:213], 0
	v_mfma_f32_16x16x32_bf16 v[112:115], v[142:145], v[218:221], 0
	v_mfma_f32_16x16x32_bf16 v[84:87], v[150:153], v[218:221], 0
	v_mfma_f32_16x16x32_bf16 v[124:127], v[146:149], v[198:201], v[124:127]
	v_mfma_f32_16x16x32_bf16 v[108:111], v[154:157], v[198:201], v[108:111]
	v_mfma_f32_16x16x32_bf16 v[120:123], v[146:149], v[206:209], v[120:123]
	v_mfma_f32_16x16x32_bf16 v[96:99], v[154:157], v[206:209], v[96:99]
	v_mfma_f32_16x16x32_bf16 v[116:119], v[146:149], v[214:217], v[116:119]
	v_mfma_f32_16x16x32_bf16 v[88:91], v[154:157], v[214:217], v[88:91]
	v_mfma_f32_16x16x32_bf16 v[112:115], v[146:149], v[224:227], v[112:115]
	v_mfma_f32_16x16x32_bf16 v[84:87], v[154:157], v[224:227], v[84:87]
	s_setprio 0
	s_setprio 1
	v_mfma_f32_16x16x32_bf16 v[68:71], v[158:161], v[194:197], 0
	v_mfma_f32_16x16x32_bf16 v[40:43], v[166:169], v[194:197], 0
	v_mfma_f32_16x16x32_bf16 v[60:63], v[158:161], v[202:205], 0
	v_mfma_f32_16x16x32_bf16 v[32:35], v[166:169], v[202:205], 0
	v_mfma_f32_16x16x32_bf16 v[52:55], v[158:161], v[210:213], 0
	v_mfma_f32_16x16x32_bf16 v[24:27], v[166:169], v[210:213], 0
	v_mfma_f32_16x16x32_bf16 v[48:51], v[158:161], v[218:221], 0
	v_mfma_f32_16x16x32_bf16 v[16:19], v[166:169], v[218:221], 0
	v_mfma_f32_16x16x32_bf16 v[68:71], v[162:165], v[198:201], v[68:71]
	v_mfma_f32_16x16x32_bf16 v[40:43], v[190:193], v[198:201], v[40:43]
	v_mfma_f32_16x16x32_bf16 v[60:63], v[162:165], v[206:209], v[60:63]
	v_mfma_f32_16x16x32_bf16 v[32:35], v[190:193], v[206:209], v[32:35]
	v_mfma_f32_16x16x32_bf16 v[52:55], v[162:165], v[214:217], v[52:55]
	v_mfma_f32_16x16x32_bf16 v[24:27], v[190:193], v[214:217], v[24:27]
	v_mfma_f32_16x16x32_bf16 v[48:51], v[162:165], v[224:227], v[48:51]
	v_mfma_f32_16x16x32_bf16 v[16:19], v[190:193], v[224:227], v[16:19]
	s_setprio 0
	s_barrier
	s_mov_b32 m0, s13
	v_lshl_add_u64 v[170:171], s[70:71], 0, v[128:129]
	s_add_u32 s64, s70, 0x40000
	ds_read_b128 v[194:197], v172 offset:16384
	ds_read_b128 v[198:201], v172 offset:17408
	ds_read_b128 v[202:205], v172 offset:18432
	ds_read_b128 v[206:209], v172 offset:19456
	ds_read_b128 v[210:213], v172 offset:20480
	ds_read_b128 v[214:217], v172 offset:21504
	ds_read_b128 v[218:221], v172 offset:22528
	ds_read_b128 v[224:227], v172 offset:23552
	global_load_lds_dwordx4 v[170:171], off
	v_lshl_add_u64 v[228:229], s[70:71], 0, v[130:131]
	s_mov_b32 m0, s14
	s_addc_u32 s65, s71, 0
	global_load_lds_dwordx4 v[228:229], off
	v_lshl_add_u64 v[230:231], s[64:65], 0, v[128:129]
	s_mov_b32 m0, s15
	v_lshl_add_u64 v[232:233], s[72:73], 0, v[130:131]
	global_load_lds_dwordx4 v[230:231], off
	v_lshl_add_u64 v[230:231], s[64:65], 0, v[130:131]
	s_mov_b32 m0, s33
	s_nop 0
	global_load_lds_dwordx4 v[230:231], off
	v_lshl_add_u64 v[230:231], s[72:73], 0, v[128:129]
	s_mov_b32 m0, s12
	s_nop 0
	global_load_lds_dwordx4 v[230:231], off
	s_mov_b32 m0, s39
	s_nop 0
	global_load_lds_dwordx4 v[232:233], off
	s_waitcnt vmcnt(8)
	s_waitcnt lgkmcnt(0)
	s_barrier
; #define PG8_STAGE(bufoff, gbase, voff) do { _Pragma("unroll") for (int _i = 0; _i < 2; ++_i) \
;         __builtin_amdgcn_global_load_lds((const unsigned*)((const char*)(gbase) + (voff)[_i]), (PG8_LAS unsigned*)(lds + (bufoff) + ldsw + _i * 8192), 16, 0, 0); } while (0)
; #define PG8_LDA(dst, b, h) do { _Pragma("unroll") for (int m = 0; m < 4; ++m) _Pragma("unroll") for (int k = 0; k < 2; ++k) dst[m][k] = *(const PG8_LAS bf16x8*)(lds + PG8_SA(b, h) + aoff + m * 2048 + k * 1024); } while (0)
; #define PG8_LDB(dst, b, h) do { _Pragma("unroll") for (int n = 0; n < 2; ++n) _Pragma("unroll") for (int k = 0; k < 2; ++k) dst[n][k] = *(const PG8_LAS bf16x8*)(lds + PG8_SB(b, h) + boff + n * 2048 + k * 1024); } while (0)
; #define PG8_MMA(ai, bj, At, Bt) do { __builtin_amdgcn_s_setprio(1); _Pragma("unroll") for (int m = 0; m < 4; ++m) _Pragma("unroll") for (int n = 0; n < 2; ++n) _Pragma("unroll") for (int k = 0; k < 2; ++k) \
;         acc[ai][bj][m][n] = __builtin_amdgcn_mfma_f32_16x16x32_bf16(Bt[n][k], At[m][k], acc[ai][bj][m][n], 0, 0, 0); __builtin_amdgcn_s_setprio(0); } while (0)
; #define PG8_WAIT_V(n) asm volatile("s_waitcnt vmcnt(" #n ")" ::: "memory")
; #define PG8_WAIT_L(n) asm volatile("s_waitcnt lgkmcnt(" #n ")" ::: "memory")
; #define PG8_BAR __builtin_amdgcn_s_barrier()
; #define PG8_SCHED __builtin_amdgcn_sched_barrier(0)
; template <class Epi, class Sched, bool ALIGN_EPI = false, bool SP2 = false>
; __device__ __forceinline__ void gemm_phase(PG8_LAS unsigned char* lds, const Gemm g, const Sched& S, const Epi& E) {
;     ...
;             PG8_WAIT_V(8); PG8_WAIT_L(0); PG8_BAR; PG8_MMA(1, 0, At, B0); PG8_MMA(1, 1, At, B1); PG8_BAR; PG8_SCHED;
;             PG8_LDB(B0, 1, 0); PG8_LDB(B1, 1, 1); PG8_SCHED; PG8_LDA(At, 1, 0); PG8_STAGE(PG8_SA(0, 1), a2 + hstep, voffA);
;             PG8_WAIT_V(8); PG8_WAIT_L(0); PG8_BAR; PG8_MMA(0, 0, At, B0); PG8_MMA(0, 1, At, B1); PG8_BAR; PG8_SCHED;
	s_setprio 1
	s_waitcnt lgkmcnt(0)
	v_mfma_f32_16x16x32_bf16 v[104:107], v[142:145], v[194:197], 0
	v_mfma_f32_16x16x32_bf16 v[76:79], v[150:153], v[194:197], 0
	v_mfma_f32_16x16x32_bf16 v[100:103], v[142:145], v[202:205], 0
	v_mfma_f32_16x16x32_bf16 v[72:75], v[150:153], v[202:205], 0
	v_mfma_f32_16x16x32_bf16 v[92:95], v[142:145], v[210:213], 0
	v_mfma_f32_16x16x32_bf16 v[64:67], v[150:153], v[210:213], 0
	v_mfma_f32_16x16x32_bf16 v[80:83], v[142:145], v[218:221], 0
	v_mfma_f32_16x16x32_bf16 v[56:59], v[150:153], v[218:221], 0
	v_mfma_f32_16x16x32_bf16 v[104:107], v[146:149], v[198:201], v[104:107]
	v_mfma_f32_16x16x32_bf16 v[76:79], v[154:157], v[198:201], v[76:79]
	v_mfma_f32_16x16x32_bf16 v[100:103], v[146:149], v[206:209], v[100:103]
	v_mfma_f32_16x16x32_bf16 v[72:75], v[154:157], v[206:209], v[72:75]
	v_mfma_f32_16x16x32_bf16 v[92:95], v[146:149], v[214:217], v[92:95]
	v_mfma_f32_16x16x32_bf16 v[64:67], v[154:157], v[214:217], v[64:67]
	v_mfma_f32_16x16x32_bf16 v[80:83], v[146:149], v[224:227], v[80:83]
	v_mfma_f32_16x16x32_bf16 v[56:59], v[154:157], v[224:227], v[56:59]
	s_setprio 0
	s_setprio 1
	v_mfma_f32_16x16x32_bf16 v[44:47], v[158:161], v[194:197], 0
	v_mfma_f32_16x16x32_bf16 v[12:15], v[166:169], v[194:197], 0
	v_mfma_f32_16x16x32_bf16 v[36:39], v[158:161], v[202:205], 0
	v_mfma_f32_16x16x32_bf16 v[8:11], v[166:169], v[202:205], 0
	v_mfma_f32_16x16x32_bf16 v[28:31], v[158:161], v[210:213], 0
	v_mfma_f32_16x16x32_bf16 v[4:7], v[166:169], v[210:213], 0
	v_mfma_f32_16x16x32_bf16 v[20:23], v[158:161], v[218:221], 0
	v_mfma_f32_16x16x32_bf16 v[0:3], v[166:169], v[218:221], 0
	v_mfma_f32_16x16x32_bf16 v[44:47], v[162:165], v[198:201], v[44:47]
	v_mfma_f32_16x16x32_bf16 v[12:15], v[190:193], v[198:201], v[12:15]
	v_mfma_f32_16x16x32_bf16 v[36:39], v[162:165], v[206:209], v[36:39]
	v_mfma_f32_16x16x32_bf16 v[8:11], v[190:193], v[206:209], v[8:11]
	v_mfma_f32_16x16x32_bf16 v[28:31], v[162:165], v[214:217], v[28:31]
	v_mfma_f32_16x16x32_bf16 v[4:7], v[190:193], v[214:217], v[4:7]
	v_mfma_f32_16x16x32_bf16 v[20:23], v[162:165], v[224:227], v[20:23]
	v_mfma_f32_16x16x32_bf16 v[0:3], v[190:193], v[224:227], v[0:3]
	s_setprio 0
	s_barrier
	ds_read_b128 v[142:145], v182
	ds_read_b128 v[146:149], v183
	ds_read_b128 v[150:153], v184
	ds_read_b128 v[154:157], v185
	ds_read_b128 v[158:161], v186
	ds_read_b128 v[162:165], v187
	ds_read_b128 v[166:169], v188
	ds_read_b128 v[190:193], v189
	s_add_u32 s64, s72, 0x40000
	s_addc_u32 s65, s73, 0
	s_mov_b32 m0, s43
	v_lshl_add_u64 v[234:235], s[64:65], 0, v[128:129]
	ds_read_b128 v[194:197], v172 offset:32768
	ds_read_b128 v[198:201], v172 offset:33792
	ds_read_b128 v[202:205], v172 offset:34816
	ds_read_b128 v[206:209], v172 offset:35840
	ds_read_b128 v[210:213], v172 offset:36864
	ds_read_b128 v[214:217], v172 offset:37888
	ds_read_b128 v[218:221], v172 offset:38912
	ds_read_b128 v[224:227], v172 offset:39936
	global_load_lds_dwordx4 v[234:235], off
	v_lshl_add_u64 v[234:235], s[64:65], 0, v[130:131]
	s_mov_b32 m0, s74
	s_nop 0
	global_load_lds_dwordx4 v[234:235], off
	s_waitcnt vmcnt(8)
	s_waitcnt lgkmcnt(0)
	s_barrier
	s_setprio 1
	s_waitcnt lgkmcnt(0)
	v_mfma_f32_16x16x32_bf16 v[124:127], v[142:145], v[194:197], v[124:127]
	v_mfma_f32_16x16x32_bf16 v[108:111], v[150:153], v[194:197], v[108:111]
	v_mfma_f32_16x16x32_bf16 v[120:123], v[142:145], v[202:205], v[120:123]
	v_mfma_f32_16x16x32_bf16 v[96:99], v[150:153], v[202:205], v[96:99]
	v_mfma_f32_16x16x32_bf16 v[116:119], v[142:145], v[210:213], v[116:119]
	v_mfma_f32_16x16x32_bf16 v[88:91], v[150:153], v[210:213], v[88:91]
	v_mfma_f32_16x16x32_bf16 v[112:115], v[142:145], v[218:221], v[112:115]
	v_mfma_f32_16x16x32_bf16 v[84:87], v[150:153], v[218:221], v[84:87]
	v_mfma_f32_16x16x32_bf16 v[124:127], v[146:149], v[198:201], v[124:127]
	v_mfma_f32_16x16x32_bf16 v[108:111], v[154:157], v[198:201], v[108:111]
	v_mfma_f32_16x16x32_bf16 v[120:123], v[146:149], v[206:209], v[120:123]
	v_mfma_f32_16x16x32_bf16 v[96:99], v[154:157], v[206:209], v[96:99]
	v_mfma_f32_16x16x32_bf16 v[116:119], v[146:149], v[214:217], v[116:119]
	v_mfma_f32_16x16x32_bf16 v[88:91], v[154:157], v[214:217], v[88:91]
	v_mfma_f32_16x16x32_bf16 v[112:115], v[146:149], v[224:227], v[112:115]
	v_mfma_f32_16x16x32_bf16 v[84:87], v[154:157], v[224:227], v[84:87]
	s_setprio 0
	s_setprio 1
	v_mfma_f32_16x16x32_bf16 v[68:71], v[158:161], v[194:197], v[68:71]
	v_mfma_f32_16x16x32_bf16 v[40:43], v[166:169], v[194:197], v[40:43]
	v_mfma_f32_16x16x32_bf16 v[60:63], v[158:161], v[202:205], v[60:63]
	v_mfma_f32_16x16x32_bf16 v[32:35], v[166:169], v[202:205], v[32:35]
	v_mfma_f32_16x16x32_bf16 v[52:55], v[158:161], v[210:213], v[52:55]
	v_mfma_f32_16x16x32_bf16 v[24:27], v[166:169], v[210:213], v[24:27]
	v_mfma_f32_16x16x32_bf16 v[48:51], v[158:161], v[218:221], v[48:51]
	v_mfma_f32_16x16x32_bf16 v[16:19], v[166:169], v[218:221], v[16:19]
	v_mfma_f32_16x16x32_bf16 v[68:71], v[162:165], v[198:201], v[68:71]
	v_mfma_f32_16x16x32_bf16 v[40:43], v[190:193], v[198:201], v[40:43]
	v_mfma_f32_16x16x32_bf16 v[60:63], v[162:165], v[206:209], v[60:63]
	v_mfma_f32_16x16x32_bf16 v[32:35], v[190:193], v[206:209], v[32:35]
	v_mfma_f32_16x16x32_bf16 v[52:55], v[162:165], v[214:217], v[52:55]
	v_mfma_f32_16x16x32_bf16 v[24:27], v[190:193], v[214:217], v[24:27]
	v_mfma_f32_16x16x32_bf16 v[48:51], v[162:165], v[224:227], v[48:51]
	v_mfma_f32_16x16x32_bf16 v[16:19], v[190:193], v[224:227], v[16:19]
	s_setprio 0
	s_barrier
; #define PG8_STAGE(bufoff, gbase, voff) do { _Pragma("unroll") for (int _i = 0; _i < 2; ++_i) \
;         __builtin_amdgcn_global_load_lds((const unsigned*)((const char*)(gbase) + (voff)[_i]), (PG8_LAS unsigned*)(lds + (bufoff) + ldsw + _i * 8192), 16, 0, 0); } while (0)
; #define PG8_LDA(dst, b, h) do { _Pragma("unroll") for (int m = 0; m < 4; ++m) _Pragma("unroll") for (int k = 0; k < 2; ++k) dst[m][k] = *(const PG8_LAS bf16x8*)(lds + PG8_SA(b, h) + aoff + m * 2048 + k * 1024); } while (0)
; #define PG8_MMA(ai, bj, At, Bt) do { __builtin_amdgcn_s_setprio(1); _Pragma("unroll") for (int m = 0; m < 4; ++m) _Pragma("unroll") for (int n = 0; n < 2; ++n) _Pragma("unroll") for (int k = 0; k < 2; ++k) \
;         acc[ai][bj][m][n] = __builtin_amdgcn_mfma_f32_16x16x32_bf16(Bt[n][k], At[m][k], acc[ai][bj][m][n], 0, 0, 0); __builtin_amdgcn_s_setprio(0); } while (0)
; #define PG8_WAIT_V(n) asm volatile("s_waitcnt vmcnt(" #n ")" ::: "memory")
; #define PG8_WAIT_L(n) asm volatile("s_waitcnt lgkmcnt(" #n ")" ::: "memory")
; #define PG8_BAR __builtin_amdgcn_s_barrier()
; #define PG8_SCHED __builtin_amdgcn_sched_barrier(0)
; template <class Epi, class Sched, bool ALIGN_EPI = false, bool SP2 = false>
; __device__ __forceinline__ void gemm_phase(PG8_LAS unsigned char* lds, const Gemm g, const Sched& S, const Epi& E) {
;     ...
;             PG8_LDA(At, 1, 1); PG8_STAGE(PG8_SB(1, 0), b3, voffB); PG8_STAGE(PG8_SB(1, 1), b3 + hstep, voffB); PG8_STAGE(PG8_SA(1, 0), a3, voffA);
;             PG8_WAIT_V(8); PG8_WAIT_L(0); PG8_BAR; PG8_MMA(1, 0, At, B0); PG8_MMA(1, 1, At, B1); PG8_BAR; PG8_SCHED;
	s_mov_b32 m0, s78
	v_lshl_add_u64 v[170:171], v[170:171], 0, s[10:11]
	s_add_u32 s64, s70, 0x40080
	ds_read_b128 v[194:197], v172 offset:49152
	ds_read_b128 v[198:201], v172 offset:50176
	ds_read_b128 v[202:205], v172 offset:51200
	ds_read_b128 v[206:209], v172 offset:52224
	ds_read_b128 v[210:213], v172 offset:53248
	ds_read_b128 v[214:217], v172 offset:54272
	ds_read_b128 v[218:221], v172 offset:55296
	ds_read_b128 v[224:227], v172 offset:56320
	global_load_lds_dwordx4 v[170:171], off
	v_lshl_add_u64 v[170:171], v[228:229], 0, s[10:11]
	s_mov_b32 m0, s79
	s_addc_u32 s65, s71, 0
	global_load_lds_dwordx4 v[170:171], off
	v_lshl_add_u64 v[170:171], s[64:65], 0, v[128:129]
	s_mov_b32 m0, s82
	s_nop 0
	global_load_lds_dwordx4 v[170:171], off
	v_lshl_add_u64 v[170:171], s[64:65], 0, v[130:131]
	s_mov_b32 m0, s83
	s_nop 0
	global_load_lds_dwordx4 v[170:171], off
	v_lshl_add_u64 v[170:171], v[230:231], 0, s[10:11]
	s_mov_b32 m0, s80
	s_nop 0
	global_load_lds_dwordx4 v[170:171], off
	v_lshl_add_u64 v[170:171], v[232:233], 0, s[10:11]
	s_mov_b32 m0, s81
	s_nop 0
	global_load_lds_dwordx4 v[170:171], off
	s_waitcnt vmcnt(8)
	s_waitcnt lgkmcnt(0)
	s_barrier
	s_setprio 1
	s_waitcnt lgkmcnt(0)
	v_mfma_f32_16x16x32_bf16 v[104:107], v[142:145], v[194:197], v[104:107]
	v_mfma_f32_16x16x32_bf16 v[76:79], v[150:153], v[194:197], v[76:79]
	v_mfma_f32_16x16x32_bf16 v[100:103], v[142:145], v[202:205], v[100:103]
	v_mfma_f32_16x16x32_bf16 v[72:75], v[150:153], v[202:205], v[72:75]
	v_mfma_f32_16x16x32_bf16 v[92:95], v[142:145], v[210:213], v[92:95]
	v_mfma_f32_16x16x32_bf16 v[64:67], v[150:153], v[210:213], v[64:67]
	v_mfma_f32_16x16x32_bf16 v[80:83], v[142:145], v[218:221], v[80:83]
	v_mfma_f32_16x16x32_bf16 v[56:59], v[150:153], v[218:221], v[56:59]
	v_mfma_f32_16x16x32_bf16 v[104:107], v[146:149], v[198:201], v[104:107]
	v_mfma_f32_16x16x32_bf16 v[76:79], v[154:157], v[198:201], v[76:79]
	v_mfma_f32_16x16x32_bf16 v[100:103], v[146:149], v[206:209], v[100:103]
	v_mfma_f32_16x16x32_bf16 v[72:75], v[154:157], v[206:209], v[72:75]
	v_mfma_f32_16x16x32_bf16 v[92:95], v[146:149], v[214:217], v[92:95]
	v_mfma_f32_16x16x32_bf16 v[64:67], v[154:157], v[214:217], v[64:67]
	v_mfma_f32_16x16x32_bf16 v[80:83], v[146:149], v[224:227], v[80:83]
	v_mfma_f32_16x16x32_bf16 v[56:59], v[154:157], v[224:227], v[56:59]
	s_setprio 0
	s_setprio 1
	v_mfma_f32_16x16x32_bf16 v[44:47], v[158:161], v[194:197], v[44:47]
	v_mfma_f32_16x16x32_bf16 v[12:15], v[166:169], v[194:197], v[12:15]
	v_mfma_f32_16x16x32_bf16 v[36:39], v[158:161], v[202:205], v[36:39]
	v_mfma_f32_16x16x32_bf16 v[8:11], v[166:169], v[202:205], v[8:11]
	v_mfma_f32_16x16x32_bf16 v[28:31], v[158:161], v[210:213], v[28:31]
	v_mfma_f32_16x16x32_bf16 v[4:7], v[166:169], v[210:213], v[4:7]
	v_mfma_f32_16x16x32_bf16 v[20:23], v[158:161], v[218:221], v[20:23]
	v_mfma_f32_16x16x32_bf16 v[0:3], v[166:169], v[218:221], v[0:3]
	v_mfma_f32_16x16x32_bf16 v[44:47], v[162:165], v[198:201], v[44:47]
	v_mfma_f32_16x16x32_bf16 v[12:15], v[190:193], v[198:201], v[12:15]
	v_mfma_f32_16x16x32_bf16 v[36:39], v[162:165], v[206:209], v[36:39]
	v_mfma_f32_16x16x32_bf16 v[8:11], v[190:193], v[206:209], v[8:11]
	v_mfma_f32_16x16x32_bf16 v[28:31], v[162:165], v[214:217], v[28:31]
	v_mfma_f32_16x16x32_bf16 v[4:7], v[190:193], v[214:217], v[4:7]
	v_mfma_f32_16x16x32_bf16 v[20:23], v[162:165], v[224:227], v[20:23]
	v_mfma_f32_16x16x32_bf16 v[0:3], v[190:193], v[224:227], v[0:3]
	s_setprio 0
	s_barrier
	s_add_i32 s6, s6, 2
	s_add_u32 s90, s90, 0x100
	s_addc_u32 s92, s92, 0
	s_mov_b64 s[64:65], s[66:67]

;     __host__ __device__ bool next(int i, Unit& u) const { const int L = i * G + c; if (L >= 16 * nkc) return false; u.kc = L % nkc; const int t = L / nkc; u.pn = t & 3; u.pm = 33 * (t >> 2); return true; }
; #define PG8_STAGE(bufoff, gbase, voff) do { _Pragma("unroll") for (int _i = 0; _i < 2; ++_i) \
;         __builtin_amdgcn_global_load_lds((const unsigned*)((const char*)(gbase) + (voff)[_i]), (PG8_LAS unsigned*)(lds + (bufoff) + ldsw + _i * 8192), 16, 0, 0); } while (0)
; #define PG8_LDA(dst, b, h) do { _Pragma("unroll") for (int m = 0; m < 4; ++m) _Pragma("unroll") for (int k = 0; k < 2; ++k) dst[m][k] = *(const PG8_LAS bf16x8*)(lds + PG8_SA(b, h) + aoff + m * 2048 + k * 1024); } while (0)
; #define PG8_LDB(dst, b, h) do { _Pragma("unroll") for (int n = 0; n < 2; ++n) _Pragma("unroll") for (int k = 0; k < 2; ++k) dst[n][k] = *(const PG8_LAS bf16x8*)(lds + PG8_SB(b, h) + boff + n * 2048 + k * 1024); } while (0)
; #define PG8_BAR __builtin_amdgcn_s_barrier()
; template <class Epi, class Sched, bool ALIGN_EPI = false, bool SP2 = false>
; __device__ __forceinline__ void gemm_phase(PG8_LAS unsigned char* lds, const Gemm g, const Sched& S, const Epi& E) {
;     ...
;         const bool has_next = S.next(ui + 1, nxt);
;         const char* nA = has_next ? (const char*)g.A + (size_t)nxt.pm * tstep + (size_t)nxt.kc * cstep : cA; const char* nB = has_next ? (const char*)g.Bt + (size_t)nxt.pn * tstep + (size_t)nxt.kc * cstep : cB;
;         for (int t = 0; t < nt; t += 2) {
;             const bool last = (t == nt - 2);
;             const char* a1 = cA + (size_t)(t + 1) * kstep;
;             const char* a2 = last ? nA : cA + (size_t)(t + 2) * kstep; const char* b2 = last ? nB : cB + (size_t)(t + 2) * kstep;
;             const char* a3 = a2 + kstep; const char* b3 = b2 + kstep;
;             if (last && has_next) S.a_ready(nxt);
;             if constexpr (SP2) {
;             PG8_LDB(B0, 0, 0); PG8_LDB(B1, 0, 1); PG8_SCHED; PG8_LDA(At, 0, 0); PG8_STAGE(PG8_SA(1, 1), a1 + hstep, voffA);
;             PG8_WAIT_V(8); PG8_WAIT_L(0); PG8_BAR; PG8_MMA(0, 0, At, B0); PG8_MMA(0, 1, At, B1); PG8_BAR; PG8_SCHED;
;             PG8_LDA(At, 0, 1); PG8_STAGE(PG8_SB(0, 0), b2, voffB); PG8_STAGE(PG8_SB(0, 1), b2 + hstep, voffB); PG8_STAGE(PG8_SA(0, 0), a2, voffA);
;             PG8_WAIT_V(8); PG8_WAIT_L(0); PG8_BAR; PG8_MMA(1, 0, At, B0); PG8_MMA(1, 1, At, B1); PG8_BAR; PG8_SCHED;
.LBB0_653:
	s_ashr_i32 s59, s58, 31
	s_lshl_b64 s[6:7], s[58:59], 19
	s_add_u32 s57, s46, s6
	s_addc_u32 s59, s47, s7
	s_ashr_i32 s55, s54, 31
	s_lshl_b64 s[6:7], s[54:55], 9
	s_add_u32 s66, s57, s6
	s_addc_u32 s67, s59, s7
	s_ashr_i32 s57, s56, 31
	s_lshl_b64 s[70:71], s[56:57], 19
	s_add_u32 s55, s0, s70
	s_addc_u32 s57, s1, s71
	s_add_u32 s70, s55, s6
	s_addc_u32 s71, s57, s7
	s_and_b64 vcc, exec, s[4:5]
	s_cbranch_vccnz .LBB0_661
	s_and_b64 s[6:7], s[62:63], exec
	s_cselect_b32 s55, s67, s73
	s_cselect_b32 s57, s66, s72
	s_cselect_b32 s59, s71, s75
	s_cselect_b32 s61, s70, s74
	s_add_u32 s90, s74, 0x100
	s_addc_u32 s92, s75, 0
	s_mov_b32 s6, 0
	ds_read_b128 v[156:159], v140
	ds_read_b128 v[160:163], v141
	ds_read_b128 v[164:167], v142
	ds_read_b128 v[168:171], v143
	ds_read_b128 v[172:175], v144
	ds_read_b128 v[176:179], v145
	ds_read_b128 v[180:183], v146
	ds_read_b128 v[184:187], v147
	s_add_i32 s7, s6, 2
	s_add_u32 s74, s72, 0x100
	s_addc_u32 s75, s73, 0
	s_cmp_eq_u32 s87, s6
	s_cselect_b32 s79, s55, s75
	s_cselect_b32 s78, s57, s74
	s_cselect_b32 s77, s59, s92
	s_cselect_b32 s76, s61, s90
	s_mov_b32 m0, s88
	v_lshl_add_u64 v[220:221], s[72:73], 0, v[134:135]
	ds_read_b128 v[188:191], v138
	ds_read_b128 v[192:195], v138 offset:1024
	ds_read_b128 v[196:199], v138 offset:2048
	ds_read_b128 v[200:203], v138 offset:3072
	ds_read_b128 v[204:207], v138 offset:4096
	ds_read_b128 v[208:211], v138 offset:5120
	ds_read_b128 v[212:215], v138 offset:6144
	ds_read_b128 v[216:219], v138 offset:7168
	global_load_lds_dwordx4 v[220:221], off
	v_lshl_add_u64 v[220:221], s[72:73], 0, v[136:137]
	s_mov_b32 m0, s89
	s_nop 0
	global_load_lds_dwordx4 v[220:221], off
	s_waitcnt vmcnt(8)
	s_waitcnt lgkmcnt(0)
	s_barrier
	s_setprio 1
	s_waitcnt lgkmcnt(0)
	v_mfma_f32_16x16x32_bf16 v[124:127], v[156:159], v[188:191], 0
	v_mfma_f32_16x16x32_bf16 v[120:123], v[164:167], v[188:191], 0
	v_mfma_f32_16x16x32_bf16 v[108:111], v[156:159], v[196:199], 0
	v_mfma_f32_16x16x32_bf16 v[104:107], v[164:167], v[196:199], 0
	v_mfma_f32_16x16x32_bf16 v[92:95], v[156:159], v[204:207], 0
	v_mfma_f32_16x16x32_bf16 v[88:91], v[164:167], v[204:207], 0
	v_mfma_f32_16x16x32_bf16 v[76:79], v[156:159], v[212:215], 0
	v_mfma_f32_16x16x32_bf16 v[72:75], v[164:167], v[212:215], 0
	v_mfma_f32_16x16x32_bf16 v[124:127], v[160:163], v[192:195], v[124:127]
	v_mfma_f32_16x16x32_bf16 v[120:123], v[168:171], v[192:195], v[120:123]
	v_mfma_f32_16x16x32_bf16 v[108:111], v[160:163], v[200:203], v[108:111]
	v_mfma_f32_16x16x32_bf16 v[104:107], v[168:171], v[200:203], v[104:107]
	v_mfma_f32_16x16x32_bf16 v[92:95], v[160:163], v[208:211], v[92:95]
	v_mfma_f32_16x16x32_bf16 v[88:91], v[168:171], v[208:211], v[88:91]
	v_mfma_f32_16x16x32_bf16 v[76:79], v[160:163], v[216:219], v[76:79]
	v_mfma_f32_16x16x32_bf16 v[72:75], v[168:171], v[216:219], v[72:75]
	s_setprio 0
	s_setprio 1
	v_mfma_f32_16x16x32_bf16 v[116:119], v[172:175], v[188:191], 0
	v_mfma_f32_16x16x32_bf16 v[112:115], v[180:183], v[188:191], 0
	v_mfma_f32_16x16x32_bf16 v[100:103], v[172:175], v[196:199], 0
	v_mfma_f32_16x16x32_bf16 v[96:99], v[180:183], v[196:199], 0
	v_mfma_f32_16x16x32_bf16 v[84:87], v[172:175], v[204:207], 0
	v_mfma_f32_16x16x32_bf16 v[80:83], v[180:183], v[204:207], 0
	v_mfma_f32_16x16x32_bf16 v[68:71], v[172:175], v[212:215], 0
	v_mfma_f32_16x16x32_bf16 v[64:67], v[180:183], v[212:215], 0
	v_mfma_f32_16x16x32_bf16 v[116:119], v[176:179], v[192:195], v[116:119]
	v_mfma_f32_16x16x32_bf16 v[112:115], v[184:187], v[192:195], v[112:115]
	v_mfma_f32_16x16x32_bf16 v[100:103], v[176:179], v[200:203], v[100:103]
	v_mfma_f32_16x16x32_bf16 v[96:99], v[184:187], v[200:203], v[96:99]
	v_mfma_f32_16x16x32_bf16 v[84:87], v[176:179], v[208:211], v[84:87]
	v_mfma_f32_16x16x32_bf16 v[80:83], v[184:187], v[208:211], v[80:83]
	v_mfma_f32_16x16x32_bf16 v[68:71], v[176:179], v[216:219], v[68:71]
	v_mfma_f32_16x16x32_bf16 v[64:67], v[184:187], v[216:219], v[64:67]
	s_setprio 0
	s_barrier
	s_mov_b32 m0, s13
	v_lshl_add_u64 v[220:221], s[76:77], 0, v[130:131]
	s_add_u32 s72, s76, 0x40000
	ds_read_b128 v[188:191], v138 offset:16384
	ds_read_b128 v[192:195], v138 offset:17408
	ds_read_b128 v[196:199], v138 offset:18432
	ds_read_b128 v[200:203], v138 offset:19456
	ds_read_b128 v[204:207], v138 offset:20480
	ds_read_b128 v[208:211], v138 offset:21504
	ds_read_b128 v[212:215], v138 offset:22528
	ds_read_b128 v[216:219], v138 offset:23552
	global_load_lds_dwordx4 v[220:221], off
	v_lshl_add_u64 v[224:225], s[76:77], 0, v[128:129]
	s_mov_b32 m0, s14
	s_addc_u32 s73, s77, 0
	global_load_lds_dwordx4 v[224:225], off
	v_lshl_add_u64 v[226:227], s[72:73], 0, v[130:131]
	s_mov_b32 m0, s15
	v_lshl_add_u64 v[228:229], s[78:79], 0, v[128:129]
	global_load_lds_dwordx4 v[226:227], off
	v_lshl_add_u64 v[226:227], s[72:73], 0, v[128:129]
	s_mov_b32 m0, s33
	s_nop 0
	global_load_lds_dwordx4 v[226:227], off
	v_lshl_add_u64 v[226:227], s[78:79], 0, v[130:131]
	s_mov_b32 m0, s12
	s_nop 0
	global_load_lds_dwordx4 v[226:227], off
	s_mov_b32 m0, s39
	s_nop 0
	global_load_lds_dwordx4 v[228:229], off
	s_waitcnt vmcnt(8)
	s_waitcnt lgkmcnt(0)
	s_barrier
; #define PG8_STAGE(bufoff, gbase, voff) do { _Pragma("unroll") for (int _i = 0; _i < 2; ++_i) \
;         __builtin_amdgcn_global_load_lds((const unsigned*)((const char*)(gbase) + (voff)[_i]), (PG8_LAS unsigned*)(lds + (bufoff) + ldsw + _i * 8192), 16, 0, 0); } while (0)
; #define PG8_LDA(dst, b, h) do { _Pragma("unroll") for (int m = 0; m < 4; ++m) _Pragma("unroll") for (int k = 0; k < 2; ++k) dst[m][k] = *(const PG8_LAS bf16x8*)(lds + PG8_SA(b, h) + aoff + m * 2048 + k * 1024); } while (0)
; #define PG8_LDB(dst, b, h) do { _Pragma("unroll") for (int n = 0; n < 2; ++n) _Pragma("unroll") for (int k = 0; k < 2; ++k) dst[n][k] = *(const PG8_LAS bf16x8*)(lds + PG8_SB(b, h) + boff + n * 2048 + k * 1024); } while (0)
; #define PG8_MMA(ai, bj, At, Bt) do { __builtin_amdgcn_s_setprio(1); _Pragma("unroll") for (int m = 0; m < 4; ++m) _Pragma("unroll") for (int n = 0; n < 2; ++n) _Pragma("unroll") for (int k = 0; k < 2; ++k) \
;         acc[ai][bj][m][n] = __builtin_amdgcn_mfma_f32_16x16x32_bf16(Bt[n][k], At[m][k], acc[ai][bj][m][n], 0, 0, 0); __builtin_amdgcn_s_setprio(0); } while (0)
; #define PG8_WAIT_V(n) asm volatile("s_waitcnt vmcnt(" #n ")" ::: "memory")
; #define PG8_WAIT_L(n) asm volatile("s_waitcnt lgkmcnt(" #n ")" ::: "memory")
; #define PG8_BAR __builtin_amdgcn_s_barrier()
; #define PG8_SCHED __builtin_amdgcn_sched_barrier(0)
; template <class Epi, class Sched, bool ALIGN_EPI = false, bool SP2 = false>
; __device__ __forceinline__ void gemm_phase(PG8_LAS unsigned char* lds, const Gemm g, const Sched& S, const Epi& E) {
;     ...
;             PG8_WAIT_V(8); PG8_WAIT_L(0); PG8_BAR; PG8_MMA(1, 0, At, B0); PG8_MMA(1, 1, At, B1); PG8_BAR; PG8_SCHED;
;             PG8_LDB(B0, 1, 0); PG8_LDB(B1, 1, 1); PG8_SCHED; PG8_LDA(At, 1, 0); PG8_STAGE(PG8_SA(0, 1), a2 + hstep, voffA);
;             PG8_WAIT_V(8); PG8_WAIT_L(0); PG8_BAR; PG8_MMA(0, 0, At, B0); PG8_MMA(0, 1, At, B1); PG8_BAR; PG8_SCHED;
	s_setprio 1
	s_waitcnt lgkmcnt(0)
	v_mfma_f32_16x16x32_bf16 v[60:63], v[156:159], v[188:191], 0
	v_mfma_f32_16x16x32_bf16 v[56:59], v[164:167], v[188:191], 0
	v_mfma_f32_16x16x32_bf16 v[44:47], v[156:159], v[196:199], 0
	v_mfma_f32_16x16x32_bf16 v[40:43], v[164:167], v[196:199], 0
	v_mfma_f32_16x16x32_bf16 v[28:31], v[156:159], v[204:207], 0
	v_mfma_f32_16x16x32_bf16 v[24:27], v[164:167], v[204:207], 0
	v_mfma_f32_16x16x32_bf16 v[12:15], v[156:159], v[212:215], 0
	v_mfma_f32_16x16x32_bf16 v[8:11], v[164:167], v[212:215], 0
	v_mfma_f32_16x16x32_bf16 v[60:63], v[160:163], v[192:195], v[60:63]
	v_mfma_f32_16x16x32_bf16 v[56:59], v[168:171], v[192:195], v[56:59]
	v_mfma_f32_16x16x32_bf16 v[44:47], v[160:163], v[200:203], v[44:47]
	v_mfma_f32_16x16x32_bf16 v[40:43], v[168:171], v[200:203], v[40:43]
	v_mfma_f32_16x16x32_bf16 v[28:31], v[160:163], v[208:211], v[28:31]
	v_mfma_f32_16x16x32_bf16 v[24:27], v[168:171], v[208:211], v[24:27]
	v_mfma_f32_16x16x32_bf16 v[12:15], v[160:163], v[216:219], v[12:15]
	v_mfma_f32_16x16x32_bf16 v[8:11], v[168:171], v[216:219], v[8:11]
	s_setprio 0
	s_setprio 1
	v_mfma_f32_16x16x32_bf16 v[52:55], v[172:175], v[188:191], 0
	v_mfma_f32_16x16x32_bf16 v[48:51], v[180:183], v[188:191], 0
	v_mfma_f32_16x16x32_bf16 v[36:39], v[172:175], v[196:199], 0
	v_mfma_f32_16x16x32_bf16 v[32:35], v[180:183], v[196:199], 0
	v_mfma_f32_16x16x32_bf16 v[20:23], v[172:175], v[204:207], 0
	v_mfma_f32_16x16x32_bf16 v[16:19], v[180:183], v[204:207], 0
	v_mfma_f32_16x16x32_bf16 v[4:7], v[172:175], v[212:215], 0
	v_mfma_f32_16x16x32_bf16 v[0:3], v[180:183], v[212:215], 0
	v_mfma_f32_16x16x32_bf16 v[52:55], v[176:179], v[192:195], v[52:55]
	v_mfma_f32_16x16x32_bf16 v[48:51], v[184:187], v[192:195], v[48:51]
	v_mfma_f32_16x16x32_bf16 v[36:39], v[176:179], v[200:203], v[36:39]
	v_mfma_f32_16x16x32_bf16 v[32:35], v[184:187], v[200:203], v[32:35]
	v_mfma_f32_16x16x32_bf16 v[20:23], v[176:179], v[208:211], v[20:23]
	v_mfma_f32_16x16x32_bf16 v[16:19], v[184:187], v[208:211], v[16:19]
	v_mfma_f32_16x16x32_bf16 v[4:7], v[176:179], v[216:219], v[4:7]
	v_mfma_f32_16x16x32_bf16 v[0:3], v[184:187], v[216:219], v[0:3]
	s_setprio 0
	s_barrier
	ds_read_b128 v[156:159], v148
	ds_read_b128 v[160:163], v149
	ds_read_b128 v[164:167], v150
	ds_read_b128 v[168:171], v151
	ds_read_b128 v[172:175], v152
	ds_read_b128 v[176:179], v153
	ds_read_b128 v[180:183], v154
	ds_read_b128 v[184:187], v155
	s_add_u32 s72, s78, 0x40000
	s_addc_u32 s73, s79, 0
	s_mov_b32 m0, s43
	v_lshl_add_u64 v[230:231], s[72:73], 0, v[130:131]
	ds_read_b128 v[188:191], v138 offset:32768
	ds_read_b128 v[192:195], v138 offset:33792
	ds_read_b128 v[196:199], v138 offset:34816
	ds_read_b128 v[200:203], v138 offset:35840
	ds_read_b128 v[204:207], v138 offset:36864
	ds_read_b128 v[208:211], v138 offset:37888
	ds_read_b128 v[212:215], v138 offset:38912
	ds_read_b128 v[216:219], v138 offset:39936
	global_load_lds_dwordx4 v[230:231], off
	v_lshl_add_u64 v[230:231], s[72:73], 0, v[128:129]
	s_mov_b32 m0, s65
	s_nop 0
	global_load_lds_dwordx4 v[230:231], off
	s_waitcnt vmcnt(8)
	s_waitcnt lgkmcnt(0)
	s_barrier
	s_setprio 1
	s_waitcnt lgkmcnt(0)
	v_mfma_f32_16x16x32_bf16 v[124:127], v[156:159], v[188:191], v[124:127]
	v_mfma_f32_16x16x32_bf16 v[120:123], v[164:167], v[188:191], v[120:123]
	v_mfma_f32_16x16x32_bf16 v[108:111], v[156:159], v[196:199], v[108:111]
	v_mfma_f32_16x16x32_bf16 v[104:107], v[164:167], v[196:199], v[104:107]
	v_mfma_f32_16x16x32_bf16 v[92:95], v[156:159], v[204:207], v[92:95]
	v_mfma_f32_16x16x32_bf16 v[88:91], v[164:167], v[204:207], v[88:91]
	v_mfma_f32_16x16x32_bf16 v[76:79], v[156:159], v[212:215], v[76:79]
	v_mfma_f32_16x16x32_bf16 v[72:75], v[164:167], v[212:215], v[72:75]
	v_mfma_f32_16x16x32_bf16 v[124:127], v[160:163], v[192:195], v[124:127]
	v_mfma_f32_16x16x32_bf16 v[120:123], v[168:171], v[192:195], v[120:123]
	v_mfma_f32_16x16x32_bf16 v[108:111], v[160:163], v[200:203], v[108:111]
	v_mfma_f32_16x16x32_bf16 v[104:107], v[168:171], v[200:203], v[104:107]
	v_mfma_f32_16x16x32_bf16 v[92:95], v[160:163], v[208:211], v[92:95]
	v_mfma_f32_16x16x32_bf16 v[88:91], v[168:171], v[208:211], v[88:91]
	v_mfma_f32_16x16x32_bf16 v[76:79], v[160:163], v[216:219], v[76:79]
	v_mfma_f32_16x16x32_bf16 v[72:75], v[168:171], v[216:219], v[72:75]
	s_setprio 0
	s_setprio 1
	v_mfma_f32_16x16x32_bf16 v[116:119], v[172:175], v[188:191], v[116:119]
	v_mfma_f32_16x16x32_bf16 v[112:115], v[180:183], v[188:191], v[112:115]
	v_mfma_f32_16x16x32_bf16 v[100:103], v[172:175], v[196:199], v[100:103]
	v_mfma_f32_16x16x32_bf16 v[96:99], v[180:183], v[196:199], v[96:99]
	v_mfma_f32_16x16x32_bf16 v[84:87], v[172:175], v[204:207], v[84:87]
	v_mfma_f32_16x16x32_bf16 v[80:83], v[180:183], v[204:207], v[80:83]
	v_mfma_f32_16x16x32_bf16 v[68:71], v[172:175], v[212:215], v[68:71]
	v_mfma_f32_16x16x32_bf16 v[64:67], v[180:183], v[212:215], v[64:67]
	v_mfma_f32_16x16x32_bf16 v[116:119], v[176:179], v[192:195], v[116:119]
	v_mfma_f32_16x16x32_bf16 v[112:115], v[184:187], v[192:195], v[112:115]
	v_mfma_f32_16x16x32_bf16 v[100:103], v[176:179], v[200:203], v[100:103]
	v_mfma_f32_16x16x32_bf16 v[96:99], v[184:187], v[200:203], v[96:99]
	v_mfma_f32_16x16x32_bf16 v[84:87], v[176:179], v[208:211], v[84:87]
	v_mfma_f32_16x16x32_bf16 v[80:83], v[184:187], v[208:211], v[80:83]
	v_mfma_f32_16x16x32_bf16 v[68:71], v[176:179], v[216:219], v[68:71]
	v_mfma_f32_16x16x32_bf16 v[64:67], v[184:187], v[216:219], v[64:67]
	s_setprio 0
	s_barrier
; #define PG8_STAGE(bufoff, gbase, voff) do { _Pragma("unroll") for (int _i = 0; _i < 2; ++_i) \
;         __builtin_amdgcn_global_load_lds((const unsigned*)((const char*)(gbase) + (voff)[_i]), (PG8_LAS unsigned*)(lds + (bufoff) + ldsw + _i * 8192), 16, 0, 0); } while (0)
; #define PG8_LDA(dst, b, h) do { _Pragma("unroll") for (int m = 0; m < 4; ++m) _Pragma("unroll") for (int k = 0; k < 2; ++k) dst[m][k] = *(const PG8_LAS bf16x8*)(lds + PG8_SA(b, h) + aoff + m * 2048 + k * 1024); } while (0)
; #define PG8_MMA(ai, bj, At, Bt) do { __builtin_amdgcn_s_setprio(1); _Pragma("unroll") for (int m = 0; m < 4; ++m) _Pragma("unroll") for (int n = 0; n < 2; ++n) _Pragma("unroll") for (int k = 0; k < 2; ++k) \
;         acc[ai][bj][m][n] = __builtin_amdgcn_mfma_f32_16x16x32_bf16(Bt[n][k], At[m][k], acc[ai][bj][m][n], 0, 0, 0); __builtin_amdgcn_s_setprio(0); } while (0)
; #define PG8_WAIT_V(n) asm volatile("s_waitcnt vmcnt(" #n ")" ::: "memory")
; #define PG8_WAIT_L(n) asm volatile("s_waitcnt lgkmcnt(" #n ")" ::: "memory")
; #define PG8_BAR __builtin_amdgcn_s_barrier()
; #define PG8_SCHED __builtin_amdgcn_sched_barrier(0)
; template <class Epi, class Sched, bool ALIGN_EPI = false, bool SP2 = false>
; __device__ __forceinline__ void gemm_phase(PG8_LAS unsigned char* lds, const Gemm g, const Sched& S, const Epi& E) {
;     ...
;             PG8_LDA(At, 1, 1); PG8_STAGE(PG8_SB(1, 0), b3, voffB); PG8_STAGE(PG8_SB(1, 1), b3 + hstep, voffB); PG8_STAGE(PG8_SA(1, 0), a3, voffA);
;             PG8_WAIT_V(8); PG8_WAIT_L(0); PG8_BAR; PG8_MMA(1, 0, At, B0); PG8_MMA(1, 1, At, B1); PG8_BAR; PG8_SCHED;
	s_mov_b32 m0, s81
	v_lshl_add_u64 v[220:221], v[220:221], 0, s[36:37]
	s_add_u32 s72, s76, 0x40080
	ds_read_b128 v[188:191], v138 offset:49152
	ds_read_b128 v[192:195], v138 offset:50176
	ds_read_b128 v[196:199], v138 offset:51200
	ds_read_b128 v[200:203], v138 offset:52224
	ds_read_b128 v[204:207], v138 offset:53248
	ds_read_b128 v[208:211], v138 offset:54272
	ds_read_b128 v[212:215], v138 offset:55296
	ds_read_b128 v[216:219], v138 offset:56320
	global_load_lds_dwordx4 v[220:221], off
	v_lshl_add_u64 v[220:221], v[224:225], 0, s[36:37]
	s_mov_b32 m0, s82
	s_addc_u32 s73, s77, 0
	global_load_lds_dwordx4 v[220:221], off
	v_lshl_add_u64 v[220:221], s[72:73], 0, v[130:131]
	s_mov_b32 m0, s85
	s_nop 0
	global_load_lds_dwordx4 v[220:221], off
	v_lshl_add_u64 v[220:221], s[72:73], 0, v[128:129]
	s_mov_b32 m0, s86
	s_nop 0
	global_load_lds_dwordx4 v[220:221], off
	v_lshl_add_u64 v[220:221], v[226:227], 0, s[36:37]
	s_mov_b32 m0, s83
	s_nop 0
	global_load_lds_dwordx4 v[220:221], off
	v_lshl_add_u64 v[220:221], v[228:229], 0, s[36:37]
	s_mov_b32 m0, s84
	s_nop 0
	global_load_lds_dwordx4 v[220:221], off
	s_waitcnt vmcnt(8)
	s_waitcnt lgkmcnt(0)
	s_barrier
	s_setprio 1
	s_waitcnt lgkmcnt(0)
	v_mfma_f32_16x16x32_bf16 v[60:63], v[156:159], v[188:191], v[60:63]
	v_mfma_f32_16x16x32_bf16 v[56:59], v[164:167], v[188:191], v[56:59]
	v_mfma_f32_16x16x32_bf16 v[44:47], v[156:159], v[196:199], v[44:47]
	v_mfma_f32_16x16x32_bf16 v[40:43], v[164:167], v[196:199], v[40:43]
	v_mfma_f32_16x16x32_bf16 v[28:31], v[156:159], v[204:207], v[28:31]
	v_mfma_f32_16x16x32_bf16 v[24:27], v[164:167], v[204:207], v[24:27]
	v_mfma_f32_16x16x32_bf16 v[12:15], v[156:159], v[212:215], v[12:15]
	v_mfma_f32_16x16x32_bf16 v[8:11], v[164:167], v[212:215], v[8:11]
	v_mfma_f32_16x16x32_bf16 v[60:63], v[160:163], v[192:195], v[60:63]
	v_mfma_f32_16x16x32_bf16 v[56:59], v[168:171], v[192:195], v[56:59]
	v_mfma_f32_16x16x32_bf16 v[44:47], v[160:163], v[200:203], v[44:47]
	v_mfma_f32_16x16x32_bf16 v[40:43], v[168:171], v[200:203], v[40:43]
	v_mfma_f32_16x16x32_bf16 v[28:31], v[160:163], v[208:211], v[28:31]
	v_mfma_f32_16x16x32_bf16 v[24:27], v[168:171], v[208:211], v[24:27]
	v_mfma_f32_16x16x32_bf16 v[12:15], v[160:163], v[216:219], v[12:15]
	v_mfma_f32_16x16x32_bf16 v[8:11], v[168:171], v[216:219], v[8:11]
	s_setprio 0
	s_setprio 1
	v_mfma_f32_16x16x32_bf16 v[52:55], v[172:175], v[188:191], v[52:55]
	v_mfma_f32_16x16x32_bf16 v[48:51], v[180:183], v[188:191], v[48:51]
	v_mfma_f32_16x16x32_bf16 v[36:39], v[172:175], v[196:199], v[36:39]
	v_mfma_f32_16x16x32_bf16 v[32:35], v[180:183], v[196:199], v[32:35]
	v_mfma_f32_16x16x32_bf16 v[20:23], v[172:175], v[204:207], v[20:23]
	v_mfma_f32_16x16x32_bf16 v[16:19], v[180:183], v[204:207], v[16:19]
	v_mfma_f32_16x16x32_bf16 v[4:7], v[172:175], v[212:215], v[4:7]
	v_mfma_f32_16x16x32_bf16 v[0:3], v[180:183], v[212:215], v[0:3]
	v_mfma_f32_16x16x32_bf16 v[52:55], v[176:179], v[192:195], v[52:55]
	v_mfma_f32_16x16x32_bf16 v[48:51], v[184:187], v[192:195], v[48:51]
	v_mfma_f32_16x16x32_bf16 v[36:39], v[176:179], v[200:203], v[36:39]
	v_mfma_f32_16x16x32_bf16 v[32:35], v[184:187], v[200:203], v[32:35]
	v_mfma_f32_16x16x32_bf16 v[20:23], v[176:179], v[208:211], v[20:23]
	v_mfma_f32_16x16x32_bf16 v[16:19], v[184:187], v[208:211], v[16:19]
	v_mfma_f32_16x16x32_bf16 v[4:7], v[176:179], v[216:219], v[4:7]
	v_mfma_f32_16x16x32_bf16 v[0:3], v[184:187], v[216:219], v[0:3]
	s_setprio 0
	s_barrier
	s_add_u32 s90, s90, 0x100
	s_addc_u32 s92, s92, 0
	s_mov_b64 s[72:73], s[74:75]
	s_mov_b32 s6, s7

;     __host__ __device__ bool next(int i, Unit& u) const { const int L = i * G + c; if (L >= 16 * nkc) return false; u.kc = L % nkc; const int t = L / nkc; u.pn = t & 3; u.pm = 33 * (t >> 2); return true; }
; #define PG8_STAGE(bufoff, gbase, voff) do { _Pragma("unroll") for (int _i = 0; _i < 2; ++_i) \
;         __builtin_amdgcn_global_load_lds((const unsigned*)((const char*)(gbase) + (voff)[_i]), (PG8_LAS unsigned*)(lds + (bufoff) + ldsw + _i * 8192), 16, 0, 0); } while (0)
; #define PG8_LDA(dst, b, h) do { _Pragma("unroll") for (int m = 0; m < 4; ++m) _Pragma("unroll") for (int k = 0; k < 2; ++k) dst[m][k] = *(const PG8_LAS bf16x8*)(lds + PG8_SA(b, h) + aoff + m * 2048 + k * 1024); } while (0)
; #define PG8_LDB(dst, b, h) do { _Pragma("unroll") for (int n = 0; n < 2; ++n) _Pragma("unroll") for (int k = 0; k < 2; ++k) dst[n][k] = *(const PG8_LAS bf16x8*)(lds + PG8_SB(b, h) + boff + n * 2048 + k * 1024); } while (0)
; #define PG8_BAR __builtin_amdgcn_s_barrier()
; template <class Epi, class Sched, bool ALIGN_EPI = false, bool SP2 = false>
; __device__ __forceinline__ void gemm_phase(PG8_LAS unsigned char* lds, const Gemm g, const Sched& S, const Epi& E) {
;     ...
;         const bool has_next = S.next(ui + 1, nxt);
;         const char* nA = has_next ? (const char*)g.A + (size_t)nxt.pm * tstep + (size_t)nxt.kc * cstep : cA; const char* nB = has_next ? (const char*)g.Bt + (size_t)nxt.pn * tstep + (size_t)nxt.kc * cstep : cB;
;         for (int t = 0; t < nt; t += 2) {
;             const bool last = (t == nt - 2);
;             const char* a1 = cA + (size_t)(t + 1) * kstep;
;             const char* a2 = last ? nA : cA + (size_t)(t + 2) * kstep; const char* b2 = last ? nB : cB + (size_t)(t + 2) * kstep;
;             const char* a3 = a2 + kstep; const char* b3 = b2 + kstep;
;             if (last && has_next) S.a_ready(nxt);
;             if constexpr (SP2) {
;             PG8_LDB(B0, 0, 0); PG8_LDB(B1, 0, 1); PG8_SCHED; PG8_LDA(At, 0, 0); PG8_STAGE(PG8_SA(1, 1), a1 + hstep, voffA);
;             PG8_WAIT_V(8); PG8_WAIT_L(0); PG8_BAR; PG8_MMA(0, 0, At, B0); PG8_MMA(0, 1, At, B1); PG8_BAR; PG8_SCHED;
;             PG8_LDA(At, 0, 1); PG8_STAGE(PG8_SB(0, 0), b2, voffB); PG8_STAGE(PG8_SB(0, 1), b2 + hstep, voffB); PG8_STAGE(PG8_SA(0, 0), a2, voffA);
;             PG8_WAIT_V(8); PG8_WAIT_L(0); PG8_BAR; PG8_MMA(1, 0, At, B0); PG8_MMA(1, 1, At, B1); PG8_BAR; PG8_SCHED;
.LBB0_792:
	s_ashr_i32 s55, s54, 31
	s_lshl_b64 s[6:7], s[54:55], 19
	s_add_u32 s56, s46, s6
	s_addc_u32 s57, s47, s7
	s_and_b64 s[6:7], s[4:5], exec
	s_cselect_b32 s55, s57, s63
	s_cselect_b32 s82, s56, s62
	s_ashr_i32 s53, s52, 31
	s_lshl_b64 s[6:7], s[52:53], 19
	s_add_u32 s58, s1, s6
	s_addc_u32 s59, s3, s7
	s_and_b64 s[6:7], s[4:5], exec
	s_cselect_b32 s53, s59, s65
	s_cselect_b32 s83, s58, s64
	s_add_u32 s62, s62, 0x40080
	s_addc_u32 s63, s63, 0
	s_add_u32 s84, s64, 0x100
	s_addc_u32 s85, s65, 0
	s_mov_b32 s86, -2
	ds_read_b128 v[166:169], v149
	ds_read_b128 v[170:173], v150
	ds_read_b128 v[174:177], v151
	ds_read_b128 v[178:181], v152
	ds_read_b128 v[182:185], v153
	ds_read_b128 v[186:189], v154
	ds_read_b128 v[190:193], v155
	ds_read_b128 v[194:197], v156
	s_add_u32 s6, s62, 0xfffc0080
	s_addc_u32 s7, s63, -1
	s_cmp_eq_u32 s86, 12
	s_cselect_b32 s67, s55, s7
	s_cselect_b32 s66, s82, s6
	s_cselect_b32 s65, s53, s85
	s_cselect_b32 s64, s83, s84
	s_mov_b32 m0, s79
	v_lshl_add_u64 v[144:145], s[62:63], 0, v[136:137]
	ds_read_b128 v[198:201], v147
	ds_read_b128 v[202:205], v147 offset:1024
	ds_read_b128 v[206:209], v147 offset:2048
	ds_read_b128 v[210:213], v147 offset:3072
	ds_read_b128 v[214:217], v147 offset:4096
	ds_read_b128 v[218:221], v147 offset:5120
	ds_read_b128 v[224:227], v147 offset:6144
	ds_read_b128 v[228:231], v147 offset:7168
	global_load_lds_dwordx4 v[144:145], off
	v_lshl_add_u64 v[144:145], s[62:63], 0, v[138:139]
	s_mov_b32 m0, s80
	s_nop 0
	global_load_lds_dwordx4 v[144:145], off
	s_waitcnt vmcnt(8)
	s_waitcnt lgkmcnt(0)
	s_barrier
	s_setprio 1
	s_waitcnt lgkmcnt(0)
	v_mfma_f32_16x16x32_bf16 v[124:127], v[166:169], v[198:201], 0
	v_mfma_f32_16x16x32_bf16 v[120:123], v[174:177], v[198:201], 0
	v_mfma_f32_16x16x32_bf16 v[108:111], v[166:169], v[206:209], 0
	v_mfma_f32_16x16x32_bf16 v[104:107], v[174:177], v[206:209], 0
	v_mfma_f32_16x16x32_bf16 v[92:95], v[166:169], v[214:217], 0
	v_mfma_f32_16x16x32_bf16 v[88:91], v[174:177], v[214:217], 0
	v_mfma_f32_16x16x32_bf16 v[76:79], v[166:169], v[224:227], 0
	v_mfma_f32_16x16x32_bf16 v[72:75], v[174:177], v[224:227], 0
	v_mfma_f32_16x16x32_bf16 v[124:127], v[170:173], v[202:205], v[124:127]
	v_mfma_f32_16x16x32_bf16 v[120:123], v[178:181], v[202:205], v[120:123]
	v_mfma_f32_16x16x32_bf16 v[108:111], v[170:173], v[210:213], v[108:111]
	v_mfma_f32_16x16x32_bf16 v[104:107], v[178:181], v[210:213], v[104:107]
	v_mfma_f32_16x16x32_bf16 v[92:95], v[170:173], v[218:221], v[92:95]
	v_mfma_f32_16x16x32_bf16 v[88:91], v[178:181], v[218:221], v[88:91]
	v_mfma_f32_16x16x32_bf16 v[76:79], v[170:173], v[228:231], v[76:79]
	v_mfma_f32_16x16x32_bf16 v[72:75], v[178:181], v[228:231], v[72:75]
	s_setprio 0
	s_setprio 1
	v_mfma_f32_16x16x32_bf16 v[116:119], v[182:185], v[198:201], 0
	v_mfma_f32_16x16x32_bf16 v[112:115], v[190:193], v[198:201], 0
	v_mfma_f32_16x16x32_bf16 v[100:103], v[182:185], v[206:209], 0
	v_mfma_f32_16x16x32_bf16 v[96:99], v[190:193], v[206:209], 0
	v_mfma_f32_16x16x32_bf16 v[84:87], v[182:185], v[214:217], 0
	v_mfma_f32_16x16x32_bf16 v[80:83], v[190:193], v[214:217], 0
	v_mfma_f32_16x16x32_bf16 v[68:71], v[182:185], v[224:227], 0
	v_mfma_f32_16x16x32_bf16 v[64:67], v[190:193], v[224:227], 0
	v_mfma_f32_16x16x32_bf16 v[116:119], v[186:189], v[202:205], v[116:119]
	v_mfma_f32_16x16x32_bf16 v[112:115], v[194:197], v[202:205], v[112:115]
	v_mfma_f32_16x16x32_bf16 v[100:103], v[186:189], v[210:213], v[100:103]
	v_mfma_f32_16x16x32_bf16 v[96:99], v[194:197], v[210:213], v[96:99]
	v_mfma_f32_16x16x32_bf16 v[84:87], v[186:189], v[218:221], v[84:87]
	v_mfma_f32_16x16x32_bf16 v[80:83], v[194:197], v[218:221], v[80:83]
	v_mfma_f32_16x16x32_bf16 v[68:71], v[186:189], v[228:231], v[68:71]
	v_mfma_f32_16x16x32_bf16 v[64:67], v[194:197], v[228:231], v[64:67]
	s_setprio 0
	s_barrier
	s_mov_b32 m0, s15
	v_lshl_add_u64 v[144:145], s[64:65], 0, v[132:133]
	s_add_u32 s6, s64, 0x40000
	ds_read_b128 v[198:201], v147 offset:16384
	ds_read_b128 v[202:205], v147 offset:17408
	ds_read_b128 v[206:209], v147 offset:18432
	ds_read_b128 v[210:213], v147 offset:19456
	ds_read_b128 v[214:217], v147 offset:20480
	ds_read_b128 v[218:221], v147 offset:21504
	ds_read_b128 v[224:227], v147 offset:22528
	ds_read_b128 v[228:231], v147 offset:23552
	global_load_lds_dwordx4 v[144:145], off
	v_lshl_add_u64 v[232:233], s[64:65], 0, v[128:129]
	s_mov_b32 m0, s39
	s_addc_u32 s7, s65, 0
	global_load_lds_dwordx4 v[232:233], off
	v_lshl_add_u64 v[234:235], s[6:7], 0, v[132:133]
	s_mov_b32 m0, s43
	v_lshl_add_u64 v[236:237], s[66:67], 0, v[130:131]
	global_load_lds_dwordx4 v[234:235], off
	v_lshl_add_u64 v[234:235], s[6:7], 0, v[128:129]
	s_mov_b32 m0, s61
	s_nop 0
	global_load_lds_dwordx4 v[234:235], off
	v_lshl_add_u64 v[234:235], s[66:67], 0, v[134:135]
	s_mov_b32 m0, s12
	s_nop 0
	global_load_lds_dwordx4 v[234:235], off
	s_mov_b32 m0, s68
	s_nop 0
	global_load_lds_dwordx4 v[236:237], off
	s_waitcnt vmcnt(8)
	s_waitcnt lgkmcnt(0)
	s_barrier
; #define PG8_STAGE(bufoff, gbase, voff) do { _Pragma("unroll") for (int _i = 0; _i < 2; ++_i) \
;         __builtin_amdgcn_global_load_lds((const unsigned*)((const char*)(gbase) + (voff)[_i]), (PG8_LAS unsigned*)(lds + (bufoff) + ldsw + _i * 8192), 16, 0, 0); } while (0)
; #define PG8_LDA(dst, b, h) do { _Pragma("unroll") for (int m = 0; m < 4; ++m) _Pragma("unroll") for (int k = 0; k < 2; ++k) dst[m][k] = *(const PG8_LAS bf16x8*)(lds + PG8_SA(b, h) + aoff + m * 2048 + k * 1024); } while (0)
; #define PG8_LDB(dst, b, h) do { _Pragma("unroll") for (int n = 0; n < 2; ++n) _Pragma("unroll") for (int k = 0; k < 2; ++k) dst[n][k] = *(const PG8_LAS bf16x8*)(lds + PG8_SB(b, h) + boff + n * 2048 + k * 1024); } while (0)
; #define PG8_MMA(ai, bj, At, Bt) do { __builtin_amdgcn_s_setprio(1); _Pragma("unroll") for (int m = 0; m < 4; ++m) _Pragma("unroll") for (int n = 0; n < 2; ++n) _Pragma("unroll") for (int k = 0; k < 2; ++k) \
;         acc[ai][bj][m][n] = __builtin_amdgcn_mfma_f32_16x16x32_bf16(Bt[n][k], At[m][k], acc[ai][bj][m][n], 0, 0, 0); __builtin_amdgcn_s_setprio(0); } while (0)
; #define PG8_WAIT_V(n) asm volatile("s_waitcnt vmcnt(" #n ")" ::: "memory")
; #define PG8_WAIT_L(n) asm volatile("s_waitcnt lgkmcnt(" #n ")" ::: "memory")
; #define PG8_BAR __builtin_amdgcn_s_barrier()
; #define PG8_SCHED __builtin_amdgcn_sched_barrier(0)
; template <class Epi, class Sched, bool ALIGN_EPI = false, bool SP2 = false>
; __device__ __forceinline__ void gemm_phase(PG8_LAS unsigned char* lds, const Gemm g, const Sched& S, const Epi& E) {
;     ...
;             PG8_WAIT_V(8); PG8_WAIT_L(0); PG8_BAR; PG8_MMA(1, 0, At, B0); PG8_MMA(1, 1, At, B1); PG8_BAR; PG8_SCHED;
;             PG8_LDB(B0, 1, 0); PG8_LDB(B1, 1, 1); PG8_SCHED; PG8_LDA(At, 1, 0); PG8_STAGE(PG8_SA(0, 1), a2 + hstep, voffA);
;             PG8_WAIT_V(8); PG8_WAIT_L(0); PG8_BAR; PG8_MMA(0, 0, At, B0); PG8_MMA(0, 1, At, B1); PG8_BAR; PG8_SCHED;
	s_setprio 1
	s_waitcnt lgkmcnt(0)
	v_mfma_f32_16x16x32_bf16 v[60:63], v[166:169], v[198:201], 0
	v_mfma_f32_16x16x32_bf16 v[56:59], v[174:177], v[198:201], 0
	v_mfma_f32_16x16x32_bf16 v[44:47], v[166:169], v[206:209], 0
	v_mfma_f32_16x16x32_bf16 v[40:43], v[174:177], v[206:209], 0
	v_mfma_f32_16x16x32_bf16 v[28:31], v[166:169], v[214:217], 0
	v_mfma_f32_16x16x32_bf16 v[24:27], v[174:177], v[214:217], 0
	v_mfma_f32_16x16x32_bf16 v[12:15], v[166:169], v[224:227], 0
	v_mfma_f32_16x16x32_bf16 v[8:11], v[174:177], v[224:227], 0
	v_mfma_f32_16x16x32_bf16 v[60:63], v[170:173], v[202:205], v[60:63]
	v_mfma_f32_16x16x32_bf16 v[56:59], v[178:181], v[202:205], v[56:59]
	v_mfma_f32_16x16x32_bf16 v[44:47], v[170:173], v[210:213], v[44:47]
	v_mfma_f32_16x16x32_bf16 v[40:43], v[178:181], v[210:213], v[40:43]
	v_mfma_f32_16x16x32_bf16 v[28:31], v[170:173], v[218:221], v[28:31]
	v_mfma_f32_16x16x32_bf16 v[24:27], v[178:181], v[218:221], v[24:27]
	v_mfma_f32_16x16x32_bf16 v[12:15], v[170:173], v[228:231], v[12:15]
	v_mfma_f32_16x16x32_bf16 v[8:11], v[178:181], v[228:231], v[8:11]
	s_setprio 0
	s_setprio 1
	v_mfma_f32_16x16x32_bf16 v[52:55], v[182:185], v[198:201], 0
	v_mfma_f32_16x16x32_bf16 v[48:51], v[190:193], v[198:201], 0
	v_mfma_f32_16x16x32_bf16 v[36:39], v[182:185], v[206:209], 0
	v_mfma_f32_16x16x32_bf16 v[32:35], v[190:193], v[206:209], 0
	v_mfma_f32_16x16x32_bf16 v[20:23], v[182:185], v[214:217], 0
	v_mfma_f32_16x16x32_bf16 v[16:19], v[190:193], v[214:217], 0
	v_mfma_f32_16x16x32_bf16 v[4:7], v[182:185], v[224:227], 0
	v_mfma_f32_16x16x32_bf16 v[0:3], v[190:193], v[224:227], 0
	v_mfma_f32_16x16x32_bf16 v[52:55], v[186:189], v[202:205], v[52:55]
	v_mfma_f32_16x16x32_bf16 v[48:51], v[194:197], v[202:205], v[48:51]
	v_mfma_f32_16x16x32_bf16 v[36:39], v[186:189], v[210:213], v[36:39]
	v_mfma_f32_16x16x32_bf16 v[32:35], v[194:197], v[210:213], v[32:35]
	v_mfma_f32_16x16x32_bf16 v[20:23], v[186:189], v[218:221], v[20:23]
	v_mfma_f32_16x16x32_bf16 v[16:19], v[194:197], v[218:221], v[16:19]
	v_mfma_f32_16x16x32_bf16 v[4:7], v[186:189], v[228:231], v[4:7]
	v_mfma_f32_16x16x32_bf16 v[0:3], v[194:197], v[228:231], v[0:3]
	s_setprio 0
	s_barrier
	ds_read_b128 v[166:169], v157
	ds_read_b128 v[170:173], v158
	ds_read_b128 v[174:177], v159
	ds_read_b128 v[178:181], v160
	ds_read_b128 v[182:185], v161
	ds_read_b128 v[186:189], v162
	ds_read_b128 v[190:193], v163
	ds_read_b128 v[194:197], v164
	s_add_u32 s6, s66, 0x40000
	s_addc_u32 s7, s67, 0
	s_mov_b32 m0, s69
	v_lshl_add_u64 v[238:239], s[6:7], 0, v[134:135]
	ds_read_b128 v[198:201], v147 offset:32768
	ds_read_b128 v[202:205], v147 offset:33792
	ds_read_b128 v[206:209], v147 offset:34816
	ds_read_b128 v[210:213], v147 offset:35840
	ds_read_b128 v[214:217], v147 offset:36864
	ds_read_b128 v[218:221], v147 offset:37888
	ds_read_b128 v[224:227], v147 offset:38912
	ds_read_b128 v[228:231], v147 offset:39936
	global_load_lds_dwordx4 v[238:239], off
	v_lshl_add_u64 v[238:239], s[6:7], 0, v[130:131]
	s_mov_b32 m0, s70
	s_nop 0
	global_load_lds_dwordx4 v[238:239], off
	s_waitcnt vmcnt(8)
	s_waitcnt lgkmcnt(0)
	s_barrier
	s_setprio 1
	s_waitcnt lgkmcnt(0)
	v_mfma_f32_16x16x32_bf16 v[124:127], v[166:169], v[198:201], v[124:127]
	v_mfma_f32_16x16x32_bf16 v[120:123], v[174:177], v[198:201], v[120:123]
	v_mfma_f32_16x16x32_bf16 v[108:111], v[166:169], v[206:209], v[108:111]
	v_mfma_f32_16x16x32_bf16 v[104:107], v[174:177], v[206:209], v[104:107]
	v_mfma_f32_16x16x32_bf16 v[92:95], v[166:169], v[214:217], v[92:95]
	v_mfma_f32_16x16x32_bf16 v[88:91], v[174:177], v[214:217], v[88:91]
	v_mfma_f32_16x16x32_bf16 v[76:79], v[166:169], v[224:227], v[76:79]
	v_mfma_f32_16x16x32_bf16 v[72:75], v[174:177], v[224:227], v[72:75]
	v_mfma_f32_16x16x32_bf16 v[124:127], v[170:173], v[202:205], v[124:127]
	v_mfma_f32_16x16x32_bf16 v[120:123], v[178:181], v[202:205], v[120:123]
	v_mfma_f32_16x16x32_bf16 v[108:111], v[170:173], v[210:213], v[108:111]
	v_mfma_f32_16x16x32_bf16 v[104:107], v[178:181], v[210:213], v[104:107]
	v_mfma_f32_16x16x32_bf16 v[92:95], v[170:173], v[218:221], v[92:95]
	v_mfma_f32_16x16x32_bf16 v[88:91], v[178:181], v[218:221], v[88:91]
	v_mfma_f32_16x16x32_bf16 v[76:79], v[170:173], v[228:231], v[76:79]
	v_mfma_f32_16x16x32_bf16 v[72:75], v[178:181], v[228:231], v[72:75]
	s_setprio 0
	s_setprio 1
	v_mfma_f32_16x16x32_bf16 v[116:119], v[182:185], v[198:201], v[116:119]
	v_mfma_f32_16x16x32_bf16 v[112:115], v[190:193], v[198:201], v[112:115]
	v_mfma_f32_16x16x32_bf16 v[100:103], v[182:185], v[206:209], v[100:103]
	v_mfma_f32_16x16x32_bf16 v[96:99], v[190:193], v[206:209], v[96:99]
	v_mfma_f32_16x16x32_bf16 v[84:87], v[182:185], v[214:217], v[84:87]
	v_mfma_f32_16x16x32_bf16 v[80:83], v[190:193], v[214:217], v[80:83]
	v_mfma_f32_16x16x32_bf16 v[68:71], v[182:185], v[224:227], v[68:71]
	v_mfma_f32_16x16x32_bf16 v[64:67], v[190:193], v[224:227], v[64:67]
	v_mfma_f32_16x16x32_bf16 v[116:119], v[186:189], v[202:205], v[116:119]
	v_mfma_f32_16x16x32_bf16 v[112:115], v[194:197], v[202:205], v[112:115]
	v_mfma_f32_16x16x32_bf16 v[100:103], v[186:189], v[210:213], v[100:103]
	v_mfma_f32_16x16x32_bf16 v[96:99], v[194:197], v[210:213], v[96:99]
	v_mfma_f32_16x16x32_bf16 v[84:87], v[186:189], v[218:221], v[84:87]
	v_mfma_f32_16x16x32_bf16 v[80:83], v[194:197], v[218:221], v[80:83]
	v_mfma_f32_16x16x32_bf16 v[68:71], v[186:189], v[228:231], v[68:71]
	v_mfma_f32_16x16x32_bf16 v[64:67], v[194:197], v[228:231], v[64:67]
	s_setprio 0
	s_barrier
; #define PG8_STAGE(bufoff, gbase, voff) do { _Pragma("unroll") for (int _i = 0; _i < 2; ++_i) \
;         __builtin_amdgcn_global_load_lds((const unsigned*)((const char*)(gbase) + (voff)[_i]), (PG8_LAS unsigned*)(lds + (bufoff) + ldsw + _i * 8192), 16, 0, 0); } while (0)
; #define PG8_LDA(dst, b, h) do { _Pragma("unroll") for (int m = 0; m < 4; ++m) _Pragma("unroll") for (int k = 0; k < 2; ++k) dst[m][k] = *(const PG8_LAS bf16x8*)(lds + PG8_SA(b, h) + aoff + m * 2048 + k * 1024); } while (0)
; #define PG8_MMA(ai, bj, At, Bt) do { __builtin_amdgcn_s_setprio(1); _Pragma("unroll") for (int m = 0; m < 4; ++m) _Pragma("unroll") for (int n = 0; n < 2; ++n) _Pragma("unroll") for (int k = 0; k < 2; ++k) \
;         acc[ai][bj][m][n] = __builtin_amdgcn_mfma_f32_16x16x32_bf16(Bt[n][k], At[m][k], acc[ai][bj][m][n], 0, 0, 0); __builtin_amdgcn_s_setprio(0); } while (0)
; #define PG8_WAIT_V(n) asm volatile("s_waitcnt vmcnt(" #n ")" ::: "memory")
; #define PG8_WAIT_L(n) asm volatile("s_waitcnt lgkmcnt(" #n ")" ::: "memory")
; #define PG8_BAR __builtin_amdgcn_s_barrier()
; #define PG8_SCHED __builtin_amdgcn_sched_barrier(0)
; template <class Epi, class Sched, bool ALIGN_EPI = false, bool SP2 = false>
; __device__ __forceinline__ void gemm_phase(PG8_LAS unsigned char* lds, const Gemm g, const Sched& S, const Epi& E) {
;     ...
;             PG8_LDA(At, 1, 1); PG8_STAGE(PG8_SB(1, 0), b3, voffB); PG8_STAGE(PG8_SB(1, 1), b3 + hstep, voffB); PG8_STAGE(PG8_SA(1, 0), a3, voffA);
;             PG8_WAIT_V(8); PG8_WAIT_L(0); PG8_BAR; PG8_MMA(1, 0, At, B0); PG8_MMA(1, 1, At, B1); PG8_BAR; PG8_SCHED;
	s_mov_b32 m0, s72
	v_lshl_add_u64 v[144:145], v[144:145], 0, s[36:37]
	s_add_u32 s6, s64, 0x40080
	ds_read_b128 v[198:201], v147 offset:49152
	ds_read_b128 v[202:205], v147 offset:50176
	ds_read_b128 v[206:209], v147 offset:51200
	ds_read_b128 v[210:213], v147 offset:52224
	ds_read_b128 v[214:217], v147 offset:53248
	ds_read_b128 v[218:221], v147 offset:54272
	ds_read_b128 v[224:227], v147 offset:55296
	ds_read_b128 v[228:231], v147 offset:56320
	global_load_lds_dwordx4 v[144:145], off
	v_lshl_add_u64 v[144:145], v[232:233], 0, s[36:37]
	s_mov_b32 m0, s73
	s_addc_u32 s7, s65, 0
	global_load_lds_dwordx4 v[144:145], off
	v_lshl_add_u64 v[144:145], s[6:7], 0, v[132:133]
	s_mov_b32 m0, s76
	s_nop 0
	global_load_lds_dwordx4 v[144:145], off
	v_lshl_add_u64 v[144:145], s[6:7], 0, v[128:129]
	s_mov_b32 m0, s77
	s_nop 0
	global_load_lds_dwordx4 v[144:145], off
	v_lshl_add_u64 v[144:145], v[234:235], 0, s[36:37]
	s_mov_b32 m0, s74
	s_nop 0
	global_load_lds_dwordx4 v[144:145], off
	v_lshl_add_u64 v[144:145], v[236:237], 0, s[36:37]
	s_mov_b32 m0, s75
	s_nop 0
	global_load_lds_dwordx4 v[144:145], off
	s_waitcnt vmcnt(8)
	s_waitcnt lgkmcnt(0)
	s_barrier
	s_setprio 1
	s_waitcnt lgkmcnt(0)
	v_mfma_f32_16x16x32_bf16 v[60:63], v[166:169], v[198:201], v[60:63]
	v_mfma_f32_16x16x32_bf16 v[56:59], v[174:177], v[198:201], v[56:59]
	v_mfma_f32_16x16x32_bf16 v[44:47], v[166:169], v[206:209], v[44:47]
	v_mfma_f32_16x16x32_bf16 v[40:43], v[174:177], v[206:209], v[40:43]
	v_mfma_f32_16x16x32_bf16 v[28:31], v[166:169], v[214:217], v[28:31]
	v_mfma_f32_16x16x32_bf16 v[24:27], v[174:177], v[214:217], v[24:27]
	v_mfma_f32_16x16x32_bf16 v[12:15], v[166:169], v[224:227], v[12:15]
	v_mfma_f32_16x16x32_bf16 v[8:11], v[174:177], v[224:227], v[8:11]
	v_mfma_f32_16x16x32_bf16 v[60:63], v[170:173], v[202:205], v[60:63]
	v_mfma_f32_16x16x32_bf16 v[56:59], v[178:181], v[202:205], v[56:59]
	v_mfma_f32_16x16x32_bf16 v[44:47], v[170:173], v[210:213], v[44:47]
	v_mfma_f32_16x16x32_bf16 v[40:43], v[178:181], v[210:213], v[40:43]
	v_mfma_f32_16x16x32_bf16 v[28:31], v[170:173], v[218:221], v[28:31]
	v_mfma_f32_16x16x32_bf16 v[24:27], v[178:181], v[218:221], v[24:27]
	v_mfma_f32_16x16x32_bf16 v[12:15], v[170:173], v[228:231], v[12:15]
	v_mfma_f32_16x16x32_bf16 v[8:11], v[178:181], v[228:231], v[8:11]
	s_setprio 0
	s_setprio 1
	v_mfma_f32_16x16x32_bf16 v[52:55], v[182:185], v[198:201], v[52:55]
	v_mfma_f32_16x16x32_bf16 v[48:51], v[190:193], v[198:201], v[48:51]
	v_mfma_f32_16x16x32_bf16 v[36:39], v[182:185], v[206:209], v[36:39]
	v_mfma_f32_16x16x32_bf16 v[32:35], v[190:193], v[206:209], v[32:35]
	v_mfma_f32_16x16x32_bf16 v[20:23], v[182:185], v[214:217], v[20:23]
	v_mfma_f32_16x16x32_bf16 v[16:19], v[190:193], v[214:217], v[16:19]
	v_mfma_f32_16x16x32_bf16 v[4:7], v[182:185], v[224:227], v[4:7]
	v_mfma_f32_16x16x32_bf16 v[0:3], v[190:193], v[224:227], v[0:3]
	v_mfma_f32_16x16x32_bf16 v[52:55], v[186:189], v[202:205], v[52:55]
	v_mfma_f32_16x16x32_bf16 v[48:51], v[194:197], v[202:205], v[48:51]
	v_mfma_f32_16x16x32_bf16 v[36:39], v[186:189], v[210:213], v[36:39]
	v_mfma_f32_16x16x32_bf16 v[32:35], v[194:197], v[210:213], v[32:35]
	v_mfma_f32_16x16x32_bf16 v[20:23], v[186:189], v[218:221], v[20:23]
	v_mfma_f32_16x16x32_bf16 v[16:19], v[194:197], v[218:221], v[16:19]
	v_mfma_f32_16x16x32_bf16 v[4:7], v[186:189], v[228:231], v[4:7]
	v_mfma_f32_16x16x32_bf16 v[0:3], v[194:197], v[228:231], v[0:3]
	s_setprio 0
	s_barrier
	s_add_i32 s86, s86, 2
	s_add_u32 s62, s62, 0x100
	s_addc_u32 s63, s63, 0
	s_add_u32 s84, s84, 0x100
	s_addc_u32 s85, s85, 0

;     __host__ __device__ bool next(int i, Unit& u) const { const int L = i * G + c; if (L >= 16 * nkc) return false; u.kc = L % nkc; const int t = L / nkc; u.pn = t & 3; u.pm = 33 * (t >> 2); return true; }
; #define PG8_STAGE(bufoff, gbase, voff) do { _Pragma("unroll") for (int _i = 0; _i < 2; ++_i) \
;         __builtin_amdgcn_global_load_lds((const unsigned*)((const char*)(gbase) + (voff)[_i]), (PG8_LAS unsigned*)(lds + (bufoff) + ldsw + _i * 8192), 16, 0, 0); } while (0)
; #define PG8_LDA(dst, b, h) do { _Pragma("unroll") for (int m = 0; m < 4; ++m) _Pragma("unroll") for (int k = 0; k < 2; ++k) dst[m][k] = *(const PG8_LAS bf16x8*)(lds + PG8_SA(b, h) + aoff + m * 2048 + k * 1024); } while (0)
; #define PG8_LDB(dst, b, h) do { _Pragma("unroll") for (int n = 0; n < 2; ++n) _Pragma("unroll") for (int k = 0; k < 2; ++k) dst[n][k] = *(const PG8_LAS bf16x8*)(lds + PG8_SB(b, h) + boff + n * 2048 + k * 1024); } while (0)
; #define PG8_BAR __builtin_amdgcn_s_barrier()
; template <class Epi, class Sched, bool ALIGN_EPI = false, bool SP2 = false>
; __device__ __forceinline__ void gemm_phase(PG8_LAS unsigned char* lds, const Gemm g, const Sched& S, const Epi& E) {
;     ...
;         const bool has_next = S.next(ui + 1, nxt);
;         const char* nA = has_next ? (const char*)g.A + (size_t)nxt.pm * tstep + (size_t)nxt.kc * cstep : cA; const char* nB = has_next ? (const char*)g.Bt + (size_t)nxt.pn * tstep + (size_t)nxt.kc * cstep : cB;
;         for (int t = 0; t < nt; t += 2) {
;             const bool last = (t == nt - 2);
;             const char* a1 = cA + (size_t)(t + 1) * kstep;
;             const char* a2 = last ? nA : cA + (size_t)(t + 2) * kstep; const char* b2 = last ? nB : cB + (size_t)(t + 2) * kstep;
;             const char* a3 = a2 + kstep; const char* b3 = b2 + kstep;
;             if (last && has_next) S.a_ready(nxt);
;             if constexpr (SP2) {
;             PG8_LDB(B0, 0, 0); PG8_LDB(B1, 0, 1); PG8_SCHED; PG8_LDA(At, 0, 0); PG8_STAGE(PG8_SA(1, 1), a1 + hstep, voffA);
;             PG8_WAIT_V(8); PG8_WAIT_L(0); PG8_BAR; PG8_MMA(0, 0, At, B0); PG8_MMA(0, 1, At, B1); PG8_BAR; PG8_SCHED;
;             PG8_LDA(At, 0, 1); PG8_STAGE(PG8_SB(0, 0), b2, voffB); PG8_STAGE(PG8_SB(0, 1), b2 + hstep, voffB); PG8_STAGE(PG8_SA(0, 0), a2, voffA);
;             PG8_WAIT_V(8); PG8_WAIT_L(0); PG8_BAR; PG8_MMA(1, 0, At, B0); PG8_MMA(1, 1, At, B1); PG8_BAR; PG8_SCHED;
.LBB0_872:
	s_add_u32 s57, s60, 0x100
	s_addc_u32 s88, s61, 0
	s_mov_b32 s89, -2
	ds_read_b128 v[142:145], v174
	ds_read_b128 v[146:149], v175
	ds_read_b128 v[150:153], v176
	ds_read_b128 v[154:157], v177
	ds_read_b128 v[158:161], v178
	ds_read_b128 v[162:165], v179
	ds_read_b128 v[166:169], v180
	ds_read_b128 v[190:193], v181
	s_add_u32 s60, s58, 0x100
	s_addc_u32 s61, s59, 0
	s_cmp_eq_u32 s89, 40
	s_cselect_b32 s65, s9, s61
	s_cselect_b32 s64, s8, s60
	s_cselect_b32 s63, s55, s88
	s_cselect_b32 s62, s54, s57
	s_mov_b32 m0, s78
	v_lshl_add_u64 v[170:171], s[58:59], 0, v[134:135]
	ds_read_b128 v[194:197], v172
	ds_read_b128 v[198:201], v172 offset:1024
	ds_read_b128 v[202:205], v172 offset:2048
	ds_read_b128 v[206:209], v172 offset:3072
	ds_read_b128 v[210:213], v172 offset:4096
	ds_read_b128 v[214:217], v172 offset:5120
	ds_read_b128 v[218:221], v172 offset:6144
	ds_read_b128 v[224:227], v172 offset:7168
	global_load_lds_dwordx4 v[170:171], off
	v_lshl_add_u64 v[170:171], s[58:59], 0, v[136:137]
	s_mov_b32 m0, s79
	s_nop 0
	global_load_lds_dwordx4 v[170:171], off
	s_waitcnt vmcnt(8)
	s_waitcnt lgkmcnt(0)
	s_barrier
	s_setprio 1
	s_waitcnt lgkmcnt(0)
	v_mfma_f32_16x16x32_bf16 v[124:127], v[142:145], v[194:197], 0
	v_mfma_f32_16x16x32_bf16 v[108:111], v[150:153], v[194:197], 0
	v_mfma_f32_16x16x32_bf16 v[120:123], v[142:145], v[202:205], 0
	v_mfma_f32_16x16x32_bf16 v[96:99], v[150:153], v[202:205], 0
	v_mfma_f32_16x16x32_bf16 v[116:119], v[142:145], v[210:213], 0
	v_mfma_f32_16x16x32_bf16 v[88:91], v[150:153], v[210:213], 0
	v_mfma_f32_16x16x32_bf16 v[112:115], v[142:145], v[218:221], 0
	v_mfma_f32_16x16x32_bf16 v[84:87], v[150:153], v[218:221], 0
	v_mfma_f32_16x16x32_bf16 v[124:127], v[146:149], v[198:201], v[124:127]
	v_mfma_f32_16x16x32_bf16 v[108:111], v[154:157], v[198:201], v[108:111]
	v_mfma_f32_16x16x32_bf16 v[120:123], v[146:149], v[206:209], v[120:123]
	v_mfma_f32_16x16x32_bf16 v[96:99], v[154:157], v[206:209], v[96:99]
	v_mfma_f32_16x16x32_bf16 v[116:119], v[146:149], v[214:217], v[116:119]
	v_mfma_f32_16x16x32_bf16 v[88:91], v[154:157], v[214:217], v[88:91]
	v_mfma_f32_16x16x32_bf16 v[112:115], v[146:149], v[224:227], v[112:115]
	v_mfma_f32_16x16x32_bf16 v[84:87], v[154:157], v[224:227], v[84:87]
	s_setprio 0
	s_setprio 1
	v_mfma_f32_16x16x32_bf16 v[68:71], v[158:161], v[194:197], 0
	v_mfma_f32_16x16x32_bf16 v[40:43], v[166:169], v[194:197], 0
	v_mfma_f32_16x16x32_bf16 v[60:63], v[158:161], v[202:205], 0
	v_mfma_f32_16x16x32_bf16 v[32:35], v[166:169], v[202:205], 0
	v_mfma_f32_16x16x32_bf16 v[52:55], v[158:161], v[210:213], 0
	v_mfma_f32_16x16x32_bf16 v[24:27], v[166:169], v[210:213], 0
	v_mfma_f32_16x16x32_bf16 v[48:51], v[158:161], v[218:221], 0
	v_mfma_f32_16x16x32_bf16 v[16:19], v[166:169], v[218:221], 0
	v_mfma_f32_16x16x32_bf16 v[68:71], v[162:165], v[198:201], v[68:71]
	v_mfma_f32_16x16x32_bf16 v[40:43], v[190:193], v[198:201], v[40:43]
	v_mfma_f32_16x16x32_bf16 v[60:63], v[162:165], v[206:209], v[60:63]
	v_mfma_f32_16x16x32_bf16 v[32:35], v[190:193], v[206:209], v[32:35]
	v_mfma_f32_16x16x32_bf16 v[52:55], v[162:165], v[214:217], v[52:55]
	v_mfma_f32_16x16x32_bf16 v[24:27], v[190:193], v[214:217], v[24:27]
	v_mfma_f32_16x16x32_bf16 v[48:51], v[162:165], v[224:227], v[48:51]
	v_mfma_f32_16x16x32_bf16 v[16:19], v[190:193], v[224:227], v[16:19]
	s_setprio 0
	s_barrier
	s_mov_b32 m0, s12
	v_lshl_add_u64 v[170:171], s[62:63], 0, v[128:129]
	s_add_u32 s58, s62, 0xb0000
	ds_read_b128 v[194:197], v172 offset:16384
	ds_read_b128 v[198:201], v172 offset:17408
	ds_read_b128 v[202:205], v172 offset:18432
	ds_read_b128 v[206:209], v172 offset:19456
	ds_read_b128 v[210:213], v172 offset:20480
	ds_read_b128 v[214:217], v172 offset:21504
	ds_read_b128 v[218:221], v172 offset:22528
	ds_read_b128 v[224:227], v172 offset:23552
	global_load_lds_dwordx4 v[170:171], off
	v_lshl_add_u64 v[228:229], s[62:63], 0, v[130:131]
	s_mov_b32 m0, s13
	s_addc_u32 s59, s63, 0
	global_load_lds_dwordx4 v[228:229], off
	v_lshl_add_u64 v[230:231], s[58:59], 0, v[128:129]
	s_mov_b32 m0, s14
	v_lshl_add_u64 v[232:233], s[64:65], 0, v[130:131]
	global_load_lds_dwordx4 v[230:231], off
	v_lshl_add_u64 v[230:231], s[58:59], 0, v[130:131]
	s_mov_b32 m0, s15
	s_nop 0
	global_load_lds_dwordx4 v[230:231], off
	v_lshl_add_u64 v[230:231], s[64:65], 0, v[128:129]
	s_mov_b32 m0, s5
	s_nop 0
	global_load_lds_dwordx4 v[230:231], off
	s_mov_b32 m0, s39
	s_nop 0
	global_load_lds_dwordx4 v[232:233], off
	s_waitcnt vmcnt(8)
	s_waitcnt lgkmcnt(0)
	s_barrier
	s_setprio 1
	s_waitcnt lgkmcnt(0)
	v_mfma_f32_16x16x32_bf16 v[104:107], v[142:145], v[194:197], 0
	v_mfma_f32_16x16x32_bf16 v[76:79], v[150:153], v[194:197], 0
	v_mfma_f32_16x16x32_bf16 v[100:103], v[142:145], v[202:205], 0
	v_mfma_f32_16x16x32_bf16 v[72:75], v[150:153], v[202:205], 0
	v_mfma_f32_16x16x32_bf16 v[92:95], v[142:145], v[210:213], 0
	v_mfma_f32_16x16x32_bf16 v[64:67], v[150:153], v[210:213], 0
	v_mfma_f32_16x16x32_bf16 v[80:83], v[142:145], v[218:221], 0
	v_mfma_f32_16x16x32_bf16 v[56:59], v[150:153], v[218:221], 0
	v_mfma_f32_16x16x32_bf16 v[104:107], v[146:149], v[198:201], v[104:107]
	v_mfma_f32_16x16x32_bf16 v[76:79], v[154:157], v[198:201], v[76:79]
	v_mfma_f32_16x16x32_bf16 v[100:103], v[146:149], v[206:209], v[100:103]
	v_mfma_f32_16x16x32_bf16 v[72:75], v[154:157], v[206:209], v[72:75]
	v_mfma_f32_16x16x32_bf16 v[92:95], v[146:149], v[214:217], v[92:95]
	v_mfma_f32_16x16x32_bf16 v[64:67], v[154:157], v[214:217], v[64:67]
	v_mfma_f32_16x16x32_bf16 v[80:83], v[146:149], v[224:227], v[80:83]
	v_mfma_f32_16x16x32_bf16 v[56:59], v[154:157], v[224:227], v[56:59]
	s_setprio 0
	s_setprio 1
	v_mfma_f32_16x16x32_bf16 v[44:47], v[158:161], v[194:197], 0
	v_mfma_f32_16x16x32_bf16 v[12:15], v[166:169], v[194:197], 0
	v_mfma_f32_16x16x32_bf16 v[36:39], v[158:161], v[202:205], 0
	v_mfma_f32_16x16x32_bf16 v[8:11], v[166:169], v[202:205], 0
	v_mfma_f32_16x16x32_bf16 v[28:31], v[158:161], v[210:213], 0
	v_mfma_f32_16x16x32_bf16 v[4:7], v[166:169], v[210:213], 0
	v_mfma_f32_16x16x32_bf16 v[20:23], v[158:161], v[218:221], 0
	v_mfma_f32_16x16x32_bf16 v[0:3], v[166:169], v[218:221], 0
	v_mfma_f32_16x16x32_bf16 v[44:47], v[162:165], v[198:201], v[44:47]
	v_mfma_f32_16x16x32_bf16 v[12:15], v[190:193], v[198:201], v[12:15]
	v_mfma_f32_16x16x32_bf16 v[36:39], v[162:165], v[206:209], v[36:39]
	v_mfma_f32_16x16x32_bf16 v[8:11], v[190:193], v[206:209], v[8:11]
	v_mfma_f32_16x16x32_bf16 v[28:31], v[162:165], v[214:217], v[28:31]
	v_mfma_f32_16x16x32_bf16 v[4:7], v[190:193], v[214:217], v[4:7]
	v_mfma_f32_16x16x32_bf16 v[20:23], v[162:165], v[224:227], v[20:23]
	v_mfma_f32_16x16x32_bf16 v[0:3], v[190:193], v[224:227], v[0:3]
	s_setprio 0
	s_barrier
; #define PG8_STAGE(bufoff, gbase, voff) do { _Pragma("unroll") for (int _i = 0; _i < 2; ++_i) \
;         __builtin_amdgcn_global_load_lds((const unsigned*)((const char*)(gbase) + (voff)[_i]), (PG8_LAS unsigned*)(lds + (bufoff) + ldsw + _i * 8192), 16, 0, 0); } while (0)
; #define PG8_LDA(dst, b, h) do { _Pragma("unroll") for (int m = 0; m < 4; ++m) _Pragma("unroll") for (int k = 0; k < 2; ++k) dst[m][k] = *(const PG8_LAS bf16x8*)(lds + PG8_SA(b, h) + aoff + m * 2048 + k * 1024); } while (0)
; #define PG8_LDB(dst, b, h) do { _Pragma("unroll") for (int n = 0; n < 2; ++n) _Pragma("unroll") for (int k = 0; k < 2; ++k) dst[n][k] = *(const PG8_LAS bf16x8*)(lds + PG8_SB(b, h) + boff + n * 2048 + k * 1024); } while (0)
; #define PG8_MMA(ai, bj, At, Bt) do { __builtin_amdgcn_s_setprio(1); _Pragma("unroll") for (int m = 0; m < 4; ++m) _Pragma("unroll") for (int n = 0; n < 2; ++n) _Pragma("unroll") for (int k = 0; k < 2; ++k) \
;         acc[ai][bj][m][n] = __builtin_amdgcn_mfma_f32_16x16x32_bf16(Bt[n][k], At[m][k], acc[ai][bj][m][n], 0, 0, 0); __builtin_amdgcn_s_setprio(0); } while (0)
; #define PG8_WAIT_V(n) asm volatile("s_waitcnt vmcnt(" #n ")" ::: "memory")
; #define PG8_WAIT_L(n) asm volatile("s_waitcnt lgkmcnt(" #n ")" ::: "memory")
; #define PG8_BAR __builtin_amdgcn_s_barrier()
; #define PG8_SCHED __builtin_amdgcn_sched_barrier(0)
; template <class Epi, class Sched, bool ALIGN_EPI = false, bool SP2 = false>
; __device__ __forceinline__ void gemm_phase(PG8_LAS unsigned char* lds, const Gemm g, const Sched& S, const Epi& E) {
;     ...
;             PG8_LDB(B0, 1, 0); PG8_LDB(B1, 1, 1); PG8_SCHED; PG8_LDA(At, 1, 0); PG8_STAGE(PG8_SA(0, 1), a2 + hstep, voffA);
;             PG8_WAIT_V(8); PG8_WAIT_L(0); PG8_BAR; PG8_MMA(0, 0, At, B0); PG8_MMA(0, 1, At, B1); PG8_BAR; PG8_SCHED;
;             PG8_LDA(At, 1, 1); PG8_STAGE(PG8_SB(1, 0), b3, voffB); PG8_STAGE(PG8_SB(1, 1), b3 + hstep, voffB); PG8_STAGE(PG8_SA(1, 0), a3, voffA);
;             PG8_WAIT_V(8); PG8_WAIT_L(0); PG8_BAR; PG8_MMA(1, 0, At, B0); PG8_MMA(1, 1, At, B1); PG8_BAR; PG8_SCHED;
	ds_read_b128 v[142:145], v182
	ds_read_b128 v[146:149], v183
	ds_read_b128 v[150:153], v184
	ds_read_b128 v[154:157], v185
	ds_read_b128 v[158:161], v186
	ds_read_b128 v[162:165], v187
	ds_read_b128 v[166:169], v188
	ds_read_b128 v[190:193], v189
	s_add_u32 s58, s64, 0xb0000
	s_addc_u32 s59, s65, 0
	s_mov_b32 m0, s43
	v_lshl_add_u64 v[234:235], s[58:59], 0, v[128:129]
	ds_read_b128 v[194:197], v172 offset:32768
	ds_read_b128 v[198:201], v172 offset:33792
	ds_read_b128 v[202:205], v172 offset:34816
	ds_read_b128 v[206:209], v172 offset:35840
	ds_read_b128 v[210:213], v172 offset:36864
	ds_read_b128 v[214:217], v172 offset:37888
	ds_read_b128 v[218:221], v172 offset:38912
	ds_read_b128 v[224:227], v172 offset:39936
	global_load_lds_dwordx4 v[234:235], off
	v_lshl_add_u64 v[234:235], s[58:59], 0, v[130:131]
	s_mov_b32 m0, s66
	s_nop 0
	global_load_lds_dwordx4 v[234:235], off
	s_waitcnt vmcnt(8)
	s_waitcnt lgkmcnt(0)
	s_barrier
	s_setprio 1
	s_waitcnt lgkmcnt(0)
	v_mfma_f32_16x16x32_bf16 v[124:127], v[142:145], v[194:197], v[124:127]
	v_mfma_f32_16x16x32_bf16 v[108:111], v[150:153], v[194:197], v[108:111]
	v_mfma_f32_16x16x32_bf16 v[120:123], v[142:145], v[202:205], v[120:123]
	v_mfma_f32_16x16x32_bf16 v[96:99], v[150:153], v[202:205], v[96:99]
	v_mfma_f32_16x16x32_bf16 v[116:119], v[142:145], v[210:213], v[116:119]
	v_mfma_f32_16x16x32_bf16 v[88:91], v[150:153], v[210:213], v[88:91]
	v_mfma_f32_16x16x32_bf16 v[112:115], v[142:145], v[218:221], v[112:115]
	v_mfma_f32_16x16x32_bf16 v[84:87], v[150:153], v[218:221], v[84:87]
	v_mfma_f32_16x16x32_bf16 v[124:127], v[146:149], v[198:201], v[124:127]
	v_mfma_f32_16x16x32_bf16 v[108:111], v[154:157], v[198:201], v[108:111]
	v_mfma_f32_16x16x32_bf16 v[120:123], v[146:149], v[206:209], v[120:123]
	v_mfma_f32_16x16x32_bf16 v[96:99], v[154:157], v[206:209], v[96:99]
	v_mfma_f32_16x16x32_bf16 v[116:119], v[146:149], v[214:217], v[116:119]
	v_mfma_f32_16x16x32_bf16 v[88:91], v[154:157], v[214:217], v[88:91]
	v_mfma_f32_16x16x32_bf16 v[112:115], v[146:149], v[224:227], v[112:115]
	v_mfma_f32_16x16x32_bf16 v[84:87], v[154:157], v[224:227], v[84:87]
	s_setprio 0
	s_setprio 1
	v_mfma_f32_16x16x32_bf16 v[68:71], v[158:161], v[194:197], v[68:71]
	v_mfma_f32_16x16x32_bf16 v[40:43], v[166:169], v[194:197], v[40:43]
	v_mfma_f32_16x16x32_bf16 v[60:63], v[158:161], v[202:205], v[60:63]
	v_mfma_f32_16x16x32_bf16 v[32:35], v[166:169], v[202:205], v[32:35]
	v_mfma_f32_16x16x32_bf16 v[52:55], v[158:161], v[210:213], v[52:55]
	v_mfma_f32_16x16x32_bf16 v[24:27], v[166:169], v[210:213], v[24:27]
	v_mfma_f32_16x16x32_bf16 v[48:51], v[158:161], v[218:221], v[48:51]
	v_mfma_f32_16x16x32_bf16 v[16:19], v[166:169], v[218:221], v[16:19]
	v_mfma_f32_16x16x32_bf16 v[68:71], v[162:165], v[198:201], v[68:71]
	v_mfma_f32_16x16x32_bf16 v[40:43], v[190:193], v[198:201], v[40:43]
	v_mfma_f32_16x16x32_bf16 v[60:63], v[162:165], v[206:209], v[60:63]
	v_mfma_f32_16x16x32_bf16 v[32:35], v[190:193], v[206:209], v[32:35]
	v_mfma_f32_16x16x32_bf16 v[52:55], v[162:165], v[214:217], v[52:55]
	v_mfma_f32_16x16x32_bf16 v[24:27], v[190:193], v[214:217], v[24:27]
	v_mfma_f32_16x16x32_bf16 v[48:51], v[162:165], v[224:227], v[48:51]
	v_mfma_f32_16x16x32_bf16 v[16:19], v[190:193], v[224:227], v[16:19]
	s_setprio 0
	s_barrier
	s_mov_b32 m0, s70
	v_lshl_add_u64 v[170:171], v[170:171], 0, s[40:41]
	s_add_u32 s58, s62, 0xb0080
	ds_read_b128 v[194:197], v172 offset:49152
	ds_read_b128 v[198:201], v172 offset:50176
	ds_read_b128 v[202:205], v172 offset:51200
	ds_read_b128 v[206:209], v172 offset:52224
	ds_read_b128 v[210:213], v172 offset:53248
	ds_read_b128 v[214:217], v172 offset:54272
	ds_read_b128 v[218:221], v172 offset:55296
	ds_read_b128 v[224:227], v172 offset:56320
	global_load_lds_dwordx4 v[170:171], off
	v_lshl_add_u64 v[170:171], v[228:229], 0, s[40:41]
	s_mov_b32 m0, s71
	s_addc_u32 s59, s63, 0
	global_load_lds_dwordx4 v[170:171], off
	v_lshl_add_u64 v[170:171], s[58:59], 0, v[128:129]
	s_mov_b32 m0, s74
	s_nop 0
	global_load_lds_dwordx4 v[170:171], off
	v_lshl_add_u64 v[170:171], s[58:59], 0, v[130:131]
	s_mov_b32 m0, s75
	s_nop 0
	global_load_lds_dwordx4 v[170:171], off
	v_lshl_add_u64 v[170:171], v[230:231], 0, s[40:41]
	s_mov_b32 m0, s72
	s_nop 0
	global_load_lds_dwordx4 v[170:171], off
	v_lshl_add_u64 v[170:171], v[232:233], 0, s[40:41]
	s_mov_b32 m0, s73
	s_nop 0
	global_load_lds_dwordx4 v[170:171], off
	s_waitcnt vmcnt(8)
	s_waitcnt lgkmcnt(0)
	s_barrier
	s_setprio 1
	s_waitcnt lgkmcnt(0)
	v_mfma_f32_16x16x32_bf16 v[104:107], v[142:145], v[194:197], v[104:107]
	v_mfma_f32_16x16x32_bf16 v[76:79], v[150:153], v[194:197], v[76:79]
	v_mfma_f32_16x16x32_bf16 v[100:103], v[142:145], v[202:205], v[100:103]
	v_mfma_f32_16x16x32_bf16 v[72:75], v[150:153], v[202:205], v[72:75]
	v_mfma_f32_16x16x32_bf16 v[92:95], v[142:145], v[210:213], v[92:95]
	v_mfma_f32_16x16x32_bf16 v[64:67], v[150:153], v[210:213], v[64:67]
	v_mfma_f32_16x16x32_bf16 v[80:83], v[142:145], v[218:221], v[80:83]
	v_mfma_f32_16x16x32_bf16 v[56:59], v[150:153], v[218:221], v[56:59]
	v_mfma_f32_16x16x32_bf16 v[104:107], v[146:149], v[198:201], v[104:107]
	v_mfma_f32_16x16x32_bf16 v[76:79], v[154:157], v[198:201], v[76:79]
	v_mfma_f32_16x16x32_bf16 v[100:103], v[146:149], v[206:209], v[100:103]
	v_mfma_f32_16x16x32_bf16 v[72:75], v[154:157], v[206:209], v[72:75]
	v_mfma_f32_16x16x32_bf16 v[92:95], v[146:149], v[214:217], v[92:95]
	v_mfma_f32_16x16x32_bf16 v[64:67], v[154:157], v[214:217], v[64:67]
	v_mfma_f32_16x16x32_bf16 v[80:83], v[146:149], v[224:227], v[80:83]
	v_mfma_f32_16x16x32_bf16 v[56:59], v[154:157], v[224:227], v[56:59]
	s_setprio 0
	s_setprio 1
	v_mfma_f32_16x16x32_bf16 v[44:47], v[158:161], v[194:197], v[44:47]
	v_mfma_f32_16x16x32_bf16 v[12:15], v[166:169], v[194:197], v[12:15]
	v_mfma_f32_16x16x32_bf16 v[36:39], v[158:161], v[202:205], v[36:39]
	v_mfma_f32_16x16x32_bf16 v[8:11], v[166:169], v[202:205], v[8:11]
	v_mfma_f32_16x16x32_bf16 v[28:31], v[158:161], v[210:213], v[28:31]
	v_mfma_f32_16x16x32_bf16 v[4:7], v[166:169], v[210:213], v[4:7]
	v_mfma_f32_16x16x32_bf16 v[20:23], v[158:161], v[218:221], v[20:23]
	v_mfma_f32_16x16x32_bf16 v[0:3], v[166:169], v[218:221], v[0:3]
	v_mfma_f32_16x16x32_bf16 v[44:47], v[162:165], v[198:201], v[44:47]
	v_mfma_f32_16x16x32_bf16 v[12:15], v[190:193], v[198:201], v[12:15]
	v_mfma_f32_16x16x32_bf16 v[36:39], v[162:165], v[206:209], v[36:39]
	v_mfma_f32_16x16x32_bf16 v[8:11], v[190:193], v[206:209], v[8:11]
	v_mfma_f32_16x16x32_bf16 v[28:31], v[162:165], v[214:217], v[28:31]
	v_mfma_f32_16x16x32_bf16 v[4:7], v[190:193], v[214:217], v[4:7]
	v_mfma_f32_16x16x32_bf16 v[20:23], v[162:165], v[224:227], v[20:23]
	v_mfma_f32_16x16x32_bf16 v[0:3], v[190:193], v[224:227], v[0:3]
	s_setprio 0
	s_barrier
	s_add_i32 s89, s89, 2
	s_add_u32 s57, s57, 0x100
	s_addc_u32 s88, s88, 0
	s_mov_b64 s[58:59], s[60:61]

;     __host__ __device__ bool next(int i, Unit& u) const { const int L = i * G + c; if (L >= 16 * nkc) return false; u.kc = L % nkc; const int t = L / nkc; u.pn = t & 3; u.pm = 33 * (t >> 2); return true; }
; #define PG8_STAGE(bufoff, gbase, voff) do { _Pragma("unroll") for (int _i = 0; _i < 2; ++_i) \
;         __builtin_amdgcn_global_load_lds((const unsigned*)((const char*)(gbase) + (voff)[_i]), (PG8_LAS unsigned*)(lds + (bufoff) + ldsw + _i * 8192), 16, 0, 0); } while (0)
; #define PG8_LDA(dst, b, h) do { _Pragma("unroll") for (int m = 0; m < 4; ++m) _Pragma("unroll") for (int k = 0; k < 2; ++k) dst[m][k] = *(const PG8_LAS bf16x8*)(lds + PG8_SA(b, h) + aoff + m * 2048 + k * 1024); } while (0)
; #define PG8_LDB(dst, b, h) do { _Pragma("unroll") for (int n = 0; n < 2; ++n) _Pragma("unroll") for (int k = 0; k < 2; ++k) dst[n][k] = *(const PG8_LAS bf16x8*)(lds + PG8_SB(b, h) + boff + n * 2048 + k * 1024); } while (0)
; #define PG8_BAR __builtin_amdgcn_s_barrier()
; template <class Epi, class Sched, bool ALIGN_EPI = false, bool SP2 = false>
; __device__ __forceinline__ void gemm_phase(PG8_LAS unsigned char* lds, const Gemm g, const Sched& S, const Epi& E) {
;     ...
;         const bool has_next = S.next(ui + 1, nxt);
;         const char* nA = has_next ? (const char*)g.A + (size_t)nxt.pm * tstep + (size_t)nxt.kc * cstep : cA; const char* nB = has_next ? (const char*)g.Bt + (size_t)nxt.pn * tstep + (size_t)nxt.kc * cstep : cB;
;         for (int t = 0; t < nt; t += 2) {
;             const bool last = (t == nt - 2);
;             const char* a1 = cA + (size_t)(t + 1) * kstep;
;             const char* a2 = last ? nA : cA + (size_t)(t + 2) * kstep; const char* b2 = last ? nB : cB + (size_t)(t + 2) * kstep;
;             const char* a3 = a2 + kstep; const char* b3 = b2 + kstep;
;             if (last && has_next) S.a_ready(nxt);
;             if constexpr (SP2) {
;             PG8_LDB(B0, 0, 0); PG8_LDB(B1, 0, 1); PG8_SCHED; PG8_LDA(At, 0, 0); PG8_STAGE(PG8_SA(1, 1), a1 + hstep, voffA);
;             PG8_WAIT_V(8); PG8_WAIT_L(0); PG8_BAR; PG8_MMA(0, 0, At, B0); PG8_MMA(0, 1, At, B1); PG8_BAR; PG8_SCHED;
;             PG8_LDA(At, 0, 1); PG8_STAGE(PG8_SB(0, 0), b2, voffB); PG8_STAGE(PG8_SB(0, 1), b2 + hstep, voffB); PG8_STAGE(PG8_SA(0, 0), a2, voffA);
;             PG8_WAIT_V(8); PG8_WAIT_L(0); PG8_BAR; PG8_MMA(1, 0, At, B0); PG8_MMA(1, 1, At, B1); PG8_BAR; PG8_SCHED;
.LBB0_895:
	s_add_u32 s33, s64, 0x100
	s_addc_u32 s55, s65, 0
	s_mov_b32 s57, 0
	ds_read_b128 v[156:159], v140
	ds_read_b128 v[160:163], v141
	ds_read_b128 v[164:167], v142
	ds_read_b128 v[168:171], v143
	ds_read_b128 v[172:175], v144
	ds_read_b128 v[176:179], v145
	ds_read_b128 v[180:183], v146
	ds_read_b128 v[184:187], v147
	s_add_i32 s86, s57, 2
	s_add_u32 s64, s62, 0x100
	s_addc_u32 s65, s63, 0
	s_cmp_eq_u32 s78, s57
	s_cselect_b32 s69, s59, s65
	s_cselect_b32 s68, s58, s64
	s_cselect_b32 s67, s61, s55
	s_cselect_b32 s66, s60, s33
	s_mov_b32 m0, s79
	v_lshl_add_u64 v[220:221], s[62:63], 0, v[134:135]
	ds_read_b128 v[188:191], v138
	ds_read_b128 v[192:195], v138 offset:1024
	ds_read_b128 v[196:199], v138 offset:2048
	ds_read_b128 v[200:203], v138 offset:3072
	ds_read_b128 v[204:207], v138 offset:4096
	ds_read_b128 v[208:211], v138 offset:5120
	ds_read_b128 v[212:215], v138 offset:6144
	ds_read_b128 v[216:219], v138 offset:7168
	global_load_lds_dwordx4 v[220:221], off
	v_lshl_add_u64 v[220:221], s[62:63], 0, v[136:137]
	s_mov_b32 m0, s80
	s_nop 0
	global_load_lds_dwordx4 v[220:221], off
	s_waitcnt vmcnt(8)
	s_waitcnt lgkmcnt(0)
	s_barrier
	s_setprio 1
	s_waitcnt lgkmcnt(0)
	v_mfma_f32_16x16x32_bf16 v[124:127], v[156:159], v[188:191], 0
	v_mfma_f32_16x16x32_bf16 v[120:123], v[164:167], v[188:191], 0
	v_mfma_f32_16x16x32_bf16 v[108:111], v[156:159], v[196:199], 0
	v_mfma_f32_16x16x32_bf16 v[104:107], v[164:167], v[196:199], 0
	v_mfma_f32_16x16x32_bf16 v[92:95], v[156:159], v[204:207], 0
	v_mfma_f32_16x16x32_bf16 v[88:91], v[164:167], v[204:207], 0
	v_mfma_f32_16x16x32_bf16 v[76:79], v[156:159], v[212:215], 0
	v_mfma_f32_16x16x32_bf16 v[72:75], v[164:167], v[212:215], 0
	v_mfma_f32_16x16x32_bf16 v[124:127], v[160:163], v[192:195], v[124:127]
	v_mfma_f32_16x16x32_bf16 v[120:123], v[168:171], v[192:195], v[120:123]
	v_mfma_f32_16x16x32_bf16 v[108:111], v[160:163], v[200:203], v[108:111]
	v_mfma_f32_16x16x32_bf16 v[104:107], v[168:171], v[200:203], v[104:107]
	v_mfma_f32_16x16x32_bf16 v[92:95], v[160:163], v[208:211], v[92:95]
	v_mfma_f32_16x16x32_bf16 v[88:91], v[168:171], v[208:211], v[88:91]
	v_mfma_f32_16x16x32_bf16 v[76:79], v[160:163], v[216:219], v[76:79]
	v_mfma_f32_16x16x32_bf16 v[72:75], v[168:171], v[216:219], v[72:75]
	s_setprio 0
	s_setprio 1
	v_mfma_f32_16x16x32_bf16 v[116:119], v[172:175], v[188:191], 0
	v_mfma_f32_16x16x32_bf16 v[112:115], v[180:183], v[188:191], 0
	v_mfma_f32_16x16x32_bf16 v[100:103], v[172:175], v[196:199], 0
	v_mfma_f32_16x16x32_bf16 v[96:99], v[180:183], v[196:199], 0
	v_mfma_f32_16x16x32_bf16 v[84:87], v[172:175], v[204:207], 0
	v_mfma_f32_16x16x32_bf16 v[80:83], v[180:183], v[204:207], 0
	v_mfma_f32_16x16x32_bf16 v[68:71], v[172:175], v[212:215], 0
	v_mfma_f32_16x16x32_bf16 v[64:67], v[180:183], v[212:215], 0
	v_mfma_f32_16x16x32_bf16 v[116:119], v[176:179], v[192:195], v[116:119]
	v_mfma_f32_16x16x32_bf16 v[112:115], v[184:187], v[192:195], v[112:115]
	v_mfma_f32_16x16x32_bf16 v[100:103], v[176:179], v[200:203], v[100:103]
	v_mfma_f32_16x16x32_bf16 v[96:99], v[184:187], v[200:203], v[96:99]
	v_mfma_f32_16x16x32_bf16 v[84:87], v[176:179], v[208:211], v[84:87]
	v_mfma_f32_16x16x32_bf16 v[80:83], v[184:187], v[208:211], v[80:83]
	v_mfma_f32_16x16x32_bf16 v[68:71], v[176:179], v[216:219], v[68:71]
	v_mfma_f32_16x16x32_bf16 v[64:67], v[184:187], v[216:219], v[64:67]
	s_setprio 0
	s_barrier
	s_mov_b32 m0, s12
	v_lshl_add_u64 v[220:221], s[66:67], 0, v[130:131]
	s_add_u32 s62, s66, 0xb0000
	ds_read_b128 v[188:191], v138 offset:16384
	ds_read_b128 v[192:195], v138 offset:17408
	ds_read_b128 v[196:199], v138 offset:18432
	ds_read_b128 v[200:203], v138 offset:19456
	ds_read_b128 v[204:207], v138 offset:20480
	ds_read_b128 v[208:211], v138 offset:21504
	ds_read_b128 v[212:215], v138 offset:22528
	ds_read_b128 v[216:219], v138 offset:23552
	global_load_lds_dwordx4 v[220:221], off
	v_lshl_add_u64 v[224:225], s[66:67], 0, v[128:129]
	s_mov_b32 m0, s13
	s_addc_u32 s63, s67, 0
	global_load_lds_dwordx4 v[224:225], off
	v_lshl_add_u64 v[226:227], s[62:63], 0, v[130:131]
	s_mov_b32 m0, s14
	v_lshl_add_u64 v[228:229], s[68:69], 0, v[128:129]
	global_load_lds_dwordx4 v[226:227], off
	v_lshl_add_u64 v[226:227], s[62:63], 0, v[128:129]
	s_mov_b32 m0, s15
	s_nop 0
	global_load_lds_dwordx4 v[226:227], off
	v_lshl_add_u64 v[226:227], s[68:69], 0, v[130:131]
	s_mov_b32 m0, s5
	s_nop 0
	global_load_lds_dwordx4 v[226:227], off
	s_mov_b32 m0, s39
	s_nop 0
	global_load_lds_dwordx4 v[228:229], off
	s_waitcnt vmcnt(8)
	s_waitcnt lgkmcnt(0)
	s_barrier
	s_setprio 1
	s_waitcnt lgkmcnt(0)
	v_mfma_f32_16x16x32_bf16 v[60:63], v[156:159], v[188:191], 0
	v_mfma_f32_16x16x32_bf16 v[56:59], v[164:167], v[188:191], 0
	v_mfma_f32_16x16x32_bf16 v[44:47], v[156:159], v[196:199], 0
	v_mfma_f32_16x16x32_bf16 v[40:43], v[164:167], v[196:199], 0
	v_mfma_f32_16x16x32_bf16 v[28:31], v[156:159], v[204:207], 0
	v_mfma_f32_16x16x32_bf16 v[24:27], v[164:167], v[204:207], 0
	v_mfma_f32_16x16x32_bf16 v[12:15], v[156:159], v[212:215], 0
	v_mfma_f32_16x16x32_bf16 v[8:11], v[164:167], v[212:215], 0
	v_mfma_f32_16x16x32_bf16 v[60:63], v[160:163], v[192:195], v[60:63]
	v_mfma_f32_16x16x32_bf16 v[56:59], v[168:171], v[192:195], v[56:59]
	v_mfma_f32_16x16x32_bf16 v[44:47], v[160:163], v[200:203], v[44:47]
	v_mfma_f32_16x16x32_bf16 v[40:43], v[168:171], v[200:203], v[40:43]
	v_mfma_f32_16x16x32_bf16 v[28:31], v[160:163], v[208:211], v[28:31]
	v_mfma_f32_16x16x32_bf16 v[24:27], v[168:171], v[208:211], v[24:27]
	v_mfma_f32_16x16x32_bf16 v[12:15], v[160:163], v[216:219], v[12:15]
	v_mfma_f32_16x16x32_bf16 v[8:11], v[168:171], v[216:219], v[8:11]
	s_setprio 0
	s_setprio 1
	v_mfma_f32_16x16x32_bf16 v[52:55], v[172:175], v[188:191], 0
	v_mfma_f32_16x16x32_bf16 v[48:51], v[180:183], v[188:191], 0
	v_mfma_f32_16x16x32_bf16 v[36:39], v[172:175], v[196:199], 0
	v_mfma_f32_16x16x32_bf16 v[32:35], v[180:183], v[196:199], 0
	v_mfma_f32_16x16x32_bf16 v[20:23], v[172:175], v[204:207], 0
	v_mfma_f32_16x16x32_bf16 v[16:19], v[180:183], v[204:207], 0
	v_mfma_f32_16x16x32_bf16 v[4:7], v[172:175], v[212:215], 0
	v_mfma_f32_16x16x32_bf16 v[0:3], v[180:183], v[212:215], 0
	v_mfma_f32_16x16x32_bf16 v[52:55], v[176:179], v[192:195], v[52:55]
	v_mfma_f32_16x16x32_bf16 v[48:51], v[184:187], v[192:195], v[48:51]
	v_mfma_f32_16x16x32_bf16 v[36:39], v[176:179], v[200:203], v[36:39]
	v_mfma_f32_16x16x32_bf16 v[32:35], v[184:187], v[200:203], v[32:35]
	v_mfma_f32_16x16x32_bf16 v[20:23], v[176:179], v[208:211], v[20:23]
	v_mfma_f32_16x16x32_bf16 v[16:19], v[184:187], v[208:211], v[16:19]
	v_mfma_f32_16x16x32_bf16 v[4:7], v[176:179], v[216:219], v[4:7]
	v_mfma_f32_16x16x32_bf16 v[0:3], v[184:187], v[216:219], v[0:3]
	s_setprio 0
	s_barrier
; #define PG8_STAGE(bufoff, gbase, voff) do { _Pragma("unroll") for (int _i = 0; _i < 2; ++_i) \
;         __builtin_amdgcn_global_load_lds((const unsigned*)((const char*)(gbase) + (voff)[_i]), (PG8_LAS unsigned*)(lds + (bufoff) + ldsw + _i * 8192), 16, 0, 0); } while (0)
; #define PG8_LDA(dst, b, h) do { _Pragma("unroll") for (int m = 0; m < 4; ++m) _Pragma("unroll") for (int k = 0; k < 2; ++k) dst[m][k] = *(const PG8_LAS bf16x8*)(lds + PG8_SA(b, h) + aoff + m * 2048 + k * 1024); } while (0)
; #define PG8_LDB(dst, b, h) do { _Pragma("unroll") for (int n = 0; n < 2; ++n) _Pragma("unroll") for (int k = 0; k < 2; ++k) dst[n][k] = *(const PG8_LAS bf16x8*)(lds + PG8_SB(b, h) + boff + n * 2048 + k * 1024); } while (0)
; #define PG8_MMA(ai, bj, At, Bt) do { __builtin_amdgcn_s_setprio(1); _Pragma("unroll") for (int m = 0; m < 4; ++m) _Pragma("unroll") for (int n = 0; n < 2; ++n) _Pragma("unroll") for (int k = 0; k < 2; ++k) \
;         acc[ai][bj][m][n] = __builtin_amdgcn_mfma_f32_16x16x32_bf16(Bt[n][k], At[m][k], acc[ai][bj][m][n], 0, 0, 0); __builtin_amdgcn_s_setprio(0); } while (0)
; #define PG8_WAIT_V(n) asm volatile("s_waitcnt vmcnt(" #n ")" ::: "memory")
; #define PG8_WAIT_L(n) asm volatile("s_waitcnt lgkmcnt(" #n ")" ::: "memory")
; #define PG8_BAR __builtin_amdgcn_s_barrier()
; #define PG8_SCHED __builtin_amdgcn_sched_barrier(0)
; template <class Epi, class Sched, bool ALIGN_EPI = false, bool SP2 = false>
; __device__ __forceinline__ void gemm_phase(PG8_LAS unsigned char* lds, const Gemm g, const Sched& S, const Epi& E) {
;     ...
;             PG8_LDB(B0, 1, 0); PG8_LDB(B1, 1, 1); PG8_SCHED; PG8_LDA(At, 1, 0); PG8_STAGE(PG8_SA(0, 1), a2 + hstep, voffA);
;             PG8_WAIT_V(8); PG8_WAIT_L(0); PG8_BAR; PG8_MMA(0, 0, At, B0); PG8_MMA(0, 1, At, B1); PG8_BAR; PG8_SCHED;
;             PG8_LDA(At, 1, 1); PG8_STAGE(PG8_SB(1, 0), b3, voffB); PG8_STAGE(PG8_SB(1, 1), b3 + hstep, voffB); PG8_STAGE(PG8_SA(1, 0), a3, voffA);
;             PG8_WAIT_V(8); PG8_WAIT_L(0); PG8_BAR; PG8_MMA(1, 0, At, B0); PG8_MMA(1, 1, At, B1); PG8_BAR; PG8_SCHED;
	ds_read_b128 v[156:159], v148
	ds_read_b128 v[160:163], v149
	ds_read_b128 v[164:167], v150
	ds_read_b128 v[168:171], v151
	ds_read_b128 v[172:175], v152
	ds_read_b128 v[176:179], v153
	ds_read_b128 v[180:183], v154
	ds_read_b128 v[184:187], v155
	s_add_u32 s62, s68, 0xb0000
	s_addc_u32 s63, s69, 0
	s_mov_b32 m0, s43
	v_lshl_add_u64 v[230:231], s[62:63], 0, v[130:131]
	ds_read_b128 v[188:191], v138 offset:32768
	ds_read_b128 v[192:195], v138 offset:33792
	ds_read_b128 v[196:199], v138 offset:34816
	ds_read_b128 v[200:203], v138 offset:35840
	ds_read_b128 v[204:207], v138 offset:36864
	ds_read_b128 v[208:211], v138 offset:37888
	ds_read_b128 v[212:215], v138 offset:38912
	ds_read_b128 v[216:219], v138 offset:39936
	global_load_lds_dwordx4 v[230:231], off
	v_lshl_add_u64 v[230:231], s[62:63], 0, v[128:129]
	s_mov_b32 m0, s70
	s_nop 0
	global_load_lds_dwordx4 v[230:231], off
	s_waitcnt vmcnt(8)
	s_waitcnt lgkmcnt(0)
	s_barrier
	s_setprio 1
	s_waitcnt lgkmcnt(0)
	v_mfma_f32_16x16x32_bf16 v[124:127], v[156:159], v[188:191], v[124:127]
	v_mfma_f32_16x16x32_bf16 v[120:123], v[164:167], v[188:191], v[120:123]
	v_mfma_f32_16x16x32_bf16 v[108:111], v[156:159], v[196:199], v[108:111]
	v_mfma_f32_16x16x32_bf16 v[104:107], v[164:167], v[196:199], v[104:107]
	v_mfma_f32_16x16x32_bf16 v[92:95], v[156:159], v[204:207], v[92:95]
	v_mfma_f32_16x16x32_bf16 v[88:91], v[164:167], v[204:207], v[88:91]
	v_mfma_f32_16x16x32_bf16 v[76:79], v[156:159], v[212:215], v[76:79]
	v_mfma_f32_16x16x32_bf16 v[72:75], v[164:167], v[212:215], v[72:75]
	v_mfma_f32_16x16x32_bf16 v[124:127], v[160:163], v[192:195], v[124:127]
	v_mfma_f32_16x16x32_bf16 v[120:123], v[168:171], v[192:195], v[120:123]
	v_mfma_f32_16x16x32_bf16 v[108:111], v[160:163], v[200:203], v[108:111]
	v_mfma_f32_16x16x32_bf16 v[104:107], v[168:171], v[200:203], v[104:107]
	v_mfma_f32_16x16x32_bf16 v[92:95], v[160:163], v[208:211], v[92:95]
	v_mfma_f32_16x16x32_bf16 v[88:91], v[168:171], v[208:211], v[88:91]
	v_mfma_f32_16x16x32_bf16 v[76:79], v[160:163], v[216:219], v[76:79]
	v_mfma_f32_16x16x32_bf16 v[72:75], v[168:171], v[216:219], v[72:75]
	s_setprio 0
	s_setprio 1
	v_mfma_f32_16x16x32_bf16 v[116:119], v[172:175], v[188:191], v[116:119]
	v_mfma_f32_16x16x32_bf16 v[112:115], v[180:183], v[188:191], v[112:115]
	v_mfma_f32_16x16x32_bf16 v[100:103], v[172:175], v[196:199], v[100:103]
	v_mfma_f32_16x16x32_bf16 v[96:99], v[180:183], v[196:199], v[96:99]
	v_mfma_f32_16x16x32_bf16 v[84:87], v[172:175], v[204:207], v[84:87]
	v_mfma_f32_16x16x32_bf16 v[80:83], v[180:183], v[204:207], v[80:83]
	v_mfma_f32_16x16x32_bf16 v[68:71], v[172:175], v[212:215], v[68:71]
	v_mfma_f32_16x16x32_bf16 v[64:67], v[180:183], v[212:215], v[64:67]
	v_mfma_f32_16x16x32_bf16 v[116:119], v[176:179], v[192:195], v[116:119]
	v_mfma_f32_16x16x32_bf16 v[112:115], v[184:187], v[192:195], v[112:115]
	v_mfma_f32_16x16x32_bf16 v[100:103], v[176:179], v[200:203], v[100:103]
	v_mfma_f32_16x16x32_bf16 v[96:99], v[184:187], v[200:203], v[96:99]
	v_mfma_f32_16x16x32_bf16 v[84:87], v[176:179], v[208:211], v[84:87]
	v_mfma_f32_16x16x32_bf16 v[80:83], v[184:187], v[208:211], v[80:83]
	v_mfma_f32_16x16x32_bf16 v[68:71], v[176:179], v[216:219], v[68:71]
	v_mfma_f32_16x16x32_bf16 v[64:67], v[184:187], v[216:219], v[64:67]
	s_setprio 0
	s_barrier
	s_mov_b32 m0, s72
	v_lshl_add_u64 v[220:221], v[220:221], 0, s[40:41]
	s_add_u32 s62, s66, 0xb0080
	ds_read_b128 v[188:191], v138 offset:49152
	ds_read_b128 v[192:195], v138 offset:50176
	ds_read_b128 v[196:199], v138 offset:51200
	ds_read_b128 v[200:203], v138 offset:52224
	ds_read_b128 v[204:207], v138 offset:53248
	ds_read_b128 v[208:211], v138 offset:54272
	ds_read_b128 v[212:215], v138 offset:55296
	ds_read_b128 v[216:219], v138 offset:56320
	global_load_lds_dwordx4 v[220:221], off
	v_lshl_add_u64 v[220:221], v[224:225], 0, s[40:41]
	s_mov_b32 m0, s73
	s_addc_u32 s63, s67, 0
	global_load_lds_dwordx4 v[220:221], off
	v_lshl_add_u64 v[220:221], s[62:63], 0, v[130:131]
	s_mov_b32 m0, s76
	s_nop 0
	global_load_lds_dwordx4 v[220:221], off
	v_lshl_add_u64 v[220:221], s[62:63], 0, v[128:129]
	s_mov_b32 m0, s77
	s_nop 0
	global_load_lds_dwordx4 v[220:221], off
	v_lshl_add_u64 v[220:221], v[226:227], 0, s[40:41]
	s_mov_b32 m0, s74
	s_nop 0
	global_load_lds_dwordx4 v[220:221], off
	v_lshl_add_u64 v[220:221], v[228:229], 0, s[40:41]
	s_mov_b32 m0, s75
	s_nop 0
	global_load_lds_dwordx4 v[220:221], off
	s_waitcnt vmcnt(8)
	s_waitcnt lgkmcnt(0)
	s_barrier
	s_setprio 1
	s_waitcnt lgkmcnt(0)
	v_mfma_f32_16x16x32_bf16 v[60:63], v[156:159], v[188:191], v[60:63]
	v_mfma_f32_16x16x32_bf16 v[56:59], v[164:167], v[188:191], v[56:59]
	v_mfma_f32_16x16x32_bf16 v[44:47], v[156:159], v[196:199], v[44:47]
	v_mfma_f32_16x16x32_bf16 v[40:43], v[164:167], v[196:199], v[40:43]
	v_mfma_f32_16x16x32_bf16 v[28:31], v[156:159], v[204:207], v[28:31]
	v_mfma_f32_16x16x32_bf16 v[24:27], v[164:167], v[204:207], v[24:27]
	v_mfma_f32_16x16x32_bf16 v[12:15], v[156:159], v[212:215], v[12:15]
	v_mfma_f32_16x16x32_bf16 v[8:11], v[164:167], v[212:215], v[8:11]
	v_mfma_f32_16x16x32_bf16 v[60:63], v[160:163], v[192:195], v[60:63]
	v_mfma_f32_16x16x32_bf16 v[56:59], v[168:171], v[192:195], v[56:59]
	v_mfma_f32_16x16x32_bf16 v[44:47], v[160:163], v[200:203], v[44:47]
	v_mfma_f32_16x16x32_bf16 v[40:43], v[168:171], v[200:203], v[40:43]
	v_mfma_f32_16x16x32_bf16 v[28:31], v[160:163], v[208:211], v[28:31]
	v_mfma_f32_16x16x32_bf16 v[24:27], v[168:171], v[208:211], v[24:27]
	v_mfma_f32_16x16x32_bf16 v[12:15], v[160:163], v[216:219], v[12:15]
	v_mfma_f32_16x16x32_bf16 v[8:11], v[168:171], v[216:219], v[8:11]
	s_setprio 0
	s_setprio 1
	v_mfma_f32_16x16x32_bf16 v[52:55], v[172:175], v[188:191], v[52:55]
	v_mfma_f32_16x16x32_bf16 v[48:51], v[180:183], v[188:191], v[48:51]
	v_mfma_f32_16x16x32_bf16 v[36:39], v[172:175], v[196:199], v[36:39]
	v_mfma_f32_16x16x32_bf16 v[32:35], v[180:183], v[196:199], v[32:35]
	v_mfma_f32_16x16x32_bf16 v[20:23], v[172:175], v[204:207], v[20:23]
	v_mfma_f32_16x16x32_bf16 v[16:19], v[180:183], v[204:207], v[16:19]
	v_mfma_f32_16x16x32_bf16 v[4:7], v[172:175], v[212:215], v[4:7]
	v_mfma_f32_16x16x32_bf16 v[0:3], v[180:183], v[212:215], v[0:3]
	v_mfma_f32_16x16x32_bf16 v[52:55], v[176:179], v[192:195], v[52:55]
	v_mfma_f32_16x16x32_bf16 v[48:51], v[184:187], v[192:195], v[48:51]
	v_mfma_f32_16x16x32_bf16 v[36:39], v[176:179], v[200:203], v[36:39]
	v_mfma_f32_16x16x32_bf16 v[32:35], v[184:187], v[200:203], v[32:35]
	v_mfma_f32_16x16x32_bf16 v[20:23], v[176:179], v[208:211], v[20:23]
	v_mfma_f32_16x16x32_bf16 v[16:19], v[184:187], v[208:211], v[16:19]
	v_mfma_f32_16x16x32_bf16 v[4:7], v[176:179], v[216:219], v[4:7]
	v_mfma_f32_16x16x32_bf16 v[0:3], v[184:187], v[216:219], v[0:3]
	s_setprio 0
	s_barrier
	s_add_u32 s33, s33, 0x100
	s_addc_u32 s55, s55, 0
	s_mov_b64 s[62:63], s[64:65]
	s_mov_b32 s57, s86

;     __host__ __device__ bool next(int i, Unit& u) const { const int L = i * G + c; if (L >= 16 * nkc) return false; u.kc = L % nkc; const int t = L / nkc; u.pn = t & 3; u.pm = 33 * (t >> 2); return true; }
; #define PG8_STAGE(bufoff, gbase, voff) do { _Pragma("unroll") for (int _i = 0; _i < 2; ++_i) \
;         __builtin_amdgcn_global_load_lds((const unsigned*)((const char*)(gbase) + (voff)[_i]), (PG8_LAS unsigned*)(lds + (bufoff) + ldsw + _i * 8192), 16, 0, 0); } while (0)
; #define PG8_LDA(dst, b, h) do { _Pragma("unroll") for (int m = 0; m < 4; ++m) _Pragma("unroll") for (int k = 0; k < 2; ++k) dst[m][k] = *(const PG8_LAS bf16x8*)(lds + PG8_SA(b, h) + aoff + m * 2048 + k * 1024); } while (0)
; #define PG8_LDB(dst, b, h) do { _Pragma("unroll") for (int n = 0; n < 2; ++n) _Pragma("unroll") for (int k = 0; k < 2; ++k) dst[n][k] = *(const PG8_LAS bf16x8*)(lds + PG8_SB(b, h) + boff + n * 2048 + k * 1024); } while (0)
; #define PG8_BAR __builtin_amdgcn_s_barrier()
; template <class Epi, class Sched, bool ALIGN_EPI = false, bool SP2 = false>
; __device__ __forceinline__ void gemm_phase(PG8_LAS unsigned char* lds, const Gemm g, const Sched& S, const Epi& E) {
;     ...
;         const bool has_next = S.next(ui + 1, nxt);
;         const char* nA = has_next ? (const char*)g.A + (size_t)nxt.pm * tstep + (size_t)nxt.kc * cstep : cA; const char* nB = has_next ? (const char*)g.Bt + (size_t)nxt.pn * tstep + (size_t)nxt.kc * cstep : cB;
;         for (int t = 0; t < nt; t += 2) {
;             const bool last = (t == nt - 2);
;             const char* a1 = cA + (size_t)(t + 1) * kstep;
;             const char* a2 = last ? nA : cA + (size_t)(t + 2) * kstep; const char* b2 = last ? nB : cB + (size_t)(t + 2) * kstep;
;             const char* a3 = a2 + kstep; const char* b3 = b2 + kstep;
;             if (last && has_next) S.a_ready(nxt);
;             if constexpr (SP2) {
;             PG8_LDB(B0, 0, 0); PG8_LDB(B1, 0, 1); PG8_SCHED; PG8_LDA(At, 0, 0); PG8_STAGE(PG8_SA(1, 1), a1 + hstep, voffA);
;             PG8_WAIT_V(8); PG8_WAIT_L(0); PG8_BAR; PG8_MMA(0, 0, At, B0); PG8_MMA(0, 1, At, B1); PG8_BAR; PG8_SCHED;
;             PG8_LDA(At, 0, 1); PG8_STAGE(PG8_SB(0, 0), b2, voffB); PG8_STAGE(PG8_SB(0, 1), b2 + hstep, voffB); PG8_STAGE(PG8_SA(0, 0), a2, voffA);
;             PG8_WAIT_V(8); PG8_WAIT_L(0); PG8_BAR; PG8_MMA(1, 0, At, B0); PG8_MMA(1, 1, At, B1); PG8_BAR; PG8_SCHED;
.LBB0_1029:
	s_ashr_i32 s57, s56, 31
	s_lshl_b64 s[58:59], s[56:57], 19
	s_add_u32 s58, s46, s58
	s_addc_u32 s59, s47, s59
	s_and_b64 s[60:61], s[8:9], exec
	s_cselect_b32 s33, s59, s11
	s_cselect_b32 s57, s58, s10
	s_ashr_i32 s55, s54, 31
	s_lshl_b64 s[60:61], s[54:55], 19
	s_add_u32 s60, s1, s60
	s_addc_u32 s61, s3, s61
	s_and_b64 s[68:69], s[8:9], exec
	s_cselect_b32 s55, s61, s67
	s_cselect_b32 s80, s60, s66
	s_add_u32 s10, s10, 0x40080
	s_addc_u32 s11, s11, 0
	s_add_u32 s81, s66, 0x100
	s_addc_u32 s82, s67, 0
	s_mov_b32 s83, -2
	ds_read_b128 v[128:131], v171
	ds_read_b128 v[132:135], v172
	ds_read_b128 v[188:191], v173
	ds_read_b128 v[192:195], v174
	ds_read_b128 v[196:199], v175
	ds_read_b128 v[200:203], v176
	ds_read_b128 v[204:207], v177
	ds_read_b128 v[208:211], v178
	s_add_u32 s66, s10, 0xfffc0080
	s_addc_u32 s67, s11, -1
	s_cmp_eq_u32 s83, 12
	s_cselect_b32 s69, s33, s67
	s_cselect_b32 s68, s57, s66
	s_cselect_b32 s67, s55, s82
	s_cselect_b32 s66, s80, s81
	s_mov_b32 m0, s77
	v_lshl_add_u64 v[136:137], s[10:11], 0, v[146:147]
	ds_read_b128 v[212:215], v159
	ds_read_b128 v[216:219], v159 offset:1024
	ds_read_b128 v[224:227], v159 offset:2048
	ds_read_b128 v[228:231], v159 offset:3072
	ds_read_b128 v[232:235], v159 offset:4096
	ds_read_b128 v[236:239], v159 offset:5120
	ds_read_b128 v[240:243], v159 offset:6144
	ds_read_b128 v[244:247], v159 offset:7168
	global_load_lds_dwordx4 v[136:137], off
	v_lshl_add_u64 v[136:137], s[10:11], 0, v[148:149]
	s_mov_b32 m0, s78
	s_nop 0
	global_load_lds_dwordx4 v[136:137], off
	s_waitcnt vmcnt(8)
	s_waitcnt lgkmcnt(0)
	s_barrier
	s_setprio 1
	s_waitcnt lgkmcnt(0)
	v_mfma_f32_16x16x32_bf16 v[124:127], v[128:131], v[212:215], 0
	v_mfma_f32_16x16x32_bf16 v[120:123], v[188:191], v[212:215], 0
	v_mfma_f32_16x16x32_bf16 v[108:111], v[128:131], v[224:227], 0
	v_mfma_f32_16x16x32_bf16 v[104:107], v[188:191], v[224:227], 0
	v_mfma_f32_16x16x32_bf16 v[92:95], v[128:131], v[232:235], 0
	v_mfma_f32_16x16x32_bf16 v[88:91], v[188:191], v[232:235], 0
	v_mfma_f32_16x16x32_bf16 v[76:79], v[128:131], v[240:243], 0
	v_mfma_f32_16x16x32_bf16 v[72:75], v[188:191], v[240:243], 0
	v_mfma_f32_16x16x32_bf16 v[124:127], v[132:135], v[216:219], v[124:127]
	v_mfma_f32_16x16x32_bf16 v[120:123], v[192:195], v[216:219], v[120:123]
	v_mfma_f32_16x16x32_bf16 v[108:111], v[132:135], v[228:231], v[108:111]
	v_mfma_f32_16x16x32_bf16 v[104:107], v[192:195], v[228:231], v[104:107]
	v_mfma_f32_16x16x32_bf16 v[92:95], v[132:135], v[236:239], v[92:95]
	v_mfma_f32_16x16x32_bf16 v[88:91], v[192:195], v[236:239], v[88:91]
	v_mfma_f32_16x16x32_bf16 v[76:79], v[132:135], v[244:247], v[76:79]
	v_mfma_f32_16x16x32_bf16 v[72:75], v[192:195], v[244:247], v[72:75]
	s_setprio 0
	s_setprio 1
	v_mfma_f32_16x16x32_bf16 v[116:119], v[196:199], v[212:215], 0
	v_mfma_f32_16x16x32_bf16 v[112:115], v[204:207], v[212:215], 0
	v_mfma_f32_16x16x32_bf16 v[100:103], v[196:199], v[224:227], 0
	v_mfma_f32_16x16x32_bf16 v[96:99], v[204:207], v[224:227], 0
	v_mfma_f32_16x16x32_bf16 v[84:87], v[196:199], v[232:235], 0
	v_mfma_f32_16x16x32_bf16 v[80:83], v[204:207], v[232:235], 0
	v_mfma_f32_16x16x32_bf16 v[68:71], v[196:199], v[240:243], 0
	v_mfma_f32_16x16x32_bf16 v[64:67], v[204:207], v[240:243], 0
	v_mfma_f32_16x16x32_bf16 v[116:119], v[200:203], v[216:219], v[116:119]
	v_mfma_f32_16x16x32_bf16 v[112:115], v[208:211], v[216:219], v[112:115]
	v_mfma_f32_16x16x32_bf16 v[100:103], v[200:203], v[228:231], v[100:103]
	v_mfma_f32_16x16x32_bf16 v[96:99], v[208:211], v[228:231], v[96:99]
	v_mfma_f32_16x16x32_bf16 v[84:87], v[200:203], v[236:239], v[84:87]
	v_mfma_f32_16x16x32_bf16 v[80:83], v[208:211], v[236:239], v[80:83]
	v_mfma_f32_16x16x32_bf16 v[68:71], v[200:203], v[244:247], v[68:71]
	v_mfma_f32_16x16x32_bf16 v[64:67], v[208:211], v[244:247], v[64:67]
	s_setprio 0
	s_barrier
	s_mov_b32 m0, s5
	v_lshl_add_u64 v[136:137], s[66:67], 0, v[140:141]
	s_add_u32 s84, s66, 0x40000
	ds_read_b128 v[212:215], v159 offset:16384
	ds_read_b128 v[216:219], v159 offset:17408
	ds_read_b128 v[224:227], v159 offset:18432
	ds_read_b128 v[228:231], v159 offset:19456
	ds_read_b128 v[232:235], v159 offset:20480
	ds_read_b128 v[236:239], v159 offset:21504
	ds_read_b128 v[240:243], v159 offset:22528
	ds_read_b128 v[244:247], v159 offset:23552
	global_load_lds_dwordx4 v[136:137], off
	v_lshl_add_u64 v[154:155], s[66:67], 0, v[144:145]
	s_mov_b32 m0, s12
	s_addc_u32 s85, s67, 0
	global_load_lds_dwordx4 v[154:155], off
	v_lshl_add_u64 v[220:221], s[84:85], 0, v[140:141]
	s_mov_b32 m0, s13
	v_lshl_add_u64 v[248:249], s[68:69], 0, v[142:143]
	global_load_lds_dwordx4 v[220:221], off
	v_lshl_add_u64 v[220:221], s[84:85], 0, v[144:145]
	s_mov_b32 m0, s14
	s_nop 0
	global_load_lds_dwordx4 v[220:221], off
	v_lshl_add_u64 v[220:221], s[68:69], 0, v[138:139]
	s_mov_b32 m0, s4
	s_nop 0
	global_load_lds_dwordx4 v[220:221], off
	s_mov_b32 m0, s15
	s_nop 0
	global_load_lds_dwordx4 v[248:249], off
	s_waitcnt vmcnt(8)
	s_waitcnt lgkmcnt(0)
	s_barrier
; #define PG8_STAGE(bufoff, gbase, voff) do { _Pragma("unroll") for (int _i = 0; _i < 2; ++_i) \
;         __builtin_amdgcn_global_load_lds((const unsigned*)((const char*)(gbase) + (voff)[_i]), (PG8_LAS unsigned*)(lds + (bufoff) + ldsw + _i * 8192), 16, 0, 0); } while (0)
; #define PG8_LDA(dst, b, h) do { _Pragma("unroll") for (int m = 0; m < 4; ++m) _Pragma("unroll") for (int k = 0; k < 2; ++k) dst[m][k] = *(const PG8_LAS bf16x8*)(lds + PG8_SA(b, h) + aoff + m * 2048 + k * 1024); } while (0)
; #define PG8_LDB(dst, b, h) do { _Pragma("unroll") for (int n = 0; n < 2; ++n) _Pragma("unroll") for (int k = 0; k < 2; ++k) dst[n][k] = *(const PG8_LAS bf16x8*)(lds + PG8_SB(b, h) + boff + n * 2048 + k * 1024); } while (0)
; #define PG8_MMA(ai, bj, At, Bt) do { __builtin_amdgcn_s_setprio(1); _Pragma("unroll") for (int m = 0; m < 4; ++m) _Pragma("unroll") for (int n = 0; n < 2; ++n) _Pragma("unroll") for (int k = 0; k < 2; ++k) \
;         acc[ai][bj][m][n] = __builtin_amdgcn_mfma_f32_16x16x32_bf16(Bt[n][k], At[m][k], acc[ai][bj][m][n], 0, 0, 0); __builtin_amdgcn_s_setprio(0); } while (0)
; #define PG8_WAIT_V(n) asm volatile("s_waitcnt vmcnt(" #n ")" ::: "memory")
; #define PG8_WAIT_L(n) asm volatile("s_waitcnt lgkmcnt(" #n ")" ::: "memory")
; #define PG8_BAR __builtin_amdgcn_s_barrier()
; #define PG8_SCHED __builtin_amdgcn_sched_barrier(0)
; template <class Epi, class Sched, bool ALIGN_EPI = false, bool SP2 = false>
; __device__ __forceinline__ void gemm_phase(PG8_LAS unsigned char* lds, const Gemm g, const Sched& S, const Epi& E) {
;     ...
;             PG8_WAIT_V(8); PG8_WAIT_L(0); PG8_BAR; PG8_MMA(1, 0, At, B0); PG8_MMA(1, 1, At, B1); PG8_BAR; PG8_SCHED;
;             PG8_LDB(B0, 1, 0); PG8_LDB(B1, 1, 1); PG8_SCHED; PG8_LDA(At, 1, 0); PG8_STAGE(PG8_SA(0, 1), a2 + hstep, voffA);
;             PG8_WAIT_V(8); PG8_WAIT_L(0); PG8_BAR; PG8_MMA(0, 0, At, B0); PG8_MMA(0, 1, At, B1); PG8_BAR; PG8_SCHED;
	s_setprio 1
	s_waitcnt lgkmcnt(0)
	v_mfma_f32_16x16x32_bf16 v[60:63], v[128:131], v[212:215], 0
	v_mfma_f32_16x16x32_bf16 v[56:59], v[188:191], v[212:215], 0
	v_mfma_f32_16x16x32_bf16 v[44:47], v[128:131], v[224:227], 0
	v_mfma_f32_16x16x32_bf16 v[40:43], v[188:191], v[224:227], 0
	v_mfma_f32_16x16x32_bf16 v[28:31], v[128:131], v[232:235], 0
	v_mfma_f32_16x16x32_bf16 v[24:27], v[188:191], v[232:235], 0
	v_mfma_f32_16x16x32_bf16 v[12:15], v[128:131], v[240:243], 0
	v_mfma_f32_16x16x32_bf16 v[8:11], v[188:191], v[240:243], 0
	v_mfma_f32_16x16x32_bf16 v[60:63], v[132:135], v[216:219], v[60:63]
	v_mfma_f32_16x16x32_bf16 v[56:59], v[192:195], v[216:219], v[56:59]
	v_mfma_f32_16x16x32_bf16 v[44:47], v[132:135], v[228:231], v[44:47]
	v_mfma_f32_16x16x32_bf16 v[40:43], v[192:195], v[228:231], v[40:43]
	v_mfma_f32_16x16x32_bf16 v[28:31], v[132:135], v[236:239], v[28:31]
	v_mfma_f32_16x16x32_bf16 v[24:27], v[192:195], v[236:239], v[24:27]
	v_mfma_f32_16x16x32_bf16 v[12:15], v[132:135], v[244:247], v[12:15]
	v_mfma_f32_16x16x32_bf16 v[8:11], v[192:195], v[244:247], v[8:11]
	s_setprio 0
	s_setprio 1
	v_mfma_f32_16x16x32_bf16 v[52:55], v[196:199], v[212:215], 0
	v_mfma_f32_16x16x32_bf16 v[48:51], v[204:207], v[212:215], 0
	v_mfma_f32_16x16x32_bf16 v[36:39], v[196:199], v[224:227], 0
	v_mfma_f32_16x16x32_bf16 v[32:35], v[204:207], v[224:227], 0
	v_mfma_f32_16x16x32_bf16 v[20:23], v[196:199], v[232:235], 0
	v_mfma_f32_16x16x32_bf16 v[16:19], v[204:207], v[232:235], 0
	v_mfma_f32_16x16x32_bf16 v[4:7], v[196:199], v[240:243], 0
	v_mfma_f32_16x16x32_bf16 v[0:3], v[204:207], v[240:243], 0
	v_mfma_f32_16x16x32_bf16 v[52:55], v[200:203], v[216:219], v[52:55]
	v_mfma_f32_16x16x32_bf16 v[48:51], v[208:211], v[216:219], v[48:51]
	v_mfma_f32_16x16x32_bf16 v[36:39], v[200:203], v[228:231], v[36:39]
	v_mfma_f32_16x16x32_bf16 v[32:35], v[208:211], v[228:231], v[32:35]
	v_mfma_f32_16x16x32_bf16 v[20:23], v[200:203], v[236:239], v[20:23]
	v_mfma_f32_16x16x32_bf16 v[16:19], v[208:211], v[236:239], v[16:19]
	v_mfma_f32_16x16x32_bf16 v[4:7], v[200:203], v[244:247], v[4:7]
	v_mfma_f32_16x16x32_bf16 v[0:3], v[208:211], v[244:247], v[0:3]
	s_setprio 0
	s_barrier
	ds_read_b128 v[128:131], v179
	ds_read_b128 v[132:135], v180
	ds_read_b128 v[188:191], v181
	ds_read_b128 v[192:195], v182
	ds_read_b128 v[196:199], v183
	ds_read_b128 v[200:203], v184
	ds_read_b128 v[204:207], v185
	ds_read_b128 v[208:211], v186
	s_add_u32 s68, s68, 0x40000
	s_addc_u32 s69, s69, 0
	s_mov_b32 m0, s39
	v_lshl_add_u64 v[250:251], s[68:69], 0, v[138:139]
	ds_read_b128 v[212:215], v159 offset:32768
	ds_read_b128 v[216:219], v159 offset:33792
	ds_read_b128 v[224:227], v159 offset:34816
	ds_read_b128 v[228:231], v159 offset:35840
	ds_read_b128 v[232:235], v159 offset:36864
	ds_read_b128 v[236:239], v159 offset:37888
	ds_read_b128 v[240:243], v159 offset:38912
	ds_read_b128 v[244:247], v159 offset:39936
	global_load_lds_dwordx4 v[250:251], off
	v_lshl_add_u64 v[250:251], s[68:69], 0, v[142:143]
	s_mov_b32 m0, s43
	s_nop 0
	global_load_lds_dwordx4 v[250:251], off
	s_waitcnt vmcnt(8)
	s_waitcnt lgkmcnt(0)
	s_barrier
	s_setprio 1
	s_waitcnt lgkmcnt(0)
	v_mfma_f32_16x16x32_bf16 v[124:127], v[128:131], v[212:215], v[124:127]
	v_mfma_f32_16x16x32_bf16 v[120:123], v[188:191], v[212:215], v[120:123]
	v_mfma_f32_16x16x32_bf16 v[108:111], v[128:131], v[224:227], v[108:111]
	v_mfma_f32_16x16x32_bf16 v[104:107], v[188:191], v[224:227], v[104:107]
	v_mfma_f32_16x16x32_bf16 v[92:95], v[128:131], v[232:235], v[92:95]
	v_mfma_f32_16x16x32_bf16 v[88:91], v[188:191], v[232:235], v[88:91]
	v_mfma_f32_16x16x32_bf16 v[76:79], v[128:131], v[240:243], v[76:79]
	v_mfma_f32_16x16x32_bf16 v[72:75], v[188:191], v[240:243], v[72:75]
	v_mfma_f32_16x16x32_bf16 v[124:127], v[132:135], v[216:219], v[124:127]
	v_mfma_f32_16x16x32_bf16 v[120:123], v[192:195], v[216:219], v[120:123]
	v_mfma_f32_16x16x32_bf16 v[108:111], v[132:135], v[228:231], v[108:111]
	v_mfma_f32_16x16x32_bf16 v[104:107], v[192:195], v[228:231], v[104:107]
	v_mfma_f32_16x16x32_bf16 v[92:95], v[132:135], v[236:239], v[92:95]
	v_mfma_f32_16x16x32_bf16 v[88:91], v[192:195], v[236:239], v[88:91]
	v_mfma_f32_16x16x32_bf16 v[76:79], v[132:135], v[244:247], v[76:79]
	v_mfma_f32_16x16x32_bf16 v[72:75], v[192:195], v[244:247], v[72:75]
	s_setprio 0
	s_setprio 1
	v_mfma_f32_16x16x32_bf16 v[116:119], v[196:199], v[212:215], v[116:119]
	v_mfma_f32_16x16x32_bf16 v[112:115], v[204:207], v[212:215], v[112:115]
	v_mfma_f32_16x16x32_bf16 v[100:103], v[196:199], v[224:227], v[100:103]
	v_mfma_f32_16x16x32_bf16 v[96:99], v[204:207], v[224:227], v[96:99]
	v_mfma_f32_16x16x32_bf16 v[84:87], v[196:199], v[232:235], v[84:87]
	v_mfma_f32_16x16x32_bf16 v[80:83], v[204:207], v[232:235], v[80:83]
	v_mfma_f32_16x16x32_bf16 v[68:71], v[196:199], v[240:243], v[68:71]
	v_mfma_f32_16x16x32_bf16 v[64:67], v[204:207], v[240:243], v[64:67]
	v_mfma_f32_16x16x32_bf16 v[116:119], v[200:203], v[216:219], v[116:119]
	v_mfma_f32_16x16x32_bf16 v[112:115], v[208:211], v[216:219], v[112:115]
	v_mfma_f32_16x16x32_bf16 v[100:103], v[200:203], v[228:231], v[100:103]
	v_mfma_f32_16x16x32_bf16 v[96:99], v[208:211], v[228:231], v[96:99]
	v_mfma_f32_16x16x32_bf16 v[84:87], v[200:203], v[236:239], v[84:87]
	v_mfma_f32_16x16x32_bf16 v[80:83], v[208:211], v[236:239], v[80:83]
	v_mfma_f32_16x16x32_bf16 v[68:71], v[200:203], v[244:247], v[68:71]
	v_mfma_f32_16x16x32_bf16 v[64:67], v[208:211], v[244:247], v[64:67]
	s_setprio 0
	s_barrier
; #define PG8_STAGE(bufoff, gbase, voff) do { _Pragma("unroll") for (int _i = 0; _i < 2; ++_i) \
;         __builtin_amdgcn_global_load_lds((const unsigned*)((const char*)(gbase) + (voff)[_i]), (PG8_LAS unsigned*)(lds + (bufoff) + ldsw + _i * 8192), 16, 0, 0); } while (0)
; #define PG8_LDA(dst, b, h) do { _Pragma("unroll") for (int m = 0; m < 4; ++m) _Pragma("unroll") for (int k = 0; k < 2; ++k) dst[m][k] = *(const PG8_LAS bf16x8*)(lds + PG8_SA(b, h) + aoff + m * 2048 + k * 1024); } while (0)
; #define PG8_MMA(ai, bj, At, Bt) do { __builtin_amdgcn_s_setprio(1); _Pragma("unroll") for (int m = 0; m < 4; ++m) _Pragma("unroll") for (int n = 0; n < 2; ++n) _Pragma("unroll") for (int k = 0; k < 2; ++k) \
;         acc[ai][bj][m][n] = __builtin_amdgcn_mfma_f32_16x16x32_bf16(Bt[n][k], At[m][k], acc[ai][bj][m][n], 0, 0, 0); __builtin_amdgcn_s_setprio(0); } while (0)
; #define PG8_WAIT_V(n) asm volatile("s_waitcnt vmcnt(" #n ")" ::: "memory")
; #define PG8_WAIT_L(n) asm volatile("s_waitcnt lgkmcnt(" #n ")" ::: "memory")
; #define PG8_BAR __builtin_amdgcn_s_barrier()
; #define PG8_SCHED __builtin_amdgcn_sched_barrier(0)
; template <class Epi, class Sched, bool ALIGN_EPI = false, bool SP2 = false>
; __device__ __forceinline__ void gemm_phase(PG8_LAS unsigned char* lds, const Gemm g, const Sched& S, const Epi& E) {
;     ...
;             PG8_LDA(At, 1, 1); PG8_STAGE(PG8_SB(1, 0), b3, voffB); PG8_STAGE(PG8_SB(1, 1), b3 + hstep, voffB); PG8_STAGE(PG8_SA(1, 0), a3, voffA);
;             PG8_WAIT_V(8); PG8_WAIT_L(0); PG8_BAR; PG8_MMA(1, 0, At, B0); PG8_MMA(1, 1, At, B1); PG8_BAR; PG8_SCHED;
	s_mov_b32 m0, s63
	v_lshl_add_u64 v[136:137], v[136:137], 0, s[40:41]
	s_add_u32 s66, s66, 0x40080
	ds_read_b128 v[212:215], v159 offset:49152
	ds_read_b128 v[216:219], v159 offset:50176
	ds_read_b128 v[224:227], v159 offset:51200
	ds_read_b128 v[228:231], v159 offset:52224
	ds_read_b128 v[232:235], v159 offset:53248
	ds_read_b128 v[236:239], v159 offset:54272
	ds_read_b128 v[240:243], v159 offset:55296
	ds_read_b128 v[244:247], v159 offset:56320
	global_load_lds_dwordx4 v[136:137], off
	v_lshl_add_u64 v[136:137], v[154:155], 0, s[40:41]
	s_mov_b32 m0, s65
	s_addc_u32 s67, s67, 0
	global_load_lds_dwordx4 v[136:137], off
	v_lshl_add_u64 v[136:137], s[66:67], 0, v[140:141]
	s_mov_b32 m0, s72
	s_nop 0
	global_load_lds_dwordx4 v[136:137], off
	v_lshl_add_u64 v[136:137], s[66:67], 0, v[144:145]
	s_mov_b32 m0, s73
	s_nop 0
	global_load_lds_dwordx4 v[136:137], off
	v_lshl_add_u64 v[136:137], v[220:221], 0, s[40:41]
	s_mov_b32 m0, s70
	s_nop 0
	global_load_lds_dwordx4 v[136:137], off
	v_lshl_add_u64 v[136:137], v[248:249], 0, s[40:41]
	s_mov_b32 m0, s71
	s_nop 0
	global_load_lds_dwordx4 v[136:137], off
	s_waitcnt vmcnt(8)
	s_waitcnt lgkmcnt(0)
	s_barrier
	s_setprio 1
	s_waitcnt lgkmcnt(0)
	v_mfma_f32_16x16x32_bf16 v[60:63], v[128:131], v[212:215], v[60:63]
	v_mfma_f32_16x16x32_bf16 v[56:59], v[188:191], v[212:215], v[56:59]
	v_mfma_f32_16x16x32_bf16 v[44:47], v[128:131], v[224:227], v[44:47]
	v_mfma_f32_16x16x32_bf16 v[40:43], v[188:191], v[224:227], v[40:43]
	v_mfma_f32_16x16x32_bf16 v[28:31], v[128:131], v[232:235], v[28:31]
	v_mfma_f32_16x16x32_bf16 v[24:27], v[188:191], v[232:235], v[24:27]
	v_mfma_f32_16x16x32_bf16 v[12:15], v[128:131], v[240:243], v[12:15]
	v_mfma_f32_16x16x32_bf16 v[8:11], v[188:191], v[240:243], v[8:11]
	v_mfma_f32_16x16x32_bf16 v[60:63], v[132:135], v[216:219], v[60:63]
	v_mfma_f32_16x16x32_bf16 v[56:59], v[192:195], v[216:219], v[56:59]
	v_mfma_f32_16x16x32_bf16 v[44:47], v[132:135], v[228:231], v[44:47]
	v_mfma_f32_16x16x32_bf16 v[40:43], v[192:195], v[228:231], v[40:43]
	v_mfma_f32_16x16x32_bf16 v[28:31], v[132:135], v[236:239], v[28:31]
	v_mfma_f32_16x16x32_bf16 v[24:27], v[192:195], v[236:239], v[24:27]
	v_mfma_f32_16x16x32_bf16 v[12:15], v[132:135], v[244:247], v[12:15]
	v_mfma_f32_16x16x32_bf16 v[8:11], v[192:195], v[244:247], v[8:11]
	s_setprio 0
	s_setprio 1
	v_mfma_f32_16x16x32_bf16 v[52:55], v[196:199], v[212:215], v[52:55]
	v_mfma_f32_16x16x32_bf16 v[48:51], v[204:207], v[212:215], v[48:51]
	v_mfma_f32_16x16x32_bf16 v[36:39], v[196:199], v[224:227], v[36:39]
	v_mfma_f32_16x16x32_bf16 v[32:35], v[204:207], v[224:227], v[32:35]
	v_mfma_f32_16x16x32_bf16 v[20:23], v[196:199], v[232:235], v[20:23]
	v_mfma_f32_16x16x32_bf16 v[16:19], v[204:207], v[232:235], v[16:19]
	v_mfma_f32_16x16x32_bf16 v[4:7], v[196:199], v[240:243], v[4:7]
	v_mfma_f32_16x16x32_bf16 v[0:3], v[204:207], v[240:243], v[0:3]
	v_mfma_f32_16x16x32_bf16 v[52:55], v[200:203], v[216:219], v[52:55]
	v_mfma_f32_16x16x32_bf16 v[48:51], v[208:211], v[216:219], v[48:51]
	v_mfma_f32_16x16x32_bf16 v[36:39], v[200:203], v[228:231], v[36:39]
	v_mfma_f32_16x16x32_bf16 v[32:35], v[208:211], v[228:231], v[32:35]
	v_mfma_f32_16x16x32_bf16 v[20:23], v[200:203], v[236:239], v[20:23]
	v_mfma_f32_16x16x32_bf16 v[16:19], v[208:211], v[236:239], v[16:19]
	v_mfma_f32_16x16x32_bf16 v[4:7], v[200:203], v[244:247], v[4:7]
	v_mfma_f32_16x16x32_bf16 v[0:3], v[208:211], v[244:247], v[0:3]
	s_setprio 0
	s_barrier
	s_add_i32 s83, s83, 2
	s_add_u32 s10, s10, 0x100
	s_addc_u32 s11, s11, 0
	s_add_u32 s81, s81, 0x100
	s_addc_u32 s82, s82, 0

;     __host__ __device__ bool next(int i, Unit& u) const { const int L = i * G + c; if (L >= 16 * nkc) return false; u.kc = L % nkc; const int t = L / nkc; u.pn = t & 3; u.pm = 33 * (t >> 2); return true; }
; #define PG8_STAGE(bufoff, gbase, voff) do { _Pragma("unroll") for (int _i = 0; _i < 2; ++_i) \
;         __builtin_amdgcn_global_load_lds((const unsigned*)((const char*)(gbase) + (voff)[_i]), (PG8_LAS unsigned*)(lds + (bufoff) + ldsw + _i * 8192), 16, 0, 0); } while (0)
; #define PG8_LDA(dst, b, h) do { _Pragma("unroll") for (int m = 0; m < 4; ++m) _Pragma("unroll") for (int k = 0; k < 2; ++k) dst[m][k] = *(const PG8_LAS bf16x8*)(lds + PG8_SA(b, h) + aoff + m * 2048 + k * 1024); } while (0)
; #define PG8_LDB(dst, b, h) do { _Pragma("unroll") for (int n = 0; n < 2; ++n) _Pragma("unroll") for (int k = 0; k < 2; ++k) dst[n][k] = *(const PG8_LAS bf16x8*)(lds + PG8_SB(b, h) + boff + n * 2048 + k * 1024); } while (0)
; #define PG8_BAR __builtin_amdgcn_s_barrier()
; template <class Epi, class Sched, bool ALIGN_EPI = false, bool SP2 = false>
; __device__ __forceinline__ void gemm_phase(PG8_LAS unsigned char* lds, const Gemm g, const Sched& S, const Epi& E) {
;     ...
;         const bool has_next = S.next(ui + 1, nxt);
;         const char* nA = has_next ? (const char*)g.A + (size_t)nxt.pm * tstep + (size_t)nxt.kc * cstep : cA; const char* nB = has_next ? (const char*)g.Bt + (size_t)nxt.pn * tstep + (size_t)nxt.kc * cstep : cB;
;         for (int t = 0; t < nt; t += 2) {
;             const bool last = (t == nt - 2);
;             const char* a1 = cA + (size_t)(t + 1) * kstep;
;             const char* a2 = last ? nA : cA + (size_t)(t + 2) * kstep; const char* b2 = last ? nB : cB + (size_t)(t + 2) * kstep;
;             const char* a3 = a2 + kstep; const char* b3 = b2 + kstep;
;             if (last && has_next) S.a_ready(nxt);
;             if constexpr (SP2) {
;             PG8_LDB(B0, 0, 0); PG8_LDB(B1, 0, 1); PG8_SCHED; PG8_LDA(At, 0, 0); PG8_STAGE(PG8_SA(1, 1), a1 + hstep, voffA);
;             PG8_WAIT_V(8); PG8_WAIT_L(0); PG8_BAR; PG8_MMA(0, 0, At, B0); PG8_MMA(0, 1, At, B1); PG8_BAR; PG8_SCHED;
;             PG8_LDA(At, 0, 1); PG8_STAGE(PG8_SB(0, 0), b2, voffB); PG8_STAGE(PG8_SB(0, 1), b2 + hstep, voffB); PG8_STAGE(PG8_SA(0, 0), a2, voffA);
;             PG8_WAIT_V(8); PG8_WAIT_L(0); PG8_BAR; PG8_MMA(1, 0, At, B0); PG8_MMA(1, 1, At, B1); PG8_BAR; PG8_SCHED;
.LBB0_1306:
	s_ashr_i32 s21, s20, 31
	s_lshl_b64 s[22:23], s[20:21], 19
	s_add_u32 s22, s46, s22
	s_addc_u32 s23, s47, s23
	s_and_b64 s[24:25], s[6:7], exec
	s_cselect_b32 s21, s23, s41
	s_cselect_b32 s37, s22, s40
	s_ashr_i32 s19, s18, 31
	s_lshl_b64 s[24:25], s[18:19], 19
	s_add_u32 s24, s3, s24
	s_addc_u32 s25, s4, s25
	s_and_b64 s[52:53], s[6:7], exec
	s_cselect_b32 s19, s25, s51
	s_cselect_b32 s76, s24, s50
	s_add_u32 s77, s50, 0x100
	s_addc_u32 s78, s51, 0
	s_mov_b32 s79, -2
	ds_read_b128 v[142:145], v174
	ds_read_b128 v[146:149], v175
	ds_read_b128 v[150:153], v176
	ds_read_b128 v[154:157], v177
	ds_read_b128 v[158:161], v178
	ds_read_b128 v[162:165], v179
	ds_read_b128 v[166:169], v180
	ds_read_b128 v[190:193], v181
	s_add_u32 s50, s40, 0x100
	s_addc_u32 s51, s41, 0
	s_cmp_eq_u32 s79, 12
	s_cselect_b32 s55, s21, s51
	s_cselect_b32 s54, s37, s50
	s_cselect_b32 s53, s19, s78
	s_cselect_b32 s52, s76, s77
	s_mov_b32 m0, s68
	v_lshl_add_u64 v[170:171], s[40:41], 0, v[134:135]
	ds_read_b128 v[194:197], v172
	ds_read_b128 v[198:201], v172 offset:1024
	ds_read_b128 v[202:205], v172 offset:2048
	ds_read_b128 v[206:209], v172 offset:3072
	ds_read_b128 v[210:213], v172 offset:4096
	ds_read_b128 v[214:217], v172 offset:5120
	ds_read_b128 v[218:221], v172 offset:6144
	ds_read_b128 v[224:227], v172 offset:7168
	global_load_lds_dwordx4 v[170:171], off
	v_lshl_add_u64 v[170:171], s[40:41], 0, v[136:137]
	s_mov_b32 m0, s69
	s_nop 0
	global_load_lds_dwordx4 v[170:171], off
	s_waitcnt vmcnt(8)
	s_waitcnt lgkmcnt(0)
	s_barrier
	s_setprio 1
	s_waitcnt lgkmcnt(0)
	v_mfma_f32_16x16x32_bf16 v[124:127], v[142:145], v[194:197], 0
	v_mfma_f32_16x16x32_bf16 v[108:111], v[150:153], v[194:197], 0
	v_mfma_f32_16x16x32_bf16 v[120:123], v[142:145], v[202:205], 0
	v_mfma_f32_16x16x32_bf16 v[96:99], v[150:153], v[202:205], 0
	v_mfma_f32_16x16x32_bf16 v[116:119], v[142:145], v[210:213], 0
	v_mfma_f32_16x16x32_bf16 v[88:91], v[150:153], v[210:213], 0
	v_mfma_f32_16x16x32_bf16 v[112:115], v[142:145], v[218:221], 0
	v_mfma_f32_16x16x32_bf16 v[84:87], v[150:153], v[218:221], 0
	v_mfma_f32_16x16x32_bf16 v[124:127], v[146:149], v[198:201], v[124:127]
	v_mfma_f32_16x16x32_bf16 v[108:111], v[154:157], v[198:201], v[108:111]
	v_mfma_f32_16x16x32_bf16 v[120:123], v[146:149], v[206:209], v[120:123]
	v_mfma_f32_16x16x32_bf16 v[96:99], v[154:157], v[206:209], v[96:99]
	v_mfma_f32_16x16x32_bf16 v[116:119], v[146:149], v[214:217], v[116:119]
	v_mfma_f32_16x16x32_bf16 v[88:91], v[154:157], v[214:217], v[88:91]
	v_mfma_f32_16x16x32_bf16 v[112:115], v[146:149], v[224:227], v[112:115]
	v_mfma_f32_16x16x32_bf16 v[84:87], v[154:157], v[224:227], v[84:87]
	s_setprio 0
	s_setprio 1
	v_mfma_f32_16x16x32_bf16 v[68:71], v[158:161], v[194:197], 0
	v_mfma_f32_16x16x32_bf16 v[40:43], v[166:169], v[194:197], 0
	v_mfma_f32_16x16x32_bf16 v[60:63], v[158:161], v[202:205], 0
	v_mfma_f32_16x16x32_bf16 v[32:35], v[166:169], v[202:205], 0
	v_mfma_f32_16x16x32_bf16 v[52:55], v[158:161], v[210:213], 0
	v_mfma_f32_16x16x32_bf16 v[24:27], v[166:169], v[210:213], 0
	v_mfma_f32_16x16x32_bf16 v[48:51], v[158:161], v[218:221], 0
	v_mfma_f32_16x16x32_bf16 v[16:19], v[166:169], v[218:221], 0
	v_mfma_f32_16x16x32_bf16 v[68:71], v[162:165], v[198:201], v[68:71]
	v_mfma_f32_16x16x32_bf16 v[40:43], v[190:193], v[198:201], v[40:43]
	v_mfma_f32_16x16x32_bf16 v[60:63], v[162:165], v[206:209], v[60:63]
	v_mfma_f32_16x16x32_bf16 v[32:35], v[190:193], v[206:209], v[32:35]
	v_mfma_f32_16x16x32_bf16 v[52:55], v[162:165], v[214:217], v[52:55]
	v_mfma_f32_16x16x32_bf16 v[24:27], v[190:193], v[214:217], v[24:27]
	v_mfma_f32_16x16x32_bf16 v[48:51], v[162:165], v[224:227], v[48:51]
	v_mfma_f32_16x16x32_bf16 v[16:19], v[190:193], v[224:227], v[16:19]
	s_setprio 0
	s_barrier
	s_mov_b32 m0, s12
	v_lshl_add_u64 v[170:171], s[52:53], 0, v[128:129]
	s_add_u32 s40, s52, 0x40000
	ds_read_b128 v[194:197], v172 offset:16384
	ds_read_b128 v[198:201], v172 offset:17408
	ds_read_b128 v[202:205], v172 offset:18432
	ds_read_b128 v[206:209], v172 offset:19456
	ds_read_b128 v[210:213], v172 offset:20480
	ds_read_b128 v[214:217], v172 offset:21504
	ds_read_b128 v[218:221], v172 offset:22528
	ds_read_b128 v[224:227], v172 offset:23552
	global_load_lds_dwordx4 v[170:171], off
	v_lshl_add_u64 v[228:229], s[52:53], 0, v[130:131]
	s_mov_b32 m0, s13
	s_addc_u32 s41, s53, 0
	global_load_lds_dwordx4 v[228:229], off
	v_lshl_add_u64 v[236:237], s[40:41], 0, v[128:129]
	s_mov_b32 m0, s14
	v_lshl_add_u64 v[238:239], s[54:55], 0, v[130:131]
	global_load_lds_dwordx4 v[236:237], off
	v_lshl_add_u64 v[236:237], s[40:41], 0, v[130:131]
	s_mov_b32 m0, s15
	s_nop 0
	global_load_lds_dwordx4 v[236:237], off
	v_lshl_add_u64 v[236:237], s[54:55], 0, v[128:129]
	s_mov_b32 m0, s5
	s_nop 0
	global_load_lds_dwordx4 v[236:237], off
	s_mov_b32 m0, s39
	s_nop 0
	global_load_lds_dwordx4 v[238:239], off
	s_waitcnt vmcnt(8)
	s_waitcnt lgkmcnt(0)
	s_barrier
; #define PG8_STAGE(bufoff, gbase, voff) do { _Pragma("unroll") for (int _i = 0; _i < 2; ++_i) \
;         __builtin_amdgcn_global_load_lds((const unsigned*)((const char*)(gbase) + (voff)[_i]), (PG8_LAS unsigned*)(lds + (bufoff) + ldsw + _i * 8192), 16, 0, 0); } while (0)
; #define PG8_LDA(dst, b, h) do { _Pragma("unroll") for (int m = 0; m < 4; ++m) _Pragma("unroll") for (int k = 0; k < 2; ++k) dst[m][k] = *(const PG8_LAS bf16x8*)(lds + PG8_SA(b, h) + aoff + m * 2048 + k * 1024); } while (0)
; #define PG8_LDB(dst, b, h) do { _Pragma("unroll") for (int n = 0; n < 2; ++n) _Pragma("unroll") for (int k = 0; k < 2; ++k) dst[n][k] = *(const PG8_LAS bf16x8*)(lds + PG8_SB(b, h) + boff + n * 2048 + k * 1024); } while (0)
; #define PG8_MMA(ai, bj, At, Bt) do { __builtin_amdgcn_s_setprio(1); _Pragma("unroll") for (int m = 0; m < 4; ++m) _Pragma("unroll") for (int n = 0; n < 2; ++n) _Pragma("unroll") for (int k = 0; k < 2; ++k) \
;         acc[ai][bj][m][n] = __builtin_amdgcn_mfma_f32_16x16x32_bf16(Bt[n][k], At[m][k], acc[ai][bj][m][n], 0, 0, 0); __builtin_amdgcn_s_setprio(0); } while (0)
; #define PG8_WAIT_V(n) asm volatile("s_waitcnt vmcnt(" #n ")" ::: "memory")
; #define PG8_WAIT_L(n) asm volatile("s_waitcnt lgkmcnt(" #n ")" ::: "memory")
; #define PG8_BAR __builtin_amdgcn_s_barrier()
; #define PG8_SCHED __builtin_amdgcn_sched_barrier(0)
; template <class Epi, class Sched, bool ALIGN_EPI = false, bool SP2 = false>
; __device__ __forceinline__ void gemm_phase(PG8_LAS unsigned char* lds, const Gemm g, const Sched& S, const Epi& E) {
;     ...
;             PG8_WAIT_V(8); PG8_WAIT_L(0); PG8_BAR; PG8_MMA(1, 0, At, B0); PG8_MMA(1, 1, At, B1); PG8_BAR; PG8_SCHED;
;             PG8_LDB(B0, 1, 0); PG8_LDB(B1, 1, 1); PG8_SCHED; PG8_LDA(At, 1, 0); PG8_STAGE(PG8_SA(0, 1), a2 + hstep, voffA);
;             PG8_WAIT_V(8); PG8_WAIT_L(0); PG8_BAR; PG8_MMA(0, 0, At, B0); PG8_MMA(0, 1, At, B1); PG8_BAR; PG8_SCHED;
	s_setprio 1
	s_waitcnt lgkmcnt(0)
	v_mfma_f32_16x16x32_bf16 v[104:107], v[142:145], v[194:197], 0
	v_mfma_f32_16x16x32_bf16 v[76:79], v[150:153], v[194:197], 0
	v_mfma_f32_16x16x32_bf16 v[100:103], v[142:145], v[202:205], 0
	v_mfma_f32_16x16x32_bf16 v[72:75], v[150:153], v[202:205], 0
	v_mfma_f32_16x16x32_bf16 v[92:95], v[142:145], v[210:213], 0
	v_mfma_f32_16x16x32_bf16 v[64:67], v[150:153], v[210:213], 0
	v_mfma_f32_16x16x32_bf16 v[80:83], v[142:145], v[218:221], 0
	v_mfma_f32_16x16x32_bf16 v[56:59], v[150:153], v[218:221], 0
	v_mfma_f32_16x16x32_bf16 v[104:107], v[146:149], v[198:201], v[104:107]
	v_mfma_f32_16x16x32_bf16 v[76:79], v[154:157], v[198:201], v[76:79]
	v_mfma_f32_16x16x32_bf16 v[100:103], v[146:149], v[206:209], v[100:103]
	v_mfma_f32_16x16x32_bf16 v[72:75], v[154:157], v[206:209], v[72:75]
	v_mfma_f32_16x16x32_bf16 v[92:95], v[146:149], v[214:217], v[92:95]
	v_mfma_f32_16x16x32_bf16 v[64:67], v[154:157], v[214:217], v[64:67]
	v_mfma_f32_16x16x32_bf16 v[80:83], v[146:149], v[224:227], v[80:83]
	v_mfma_f32_16x16x32_bf16 v[56:59], v[154:157], v[224:227], v[56:59]
	s_setprio 0
	s_setprio 1
	v_mfma_f32_16x16x32_bf16 v[44:47], v[158:161], v[194:197], 0
	v_mfma_f32_16x16x32_bf16 v[12:15], v[166:169], v[194:197], 0
	v_mfma_f32_16x16x32_bf16 v[36:39], v[158:161], v[202:205], 0
	v_mfma_f32_16x16x32_bf16 v[8:11], v[166:169], v[202:205], 0
	v_mfma_f32_16x16x32_bf16 v[28:31], v[158:161], v[210:213], 0
	v_mfma_f32_16x16x32_bf16 v[4:7], v[166:169], v[210:213], 0
	v_mfma_f32_16x16x32_bf16 v[20:23], v[158:161], v[218:221], 0
	v_mfma_f32_16x16x32_bf16 v[0:3], v[166:169], v[218:221], 0
	v_mfma_f32_16x16x32_bf16 v[44:47], v[162:165], v[198:201], v[44:47]
	v_mfma_f32_16x16x32_bf16 v[12:15], v[190:193], v[198:201], v[12:15]
	v_mfma_f32_16x16x32_bf16 v[36:39], v[162:165], v[206:209], v[36:39]
	v_mfma_f32_16x16x32_bf16 v[8:11], v[190:193], v[206:209], v[8:11]
	v_mfma_f32_16x16x32_bf16 v[28:31], v[162:165], v[214:217], v[28:31]
	v_mfma_f32_16x16x32_bf16 v[4:7], v[190:193], v[214:217], v[4:7]
	v_mfma_f32_16x16x32_bf16 v[20:23], v[162:165], v[224:227], v[20:23]
	v_mfma_f32_16x16x32_bf16 v[0:3], v[190:193], v[224:227], v[0:3]
	s_setprio 0
	s_barrier
	ds_read_b128 v[142:145], v182
	ds_read_b128 v[146:149], v183
	ds_read_b128 v[150:153], v184
	ds_read_b128 v[154:157], v185
	ds_read_b128 v[158:161], v186
	ds_read_b128 v[162:165], v187
	ds_read_b128 v[166:169], v188
	ds_read_b128 v[190:193], v189
	s_add_u32 s40, s54, 0x40000
	s_addc_u32 s41, s55, 0
	s_mov_b32 m0, s43
	v_lshl_add_u64 v[240:241], s[40:41], 0, v[128:129]
	ds_read_b128 v[194:197], v172 offset:32768
	ds_read_b128 v[198:201], v172 offset:33792
	ds_read_b128 v[202:205], v172 offset:34816
	ds_read_b128 v[206:209], v172 offset:35840
	ds_read_b128 v[210:213], v172 offset:36864
	ds_read_b128 v[214:217], v172 offset:37888
	ds_read_b128 v[218:221], v172 offset:38912
	ds_read_b128 v[224:227], v172 offset:39936
	global_load_lds_dwordx4 v[240:241], off
	v_lshl_add_u64 v[240:241], s[40:41], 0, v[130:131]
	s_mov_b32 m0, s56
	s_nop 0
	global_load_lds_dwordx4 v[240:241], off
	s_waitcnt vmcnt(8)
	s_waitcnt lgkmcnt(0)
	s_barrier
	s_setprio 1
	s_waitcnt lgkmcnt(0)
	v_mfma_f32_16x16x32_bf16 v[124:127], v[142:145], v[194:197], v[124:127]
	v_mfma_f32_16x16x32_bf16 v[108:111], v[150:153], v[194:197], v[108:111]
	v_mfma_f32_16x16x32_bf16 v[120:123], v[142:145], v[202:205], v[120:123]
	v_mfma_f32_16x16x32_bf16 v[96:99], v[150:153], v[202:205], v[96:99]
	v_mfma_f32_16x16x32_bf16 v[116:119], v[142:145], v[210:213], v[116:119]
	v_mfma_f32_16x16x32_bf16 v[88:91], v[150:153], v[210:213], v[88:91]
	v_mfma_f32_16x16x32_bf16 v[112:115], v[142:145], v[218:221], v[112:115]
	v_mfma_f32_16x16x32_bf16 v[84:87], v[150:153], v[218:221], v[84:87]
	v_mfma_f32_16x16x32_bf16 v[124:127], v[146:149], v[198:201], v[124:127]
	v_mfma_f32_16x16x32_bf16 v[108:111], v[154:157], v[198:201], v[108:111]
	v_mfma_f32_16x16x32_bf16 v[120:123], v[146:149], v[206:209], v[120:123]
	v_mfma_f32_16x16x32_bf16 v[96:99], v[154:157], v[206:209], v[96:99]
	v_mfma_f32_16x16x32_bf16 v[116:119], v[146:149], v[214:217], v[116:119]
	v_mfma_f32_16x16x32_bf16 v[88:91], v[154:157], v[214:217], v[88:91]
	v_mfma_f32_16x16x32_bf16 v[112:115], v[146:149], v[224:227], v[112:115]
	v_mfma_f32_16x16x32_bf16 v[84:87], v[154:157], v[224:227], v[84:87]
	s_setprio 0
	s_setprio 1
	v_mfma_f32_16x16x32_bf16 v[68:71], v[158:161], v[194:197], v[68:71]
	v_mfma_f32_16x16x32_bf16 v[40:43], v[166:169], v[194:197], v[40:43]
	v_mfma_f32_16x16x32_bf16 v[60:63], v[158:161], v[202:205], v[60:63]
	v_mfma_f32_16x16x32_bf16 v[32:35], v[166:169], v[202:205], v[32:35]
	v_mfma_f32_16x16x32_bf16 v[52:55], v[158:161], v[210:213], v[52:55]
	v_mfma_f32_16x16x32_bf16 v[24:27], v[166:169], v[210:213], v[24:27]
	v_mfma_f32_16x16x32_bf16 v[48:51], v[158:161], v[218:221], v[48:51]
	v_mfma_f32_16x16x32_bf16 v[16:19], v[166:169], v[218:221], v[16:19]
	v_mfma_f32_16x16x32_bf16 v[68:71], v[162:165], v[198:201], v[68:71]
	v_mfma_f32_16x16x32_bf16 v[40:43], v[190:193], v[198:201], v[40:43]
	v_mfma_f32_16x16x32_bf16 v[60:63], v[162:165], v[206:209], v[60:63]
	v_mfma_f32_16x16x32_bf16 v[32:35], v[190:193], v[206:209], v[32:35]
	v_mfma_f32_16x16x32_bf16 v[52:55], v[162:165], v[214:217], v[52:55]
	v_mfma_f32_16x16x32_bf16 v[24:27], v[190:193], v[214:217], v[24:27]
	v_mfma_f32_16x16x32_bf16 v[48:51], v[162:165], v[224:227], v[48:51]
	v_mfma_f32_16x16x32_bf16 v[16:19], v[190:193], v[224:227], v[16:19]
	s_setprio 0
	s_barrier
; #define PG8_STAGE(bufoff, gbase, voff) do { _Pragma("unroll") for (int _i = 0; _i < 2; ++_i) \
;         __builtin_amdgcn_global_load_lds((const unsigned*)((const char*)(gbase) + (voff)[_i]), (PG8_LAS unsigned*)(lds + (bufoff) + ldsw + _i * 8192), 16, 0, 0); } while (0)
; #define PG8_LDA(dst, b, h) do { _Pragma("unroll") for (int m = 0; m < 4; ++m) _Pragma("unroll") for (int k = 0; k < 2; ++k) dst[m][k] = *(const PG8_LAS bf16x8*)(lds + PG8_SA(b, h) + aoff + m * 2048 + k * 1024); } while (0)
; #define PG8_MMA(ai, bj, At, Bt) do { __builtin_amdgcn_s_setprio(1); _Pragma("unroll") for (int m = 0; m < 4; ++m) _Pragma("unroll") for (int n = 0; n < 2; ++n) _Pragma("unroll") for (int k = 0; k < 2; ++k) \
;         acc[ai][bj][m][n] = __builtin_amdgcn_mfma_f32_16x16x32_bf16(Bt[n][k], At[m][k], acc[ai][bj][m][n], 0, 0, 0); __builtin_amdgcn_s_setprio(0); } while (0)
; #define PG8_WAIT_V(n) asm volatile("s_waitcnt vmcnt(" #n ")" ::: "memory")
; #define PG8_WAIT_L(n) asm volatile("s_waitcnt lgkmcnt(" #n ")" ::: "memory")
; #define PG8_BAR __builtin_amdgcn_s_barrier()
; #define PG8_SCHED __builtin_amdgcn_sched_barrier(0)
; template <class Epi, class Sched, bool ALIGN_EPI = false, bool SP2 = false>
; __device__ __forceinline__ void gemm_phase(PG8_LAS unsigned char* lds, const Gemm g, const Sched& S, const Epi& E) {
;     ...
;             PG8_LDA(At, 1, 1); PG8_STAGE(PG8_SB(1, 0), b3, voffB); PG8_STAGE(PG8_SB(1, 1), b3 + hstep, voffB); PG8_STAGE(PG8_SA(1, 0), a3, voffA);
;             PG8_WAIT_V(8); PG8_WAIT_L(0); PG8_BAR; PG8_MMA(1, 0, At, B0); PG8_MMA(1, 1, At, B1); PG8_BAR; PG8_SCHED;
	s_mov_b32 m0, s60
	v_lshl_add_u64 v[170:171], v[170:171], 0, s[10:11]
	s_add_u32 s40, s52, 0x40080
	ds_read_b128 v[194:197], v172 offset:49152
	ds_read_b128 v[198:201], v172 offset:50176
	ds_read_b128 v[202:205], v172 offset:51200
	ds_read_b128 v[206:209], v172 offset:52224
	ds_read_b128 v[210:213], v172 offset:53248
	ds_read_b128 v[214:217], v172 offset:54272
	ds_read_b128 v[218:221], v172 offset:55296
	ds_read_b128 v[224:227], v172 offset:56320
	global_load_lds_dwordx4 v[170:171], off
	v_lshl_add_u64 v[170:171], v[228:229], 0, s[10:11]
	s_mov_b32 m0, s61
	s_addc_u32 s41, s53, 0
	global_load_lds_dwordx4 v[170:171], off
	v_lshl_add_u64 v[170:171], s[40:41], 0, v[128:129]
	s_mov_b32 m0, s64
	s_nop 0
	global_load_lds_dwordx4 v[170:171], off
	v_lshl_add_u64 v[170:171], s[40:41], 0, v[130:131]
	s_mov_b32 m0, s65
	s_nop 0
	global_load_lds_dwordx4 v[170:171], off
	v_lshl_add_u64 v[170:171], v[236:237], 0, s[10:11]
	s_mov_b32 m0, s62
	s_nop 0
	global_load_lds_dwordx4 v[170:171], off
	v_lshl_add_u64 v[170:171], v[238:239], 0, s[10:11]
	s_mov_b32 m0, s63
	s_nop 0
	global_load_lds_dwordx4 v[170:171], off
	s_waitcnt vmcnt(8)
	s_waitcnt lgkmcnt(0)
	s_barrier
	s_setprio 1
	s_waitcnt lgkmcnt(0)
	v_mfma_f32_16x16x32_bf16 v[104:107], v[142:145], v[194:197], v[104:107]
	v_mfma_f32_16x16x32_bf16 v[76:79], v[150:153], v[194:197], v[76:79]
	v_mfma_f32_16x16x32_bf16 v[100:103], v[142:145], v[202:205], v[100:103]
	v_mfma_f32_16x16x32_bf16 v[72:75], v[150:153], v[202:205], v[72:75]
	v_mfma_f32_16x16x32_bf16 v[92:95], v[142:145], v[210:213], v[92:95]
	v_mfma_f32_16x16x32_bf16 v[64:67], v[150:153], v[210:213], v[64:67]
	v_mfma_f32_16x16x32_bf16 v[80:83], v[142:145], v[218:221], v[80:83]
	v_mfma_f32_16x16x32_bf16 v[56:59], v[150:153], v[218:221], v[56:59]
	v_mfma_f32_16x16x32_bf16 v[104:107], v[146:149], v[198:201], v[104:107]
	v_mfma_f32_16x16x32_bf16 v[76:79], v[154:157], v[198:201], v[76:79]
	v_mfma_f32_16x16x32_bf16 v[100:103], v[146:149], v[206:209], v[100:103]
	v_mfma_f32_16x16x32_bf16 v[72:75], v[154:157], v[206:209], v[72:75]
	v_mfma_f32_16x16x32_bf16 v[92:95], v[146:149], v[214:217], v[92:95]
	v_mfma_f32_16x16x32_bf16 v[64:67], v[154:157], v[214:217], v[64:67]
	v_mfma_f32_16x16x32_bf16 v[80:83], v[146:149], v[224:227], v[80:83]
	v_mfma_f32_16x16x32_bf16 v[56:59], v[154:157], v[224:227], v[56:59]
	s_setprio 0
	s_setprio 1
	v_mfma_f32_16x16x32_bf16 v[44:47], v[158:161], v[194:197], v[44:47]
	v_mfma_f32_16x16x32_bf16 v[12:15], v[166:169], v[194:197], v[12:15]
	v_mfma_f32_16x16x32_bf16 v[36:39], v[158:161], v[202:205], v[36:39]
	v_mfma_f32_16x16x32_bf16 v[8:11], v[166:169], v[202:205], v[8:11]
	v_mfma_f32_16x16x32_bf16 v[28:31], v[158:161], v[210:213], v[28:31]
	v_mfma_f32_16x16x32_bf16 v[4:7], v[166:169], v[210:213], v[4:7]
	v_mfma_f32_16x16x32_bf16 v[20:23], v[158:161], v[218:221], v[20:23]
	v_mfma_f32_16x16x32_bf16 v[0:3], v[166:169], v[218:221], v[0:3]
	v_mfma_f32_16x16x32_bf16 v[44:47], v[162:165], v[198:201], v[44:47]
	v_mfma_f32_16x16x32_bf16 v[12:15], v[190:193], v[198:201], v[12:15]
	v_mfma_f32_16x16x32_bf16 v[36:39], v[162:165], v[206:209], v[36:39]
	v_mfma_f32_16x16x32_bf16 v[8:11], v[190:193], v[206:209], v[8:11]
	v_mfma_f32_16x16x32_bf16 v[28:31], v[162:165], v[214:217], v[28:31]
	v_mfma_f32_16x16x32_bf16 v[4:7], v[190:193], v[214:217], v[4:7]
	v_mfma_f32_16x16x32_bf16 v[20:23], v[162:165], v[224:227], v[20:23]
	v_mfma_f32_16x16x32_bf16 v[0:3], v[190:193], v[224:227], v[0:3]
	s_setprio 0
	s_barrier
	s_add_i32 s79, s79, 2
	s_add_u32 s77, s77, 0x100
	s_addc_u32 s78, s78, 0
	s_mov_b64 s[40:41], s[50:51]

;     __host__ __device__ bool next(int i, Unit& u) const { const int L = i * G + c; if (L >= 16 * nkc) return false; u.kc = L % nkc; const int t = L / nkc; u.pn = t & 3; u.pm = 33 * (t >> 2); return true; }
; #define PG8_STAGE(bufoff, gbase, voff) do { _Pragma("unroll") for (int _i = 0; _i < 2; ++_i) \
;         __builtin_amdgcn_global_load_lds((const unsigned*)((const char*)(gbase) + (voff)[_i]), (PG8_LAS unsigned*)(lds + (bufoff) + ldsw + _i * 8192), 16, 0, 0); } while (0)
; #define PG8_LDA(dst, b, h) do { _Pragma("unroll") for (int m = 0; m < 4; ++m) _Pragma("unroll") for (int k = 0; k < 2; ++k) dst[m][k] = *(const PG8_LAS bf16x8*)(lds + PG8_SA(b, h) + aoff + m * 2048 + k * 1024); } while (0)
; #define PG8_LDB(dst, b, h) do { _Pragma("unroll") for (int n = 0; n < 2; ++n) _Pragma("unroll") for (int k = 0; k < 2; ++k) dst[n][k] = *(const PG8_LAS bf16x8*)(lds + PG8_SB(b, h) + boff + n * 2048 + k * 1024); } while (0)
; #define PG8_BAR __builtin_amdgcn_s_barrier()
; template <class Epi, class Sched, bool ALIGN_EPI = false, bool SP2 = false>
; __device__ __forceinline__ void gemm_phase(PG8_LAS unsigned char* lds, const Gemm g, const Sched& S, const Epi& E) {
;     ...
;         const bool has_next = S.next(ui + 1, nxt);
;         const char* nA = has_next ? (const char*)g.A + (size_t)nxt.pm * tstep + (size_t)nxt.kc * cstep : cA; const char* nB = has_next ? (const char*)g.Bt + (size_t)nxt.pn * tstep + (size_t)nxt.kc * cstep : cB;
;         for (int t = 0; t < nt; t += 2) {
;             const bool last = (t == nt - 2);
;             const char* a1 = cA + (size_t)(t + 1) * kstep;
;             const char* a2 = last ? nA : cA + (size_t)(t + 2) * kstep; const char* b2 = last ? nB : cB + (size_t)(t + 2) * kstep;
;             const char* a3 = a2 + kstep; const char* b3 = b2 + kstep;
;             if (last && has_next) S.a_ready(nxt);
;             if constexpr (SP2) {
;             PG8_LDB(B0, 0, 0); PG8_LDB(B1, 0, 1); PG8_SCHED; PG8_LDA(At, 0, 0); PG8_STAGE(PG8_SA(1, 1), a1 + hstep, voffA);
;             PG8_WAIT_V(8); PG8_WAIT_L(0); PG8_BAR; PG8_MMA(0, 0, At, B0); PG8_MMA(0, 1, At, B1); PG8_BAR; PG8_SCHED;
;             PG8_LDA(At, 0, 1); PG8_STAGE(PG8_SB(0, 0), b2, voffB); PG8_STAGE(PG8_SB(0, 1), b2 + hstep, voffB); PG8_STAGE(PG8_SA(0, 0), a2, voffA);
;             PG8_WAIT_V(8); PG8_WAIT_L(0); PG8_BAR; PG8_MMA(1, 0, At, B0); PG8_MMA(1, 1, At, B1); PG8_BAR; PG8_SCHED;
.LBB0_1437:
	s_ashr_i32 s19, s18, 31
	s_lshl_b64 s[20:21], s[18:19], 19
	s_add_u32 s20, s46, s20
	s_addc_u32 s21, s47, s21
	s_and_b64 s[22:23], s[6:7], exec
	s_cselect_b32 s19, s21, s37
	s_cselect_b32 s66, s20, s36
	s_ashr_i32 s17, s16, 31
	s_lshl_b64 s[22:23], s[16:17], 19
	s_add_u32 s22, s1, s22
	s_addc_u32 s23, s3, s23
	s_and_b64 s[50:51], s[6:7], exec
	s_cselect_b32 s17, s23, s41
	s_cselect_b32 s67, s22, s40
	s_add_u32 s36, s36, 0x40080
	s_addc_u32 s37, s37, 0
	s_add_u32 s68, s40, 0x100
	s_addc_u32 s69, s41, 0
	s_mov_b32 s70, -2
	ds_read_b128 v[166:169], v149
	ds_read_b128 v[170:173], v150
	ds_read_b128 v[174:177], v151
	ds_read_b128 v[178:181], v152
	ds_read_b128 v[182:185], v153
	ds_read_b128 v[186:189], v154
	ds_read_b128 v[190:193], v155
	ds_read_b128 v[194:197], v156
	s_add_u32 s40, s36, 0xfffc0080
	s_addc_u32 s41, s37, -1
	s_cmp_eq_u32 s70, 12
	s_cselect_b32 s51, s19, s41
	s_cselect_b32 s50, s66, s40
	s_cselect_b32 s41, s17, s69
	s_cselect_b32 s40, s67, s68
	s_mov_b32 m0, s63
	v_lshl_add_u64 v[144:145], s[36:37], 0, v[136:137]
	ds_read_b128 v[198:201], v147
	ds_read_b128 v[202:205], v147 offset:1024
	ds_read_b128 v[206:209], v147 offset:2048
	ds_read_b128 v[210:213], v147 offset:3072
	ds_read_b128 v[214:217], v147 offset:4096
	ds_read_b128 v[218:221], v147 offset:5120
	ds_read_b128 v[224:227], v147 offset:6144
	ds_read_b128 v[236:239], v147 offset:7168
	global_load_lds_dwordx4 v[144:145], off
	v_lshl_add_u64 v[144:145], s[36:37], 0, v[138:139]
	s_mov_b32 m0, s64
	s_nop 0
	global_load_lds_dwordx4 v[144:145], off
	s_waitcnt vmcnt(8)
	s_waitcnt lgkmcnt(0)
	s_barrier
	s_setprio 1
	s_waitcnt lgkmcnt(0)
	v_mfma_f32_16x16x32_bf16 v[124:127], v[166:169], v[198:201], 0
	v_mfma_f32_16x16x32_bf16 v[120:123], v[174:177], v[198:201], 0
	v_mfma_f32_16x16x32_bf16 v[108:111], v[166:169], v[206:209], 0
	v_mfma_f32_16x16x32_bf16 v[104:107], v[174:177], v[206:209], 0
	v_mfma_f32_16x16x32_bf16 v[92:95], v[166:169], v[214:217], 0
	v_mfma_f32_16x16x32_bf16 v[88:91], v[174:177], v[214:217], 0
	v_mfma_f32_16x16x32_bf16 v[76:79], v[166:169], v[224:227], 0
	v_mfma_f32_16x16x32_bf16 v[72:75], v[174:177], v[224:227], 0
	v_mfma_f32_16x16x32_bf16 v[124:127], v[170:173], v[202:205], v[124:127]
	v_mfma_f32_16x16x32_bf16 v[120:123], v[178:181], v[202:205], v[120:123]
	v_mfma_f32_16x16x32_bf16 v[108:111], v[170:173], v[210:213], v[108:111]
	v_mfma_f32_16x16x32_bf16 v[104:107], v[178:181], v[210:213], v[104:107]
	v_mfma_f32_16x16x32_bf16 v[92:95], v[170:173], v[218:221], v[92:95]
	v_mfma_f32_16x16x32_bf16 v[88:91], v[178:181], v[218:221], v[88:91]
	v_mfma_f32_16x16x32_bf16 v[76:79], v[170:173], v[236:239], v[76:79]
	v_mfma_f32_16x16x32_bf16 v[72:75], v[178:181], v[236:239], v[72:75]
	s_setprio 0
	s_setprio 1
	v_mfma_f32_16x16x32_bf16 v[116:119], v[182:185], v[198:201], 0
	v_mfma_f32_16x16x32_bf16 v[112:115], v[190:193], v[198:201], 0
	v_mfma_f32_16x16x32_bf16 v[100:103], v[182:185], v[206:209], 0
	v_mfma_f32_16x16x32_bf16 v[96:99], v[190:193], v[206:209], 0
	v_mfma_f32_16x16x32_bf16 v[84:87], v[182:185], v[214:217], 0
	v_mfma_f32_16x16x32_bf16 v[80:83], v[190:193], v[214:217], 0
	v_mfma_f32_16x16x32_bf16 v[68:71], v[182:185], v[224:227], 0
	v_mfma_f32_16x16x32_bf16 v[64:67], v[190:193], v[224:227], 0
	v_mfma_f32_16x16x32_bf16 v[116:119], v[186:189], v[202:205], v[116:119]
	v_mfma_f32_16x16x32_bf16 v[112:115], v[194:197], v[202:205], v[112:115]
	v_mfma_f32_16x16x32_bf16 v[100:103], v[186:189], v[210:213], v[100:103]
	v_mfma_f32_16x16x32_bf16 v[96:99], v[194:197], v[210:213], v[96:99]
	v_mfma_f32_16x16x32_bf16 v[84:87], v[186:189], v[218:221], v[84:87]
	v_mfma_f32_16x16x32_bf16 v[80:83], v[194:197], v[218:221], v[80:83]
	v_mfma_f32_16x16x32_bf16 v[68:71], v[186:189], v[236:239], v[68:71]
	v_mfma_f32_16x16x32_bf16 v[64:67], v[194:197], v[236:239], v[64:67]
	s_setprio 0
	s_barrier
	s_mov_b32 m0, s15
	v_lshl_add_u64 v[144:145], s[40:41], 0, v[132:133]
	s_add_u32 s72, s40, 0x40000
	ds_read_b128 v[198:201], v147 offset:16384
	ds_read_b128 v[202:205], v147 offset:17408
	ds_read_b128 v[206:209], v147 offset:18432
	ds_read_b128 v[210:213], v147 offset:19456
	ds_read_b128 v[214:217], v147 offset:20480
	ds_read_b128 v[218:221], v147 offset:21504
	ds_read_b128 v[224:227], v147 offset:22528
	ds_read_b128 v[236:239], v147 offset:23552
	global_load_lds_dwordx4 v[144:145], off
	v_lshl_add_u64 v[228:229], s[40:41], 0, v[128:129]
	s_mov_b32 m0, s25
	s_addc_u32 s73, s41, 0
	global_load_lds_dwordx4 v[228:229], off
	v_lshl_add_u64 v[240:241], s[72:73], 0, v[132:133]
	s_mov_b32 m0, s39
	v_lshl_add_u64 v[242:243], s[50:51], 0, v[130:131]
	global_load_lds_dwordx4 v[240:241], off
	v_lshl_add_u64 v[240:241], s[72:73], 0, v[128:129]
	s_mov_b32 m0, s43
	s_nop 0
	global_load_lds_dwordx4 v[240:241], off
	v_lshl_add_u64 v[240:241], s[50:51], 0, v[134:135]
	s_mov_b32 m0, s4
	s_nop 0
	global_load_lds_dwordx4 v[240:241], off
	s_mov_b32 m0, s52
	s_nop 0
	global_load_lds_dwordx4 v[242:243], off
	s_waitcnt vmcnt(8)
	s_waitcnt lgkmcnt(0)
	s_barrier
; #define PG8_STAGE(bufoff, gbase, voff) do { _Pragma("unroll") for (int _i = 0; _i < 2; ++_i) \
;         __builtin_amdgcn_global_load_lds((const unsigned*)((const char*)(gbase) + (voff)[_i]), (PG8_LAS unsigned*)(lds + (bufoff) + ldsw + _i * 8192), 16, 0, 0); } while (0)
; #define PG8_LDA(dst, b, h) do { _Pragma("unroll") for (int m = 0; m < 4; ++m) _Pragma("unroll") for (int k = 0; k < 2; ++k) dst[m][k] = *(const PG8_LAS bf16x8*)(lds + PG8_SA(b, h) + aoff + m * 2048 + k * 1024); } while (0)
; #define PG8_LDB(dst, b, h) do { _Pragma("unroll") for (int n = 0; n < 2; ++n) _Pragma("unroll") for (int k = 0; k < 2; ++k) dst[n][k] = *(const PG8_LAS bf16x8*)(lds + PG8_SB(b, h) + boff + n * 2048 + k * 1024); } while (0)
; #define PG8_MMA(ai, bj, At, Bt) do { __builtin_amdgcn_s_setprio(1); _Pragma("unroll") for (int m = 0; m < 4; ++m) _Pragma("unroll") for (int n = 0; n < 2; ++n) _Pragma("unroll") for (int k = 0; k < 2; ++k) \
;         acc[ai][bj][m][n] = __builtin_amdgcn_mfma_f32_16x16x32_bf16(Bt[n][k], At[m][k], acc[ai][bj][m][n], 0, 0, 0); __builtin_amdgcn_s_setprio(0); } while (0)
; #define PG8_WAIT_V(n) asm volatile("s_waitcnt vmcnt(" #n ")" ::: "memory")
; #define PG8_WAIT_L(n) asm volatile("s_waitcnt lgkmcnt(" #n ")" ::: "memory")
; #define PG8_BAR __builtin_amdgcn_s_barrier()
; #define PG8_SCHED __builtin_amdgcn_sched_barrier(0)
; template <class Epi, class Sched, bool ALIGN_EPI = false, bool SP2 = false>
; __device__ __forceinline__ void gemm_phase(PG8_LAS unsigned char* lds, const Gemm g, const Sched& S, const Epi& E) {
;     ...
;             PG8_WAIT_V(8); PG8_WAIT_L(0); PG8_BAR; PG8_MMA(1, 0, At, B0); PG8_MMA(1, 1, At, B1); PG8_BAR; PG8_SCHED;
;             PG8_LDB(B0, 1, 0); PG8_LDB(B1, 1, 1); PG8_SCHED; PG8_LDA(At, 1, 0); PG8_STAGE(PG8_SA(0, 1), a2 + hstep, voffA);
;             PG8_WAIT_V(8); PG8_WAIT_L(0); PG8_BAR; PG8_MMA(0, 0, At, B0); PG8_MMA(0, 1, At, B1); PG8_BAR; PG8_SCHED;
	s_setprio 1
	s_waitcnt lgkmcnt(0)
	v_mfma_f32_16x16x32_bf16 v[60:63], v[166:169], v[198:201], 0
	v_mfma_f32_16x16x32_bf16 v[56:59], v[174:177], v[198:201], 0
	v_mfma_f32_16x16x32_bf16 v[44:47], v[166:169], v[206:209], 0
	v_mfma_f32_16x16x32_bf16 v[40:43], v[174:177], v[206:209], 0
	v_mfma_f32_16x16x32_bf16 v[28:31], v[166:169], v[214:217], 0
	v_mfma_f32_16x16x32_bf16 v[24:27], v[174:177], v[214:217], 0
	v_mfma_f32_16x16x32_bf16 v[12:15], v[166:169], v[224:227], 0
	v_mfma_f32_16x16x32_bf16 v[8:11], v[174:177], v[224:227], 0
	v_mfma_f32_16x16x32_bf16 v[60:63], v[170:173], v[202:205], v[60:63]
	v_mfma_f32_16x16x32_bf16 v[56:59], v[178:181], v[202:205], v[56:59]
	v_mfma_f32_16x16x32_bf16 v[44:47], v[170:173], v[210:213], v[44:47]
	v_mfma_f32_16x16x32_bf16 v[40:43], v[178:181], v[210:213], v[40:43]
	v_mfma_f32_16x16x32_bf16 v[28:31], v[170:173], v[218:221], v[28:31]
	v_mfma_f32_16x16x32_bf16 v[24:27], v[178:181], v[218:221], v[24:27]
	v_mfma_f32_16x16x32_bf16 v[12:15], v[170:173], v[236:239], v[12:15]
	v_mfma_f32_16x16x32_bf16 v[8:11], v[178:181], v[236:239], v[8:11]
	s_setprio 0
	s_setprio 1
	v_mfma_f32_16x16x32_bf16 v[52:55], v[182:185], v[198:201], 0
	v_mfma_f32_16x16x32_bf16 v[48:51], v[190:193], v[198:201], 0
	v_mfma_f32_16x16x32_bf16 v[36:39], v[182:185], v[206:209], 0
	v_mfma_f32_16x16x32_bf16 v[32:35], v[190:193], v[206:209], 0
	v_mfma_f32_16x16x32_bf16 v[20:23], v[182:185], v[214:217], 0
	v_mfma_f32_16x16x32_bf16 v[16:19], v[190:193], v[214:217], 0
	v_mfma_f32_16x16x32_bf16 v[4:7], v[182:185], v[224:227], 0
	v_mfma_f32_16x16x32_bf16 v[0:3], v[190:193], v[224:227], 0
	v_mfma_f32_16x16x32_bf16 v[52:55], v[186:189], v[202:205], v[52:55]
	v_mfma_f32_16x16x32_bf16 v[48:51], v[194:197], v[202:205], v[48:51]
	v_mfma_f32_16x16x32_bf16 v[36:39], v[186:189], v[210:213], v[36:39]
	v_mfma_f32_16x16x32_bf16 v[32:35], v[194:197], v[210:213], v[32:35]
	v_mfma_f32_16x16x32_bf16 v[20:23], v[186:189], v[218:221], v[20:23]
	v_mfma_f32_16x16x32_bf16 v[16:19], v[194:197], v[218:221], v[16:19]
	v_mfma_f32_16x16x32_bf16 v[4:7], v[186:189], v[236:239], v[4:7]
	v_mfma_f32_16x16x32_bf16 v[0:3], v[194:197], v[236:239], v[0:3]
	s_setprio 0
	s_barrier
	ds_read_b128 v[166:169], v157
	ds_read_b128 v[170:173], v158
	ds_read_b128 v[174:177], v159
	ds_read_b128 v[178:181], v160
	ds_read_b128 v[182:185], v161
	ds_read_b128 v[186:189], v162
	ds_read_b128 v[190:193], v163
	ds_read_b128 v[194:197], v164
	s_add_u32 s50, s50, 0x40000
	s_addc_u32 s51, s51, 0
	s_mov_b32 m0, s53
	v_lshl_add_u64 v[244:245], s[50:51], 0, v[134:135]
	ds_read_b128 v[198:201], v147 offset:32768
	ds_read_b128 v[202:205], v147 offset:33792
	ds_read_b128 v[206:209], v147 offset:34816
	ds_read_b128 v[210:213], v147 offset:35840
	ds_read_b128 v[214:217], v147 offset:36864
	ds_read_b128 v[218:221], v147 offset:37888
	ds_read_b128 v[224:227], v147 offset:38912
	ds_read_b128 v[236:239], v147 offset:39936
	global_load_lds_dwordx4 v[244:245], off
	v_lshl_add_u64 v[244:245], s[50:51], 0, v[130:131]
	s_mov_b32 m0, s54
	s_nop 0
	global_load_lds_dwordx4 v[244:245], off
	s_waitcnt vmcnt(8)
	s_waitcnt lgkmcnt(0)
	s_barrier
	s_setprio 1
	s_waitcnt lgkmcnt(0)
	v_mfma_f32_16x16x32_bf16 v[124:127], v[166:169], v[198:201], v[124:127]
	v_mfma_f32_16x16x32_bf16 v[120:123], v[174:177], v[198:201], v[120:123]
	v_mfma_f32_16x16x32_bf16 v[108:111], v[166:169], v[206:209], v[108:111]
	v_mfma_f32_16x16x32_bf16 v[104:107], v[174:177], v[206:209], v[104:107]
	v_mfma_f32_16x16x32_bf16 v[92:95], v[166:169], v[214:217], v[92:95]
	v_mfma_f32_16x16x32_bf16 v[88:91], v[174:177], v[214:217], v[88:91]
	v_mfma_f32_16x16x32_bf16 v[76:79], v[166:169], v[224:227], v[76:79]
	v_mfma_f32_16x16x32_bf16 v[72:75], v[174:177], v[224:227], v[72:75]
	v_mfma_f32_16x16x32_bf16 v[124:127], v[170:173], v[202:205], v[124:127]
	v_mfma_f32_16x16x32_bf16 v[120:123], v[178:181], v[202:205], v[120:123]
	v_mfma_f32_16x16x32_bf16 v[108:111], v[170:173], v[210:213], v[108:111]
	v_mfma_f32_16x16x32_bf16 v[104:107], v[178:181], v[210:213], v[104:107]
	v_mfma_f32_16x16x32_bf16 v[92:95], v[170:173], v[218:221], v[92:95]
	v_mfma_f32_16x16x32_bf16 v[88:91], v[178:181], v[218:221], v[88:91]
	v_mfma_f32_16x16x32_bf16 v[76:79], v[170:173], v[236:239], v[76:79]
	v_mfma_f32_16x16x32_bf16 v[72:75], v[178:181], v[236:239], v[72:75]
	s_setprio 0
	s_setprio 1
	v_mfma_f32_16x16x32_bf16 v[116:119], v[182:185], v[198:201], v[116:119]
	v_mfma_f32_16x16x32_bf16 v[112:115], v[190:193], v[198:201], v[112:115]
	v_mfma_f32_16x16x32_bf16 v[100:103], v[182:185], v[206:209], v[100:103]
	v_mfma_f32_16x16x32_bf16 v[96:99], v[190:193], v[206:209], v[96:99]
	v_mfma_f32_16x16x32_bf16 v[84:87], v[182:185], v[214:217], v[84:87]
	v_mfma_f32_16x16x32_bf16 v[80:83], v[190:193], v[214:217], v[80:83]
	v_mfma_f32_16x16x32_bf16 v[68:71], v[182:185], v[224:227], v[68:71]
	v_mfma_f32_16x16x32_bf16 v[64:67], v[190:193], v[224:227], v[64:67]
	v_mfma_f32_16x16x32_bf16 v[116:119], v[186:189], v[202:205], v[116:119]
	v_mfma_f32_16x16x32_bf16 v[112:115], v[194:197], v[202:205], v[112:115]
	v_mfma_f32_16x16x32_bf16 v[100:103], v[186:189], v[210:213], v[100:103]
	v_mfma_f32_16x16x32_bf16 v[96:99], v[194:197], v[210:213], v[96:99]
	v_mfma_f32_16x16x32_bf16 v[84:87], v[186:189], v[218:221], v[84:87]
	v_mfma_f32_16x16x32_bf16 v[80:83], v[194:197], v[218:221], v[80:83]
	v_mfma_f32_16x16x32_bf16 v[68:71], v[186:189], v[236:239], v[68:71]
	v_mfma_f32_16x16x32_bf16 v[64:67], v[194:197], v[236:239], v[64:67]
	s_setprio 0
	s_barrier
; #define PG8_STAGE(bufoff, gbase, voff) do { _Pragma("unroll") for (int _i = 0; _i < 2; ++_i) \
;         __builtin_amdgcn_global_load_lds((const unsigned*)((const char*)(gbase) + (voff)[_i]), (PG8_LAS unsigned*)(lds + (bufoff) + ldsw + _i * 8192), 16, 0, 0); } while (0)
; #define PG8_LDA(dst, b, h) do { _Pragma("unroll") for (int m = 0; m < 4; ++m) _Pragma("unroll") for (int k = 0; k < 2; ++k) dst[m][k] = *(const PG8_LAS bf16x8*)(lds + PG8_SA(b, h) + aoff + m * 2048 + k * 1024); } while (0)
; #define PG8_MMA(ai, bj, At, Bt) do { __builtin_amdgcn_s_setprio(1); _Pragma("unroll") for (int m = 0; m < 4; ++m) _Pragma("unroll") for (int n = 0; n < 2; ++n) _Pragma("unroll") for (int k = 0; k < 2; ++k) \
;         acc[ai][bj][m][n] = __builtin_amdgcn_mfma_f32_16x16x32_bf16(Bt[n][k], At[m][k], acc[ai][bj][m][n], 0, 0, 0); __builtin_amdgcn_s_setprio(0); } while (0)
; #define PG8_WAIT_V(n) asm volatile("s_waitcnt vmcnt(" #n ")" ::: "memory")
; #define PG8_WAIT_L(n) asm volatile("s_waitcnt lgkmcnt(" #n ")" ::: "memory")
; #define PG8_BAR __builtin_amdgcn_s_barrier()
; #define PG8_SCHED __builtin_amdgcn_sched_barrier(0)
; template <class Epi, class Sched, bool ALIGN_EPI = false, bool SP2 = false>
; __device__ __forceinline__ void gemm_phase(PG8_LAS unsigned char* lds, const Gemm g, const Sched& S, const Epi& E) {
;     ...
;             PG8_LDA(At, 1, 1); PG8_STAGE(PG8_SB(1, 0), b3, voffB); PG8_STAGE(PG8_SB(1, 1), b3 + hstep, voffB); PG8_STAGE(PG8_SA(1, 0), a3, voffA);
;             PG8_WAIT_V(8); PG8_WAIT_L(0); PG8_BAR; PG8_MMA(1, 0, At, B0); PG8_MMA(1, 1, At, B1); PG8_BAR; PG8_SCHED;
	s_mov_b32 m0, s56
	v_lshl_add_u64 v[144:145], v[144:145], 0, s[10:11]
	s_add_u32 s40, s40, 0x40080
	ds_read_b128 v[198:201], v147 offset:49152
	ds_read_b128 v[202:205], v147 offset:50176
	ds_read_b128 v[206:209], v147 offset:51200
	ds_read_b128 v[210:213], v147 offset:52224
	ds_read_b128 v[214:217], v147 offset:53248
	ds_read_b128 v[218:221], v147 offset:54272
	ds_read_b128 v[224:227], v147 offset:55296
	ds_read_b128 v[236:239], v147 offset:56320
	global_load_lds_dwordx4 v[144:145], off
	v_lshl_add_u64 v[144:145], v[228:229], 0, s[10:11]
	s_mov_b32 m0, s57
	s_addc_u32 s41, s41, 0
	global_load_lds_dwordx4 v[144:145], off
	v_lshl_add_u64 v[144:145], s[40:41], 0, v[132:133]
	s_mov_b32 m0, s60
	s_nop 0
	global_load_lds_dwordx4 v[144:145], off
	v_lshl_add_u64 v[144:145], s[40:41], 0, v[128:129]
	s_mov_b32 m0, s61
	s_nop 0
	global_load_lds_dwordx4 v[144:145], off
	v_lshl_add_u64 v[144:145], v[240:241], 0, s[10:11]
	s_mov_b32 m0, s58
	s_nop 0
	global_load_lds_dwordx4 v[144:145], off
	v_lshl_add_u64 v[144:145], v[242:243], 0, s[10:11]
	s_mov_b32 m0, s59
	s_nop 0
	global_load_lds_dwordx4 v[144:145], off
	s_waitcnt vmcnt(8)
	s_waitcnt lgkmcnt(0)
	s_barrier
	s_setprio 1
	s_waitcnt lgkmcnt(0)
	v_mfma_f32_16x16x32_bf16 v[60:63], v[166:169], v[198:201], v[60:63]
	v_mfma_f32_16x16x32_bf16 v[56:59], v[174:177], v[198:201], v[56:59]
	v_mfma_f32_16x16x32_bf16 v[44:47], v[166:169], v[206:209], v[44:47]
	v_mfma_f32_16x16x32_bf16 v[40:43], v[174:177], v[206:209], v[40:43]
	v_mfma_f32_16x16x32_bf16 v[28:31], v[166:169], v[214:217], v[28:31]
	v_mfma_f32_16x16x32_bf16 v[24:27], v[174:177], v[214:217], v[24:27]
	v_mfma_f32_16x16x32_bf16 v[12:15], v[166:169], v[224:227], v[12:15]
	v_mfma_f32_16x16x32_bf16 v[8:11], v[174:177], v[224:227], v[8:11]
	v_mfma_f32_16x16x32_bf16 v[60:63], v[170:173], v[202:205], v[60:63]
	v_mfma_f32_16x16x32_bf16 v[56:59], v[178:181], v[202:205], v[56:59]
	v_mfma_f32_16x16x32_bf16 v[44:47], v[170:173], v[210:213], v[44:47]
	v_mfma_f32_16x16x32_bf16 v[40:43], v[178:181], v[210:213], v[40:43]
	v_mfma_f32_16x16x32_bf16 v[28:31], v[170:173], v[218:221], v[28:31]
	v_mfma_f32_16x16x32_bf16 v[24:27], v[178:181], v[218:221], v[24:27]
	v_mfma_f32_16x16x32_bf16 v[12:15], v[170:173], v[236:239], v[12:15]
	v_mfma_f32_16x16x32_bf16 v[8:11], v[178:181], v[236:239], v[8:11]
	s_setprio 0
	s_setprio 1
	v_mfma_f32_16x16x32_bf16 v[52:55], v[182:185], v[198:201], v[52:55]
	v_mfma_f32_16x16x32_bf16 v[48:51], v[190:193], v[198:201], v[48:51]
	v_mfma_f32_16x16x32_bf16 v[36:39], v[182:185], v[206:209], v[36:39]
	v_mfma_f32_16x16x32_bf16 v[32:35], v[190:193], v[206:209], v[32:35]
	v_mfma_f32_16x16x32_bf16 v[20:23], v[182:185], v[214:217], v[20:23]
	v_mfma_f32_16x16x32_bf16 v[16:19], v[190:193], v[214:217], v[16:19]
	v_mfma_f32_16x16x32_bf16 v[4:7], v[182:185], v[224:227], v[4:7]
	v_mfma_f32_16x16x32_bf16 v[0:3], v[190:193], v[224:227], v[0:3]
	v_mfma_f32_16x16x32_bf16 v[52:55], v[186:189], v[202:205], v[52:55]
	v_mfma_f32_16x16x32_bf16 v[48:51], v[194:197], v[202:205], v[48:51]
	v_mfma_f32_16x16x32_bf16 v[36:39], v[186:189], v[210:213], v[36:39]
	v_mfma_f32_16x16x32_bf16 v[32:35], v[194:197], v[210:213], v[32:35]
	v_mfma_f32_16x16x32_bf16 v[20:23], v[186:189], v[218:221], v[20:23]
	v_mfma_f32_16x16x32_bf16 v[16:19], v[194:197], v[218:221], v[16:19]
	v_mfma_f32_16x16x32_bf16 v[4:7], v[186:189], v[236:239], v[4:7]
	v_mfma_f32_16x16x32_bf16 v[0:3], v[194:197], v[236:239], v[0:3]
	s_setprio 0
	s_barrier
	s_add_i32 s70, s70, 2
	s_add_u32 s36, s36, 0x100
	s_addc_u32 s37, s37, 0
	s_add_u32 s68, s68, 0x100
	s_addc_u32 s69, s69, 0

; #define PG8_STAGE(bufoff, gbase, voff) do { _Pragma("unroll") for (int _i = 0; _i < 2; ++_i) \
;         __builtin_amdgcn_global_load_lds((const unsigned*)((const char*)(gbase) + (voff)[_i]), (PG8_LAS unsigned*)(lds + (bufoff) + ldsw + _i * 8192), 16, 0, 0); } while (0)
; #define PG8_LDA(dst, b, h) do { _Pragma("unroll") for (int m = 0; m < 4; ++m) _Pragma("unroll") for (int k = 0; k < 2; ++k) dst[m][k] = *(const PG8_LAS bf16x8*)(lds + PG8_SA(b, h) + aoff + m * 2048 + k * 1024); } while (0)
; #define PG8_LDB(dst, b, h) do { _Pragma("unroll") for (int n = 0; n < 2; ++n) _Pragma("unroll") for (int k = 0; k < 2; ++k) dst[n][k] = *(const PG8_LAS bf16x8*)(lds + PG8_SB(b, h) + boff + n * 2048 + k * 1024); } while (0)
; #define PG8_WAIT_V(n) asm volatile("s_waitcnt vmcnt(" #n ")" ::: "memory")
; #define PG8_WAIT_L(n) asm volatile("s_waitcnt lgkmcnt(" #n ")" ::: "memory")
; #define PG8_BAR __builtin_amdgcn_s_barrier()
; template <class Epi, class Sched, bool ALIGN_EPI = false, bool SP2 = false>
; __device__ __forceinline__ void gemm_phase(PG8_LAS unsigned char* lds, const Gemm g, const Sched& S, const Epi& E) {
;     ...
;         for (int t = 0; t < nt; t += 2) {
;             const bool last = (t == nt - 2);
;             const char* a1 = cA + (size_t)(t + 1) * kstep;
;             const char* a2 = last ? nA : cA + (size_t)(t + 2) * kstep; const char* b2 = last ? nB : cB + (size_t)(t + 2) * kstep;
;             const char* a3 = a2 + kstep; const char* b3 = b2 + kstep;
;             if (last && has_next) S.a_ready(nxt);
;             if constexpr (SP2) {
;             PG8_LDB(B0, 0, 0); PG8_LDB(B1, 0, 1); PG8_SCHED; PG8_LDA(At, 0, 0); PG8_STAGE(PG8_SA(1, 1), a1 + hstep, voffA);
;             PG8_WAIT_V(8); PG8_WAIT_L(0); PG8_BAR; PG8_MMA(0, 0, At, B0); PG8_MMA(0, 1, At, B1); PG8_BAR; PG8_SCHED;
;             PG8_LDA(At, 0, 1); PG8_STAGE(PG8_SB(0, 0), b2, voffB); PG8_STAGE(PG8_SB(0, 1), b2 + hstep, voffB); PG8_STAGE(PG8_SA(0, 0), a2, voffA);
;             PG8_WAIT_V(8); PG8_WAIT_L(0); PG8_BAR; PG8_MMA(1, 0, At, B0); PG8_MMA(1, 1, At, B1); PG8_BAR; PG8_SCHED;
;     ...
;         for (int a = 0; a < 2; ++a)
; #pragma unroll
;             for (int b = 0; b < 2; ++b)
; #pragma unroll
;                 for (int m = 0; m < 4; ++m)
; #pragma unroll
;                     for (int n = 0; n < 2; ++n) acc[a][b][m][n] = (f32x4){0.f, 0.f, 0.f, 0.f};
.LBB0_1517:
	s_add_u32 s33, s22, 0x100
	s_addc_u32 s72, s23, 0
	s_mov_b32 s73, -2
	ds_read_b128 v[142:145], v174
	ds_read_b128 v[146:149], v175
	ds_read_b128 v[150:153], v176
	ds_read_b128 v[154:157], v177
	ds_read_b128 v[158:161], v178
	ds_read_b128 v[162:165], v179
	ds_read_b128 v[166:169], v180
	ds_read_b128 v[190:193], v181
	s_add_u32 s22, s20, 0x100
	s_addc_u32 s23, s21, 0
	s_cmp_eq_u32 s73, 40
	s_cselect_b32 s37, s5, s23
	s_cselect_b32 s36, s4, s22
	s_cselect_b32 s25, s17, s72
	s_cselect_b32 s24, s16, s33
	s_mov_b32 m0, s62
	v_lshl_add_u64 v[170:171], s[20:21], 0, v[134:135]
	ds_read_b128 v[194:197], v172
	ds_read_b128 v[198:201], v172 offset:1024
	ds_read_b128 v[202:205], v172 offset:2048
	ds_read_b128 v[206:209], v172 offset:3072
	ds_read_b128 v[210:213], v172 offset:4096
	ds_read_b128 v[214:217], v172 offset:5120
	ds_read_b128 v[218:221], v172 offset:6144
	ds_read_b128 v[224:227], v172 offset:7168
	global_load_lds_dwordx4 v[170:171], off
	v_lshl_add_u64 v[170:171], s[20:21], 0, v[136:137]
	s_mov_b32 m0, s63
	s_nop 0
	global_load_lds_dwordx4 v[170:171], off
	s_waitcnt vmcnt(8)
	s_waitcnt lgkmcnt(0)
	s_barrier
	s_setprio 1
	s_waitcnt lgkmcnt(0)
	v_mfma_f32_16x16x32_bf16 v[124:127], v[142:145], v[194:197], 0
	v_mfma_f32_16x16x32_bf16 v[108:111], v[150:153], v[194:197], 0
	v_mfma_f32_16x16x32_bf16 v[120:123], v[142:145], v[202:205], 0
	v_mfma_f32_16x16x32_bf16 v[96:99], v[150:153], v[202:205], 0
	v_mfma_f32_16x16x32_bf16 v[116:119], v[142:145], v[210:213], 0
	v_mfma_f32_16x16x32_bf16 v[88:91], v[150:153], v[210:213], 0
	v_mfma_f32_16x16x32_bf16 v[112:115], v[142:145], v[218:221], 0
	v_mfma_f32_16x16x32_bf16 v[84:87], v[150:153], v[218:221], 0
	v_mfma_f32_16x16x32_bf16 v[124:127], v[146:149], v[198:201], v[124:127]
	v_mfma_f32_16x16x32_bf16 v[108:111], v[154:157], v[198:201], v[108:111]
	v_mfma_f32_16x16x32_bf16 v[120:123], v[146:149], v[206:209], v[120:123]
	v_mfma_f32_16x16x32_bf16 v[96:99], v[154:157], v[206:209], v[96:99]
	v_mfma_f32_16x16x32_bf16 v[116:119], v[146:149], v[214:217], v[116:119]
	v_mfma_f32_16x16x32_bf16 v[88:91], v[154:157], v[214:217], v[88:91]
	v_mfma_f32_16x16x32_bf16 v[112:115], v[146:149], v[224:227], v[112:115]
	v_mfma_f32_16x16x32_bf16 v[84:87], v[154:157], v[224:227], v[84:87]
	s_setprio 0
	s_setprio 1
	v_mfma_f32_16x16x32_bf16 v[68:71], v[158:161], v[194:197], 0
	v_mfma_f32_16x16x32_bf16 v[40:43], v[166:169], v[194:197], 0
	v_mfma_f32_16x16x32_bf16 v[60:63], v[158:161], v[202:205], 0
	v_mfma_f32_16x16x32_bf16 v[32:35], v[166:169], v[202:205], 0
	v_mfma_f32_16x16x32_bf16 v[52:55], v[158:161], v[210:213], 0
	v_mfma_f32_16x16x32_bf16 v[24:27], v[166:169], v[210:213], 0
	v_mfma_f32_16x16x32_bf16 v[48:51], v[158:161], v[218:221], 0
	v_mfma_f32_16x16x32_bf16 v[16:19], v[166:169], v[218:221], 0
	v_mfma_f32_16x16x32_bf16 v[68:71], v[162:165], v[198:201], v[68:71]
	v_mfma_f32_16x16x32_bf16 v[40:43], v[190:193], v[198:201], v[40:43]
	v_mfma_f32_16x16x32_bf16 v[60:63], v[162:165], v[206:209], v[60:63]
	v_mfma_f32_16x16x32_bf16 v[32:35], v[190:193], v[206:209], v[32:35]
	v_mfma_f32_16x16x32_bf16 v[52:55], v[162:165], v[214:217], v[52:55]
	v_mfma_f32_16x16x32_bf16 v[24:27], v[190:193], v[214:217], v[24:27]
	v_mfma_f32_16x16x32_bf16 v[48:51], v[162:165], v[224:227], v[48:51]
	v_mfma_f32_16x16x32_bf16 v[16:19], v[190:193], v[224:227], v[16:19]
	s_setprio 0
	s_barrier
	s_mov_b32 m0, s39
	v_lshl_add_u64 v[170:171], s[24:25], 0, v[128:129]
	s_add_u32 s20, s24, 0xb0000
	ds_read_b128 v[194:197], v172 offset:16384
	ds_read_b128 v[198:201], v172 offset:17408
	ds_read_b128 v[202:205], v172 offset:18432
	ds_read_b128 v[206:209], v172 offset:19456
	ds_read_b128 v[210:213], v172 offset:20480
	ds_read_b128 v[214:217], v172 offset:21504
	ds_read_b128 v[218:221], v172 offset:22528
	ds_read_b128 v[224:227], v172 offset:23552
	global_load_lds_dwordx4 v[170:171], off
	v_lshl_add_u64 v[228:229], s[24:25], 0, v[130:131]
	s_mov_b32 m0, s40
	s_addc_u32 s21, s25, 0
	global_load_lds_dwordx4 v[228:229], off
	v_lshl_add_u64 v[236:237], s[20:21], 0, v[128:129]
	s_mov_b32 m0, s41
	v_lshl_add_u64 v[238:239], s[36:37], 0, v[130:131]
	global_load_lds_dwordx4 v[236:237], off
	v_lshl_add_u64 v[236:237], s[20:21], 0, v[130:131]
	s_mov_b32 m0, s43
	s_nop 0
	global_load_lds_dwordx4 v[236:237], off
	v_lshl_add_u64 v[236:237], s[36:37], 0, v[128:129]
	s_mov_b32 m0, s15
	s_nop 0
	global_load_lds_dwordx4 v[236:237], off
	s_mov_b32 m0, s46
	s_nop 0
	global_load_lds_dwordx4 v[238:239], off
	s_waitcnt vmcnt(8)
	s_waitcnt lgkmcnt(0)
	s_barrier
	s_setprio 1
	s_waitcnt lgkmcnt(0)
	v_mfma_f32_16x16x32_bf16 v[104:107], v[142:145], v[194:197], 0
	v_mfma_f32_16x16x32_bf16 v[76:79], v[150:153], v[194:197], 0
	v_mfma_f32_16x16x32_bf16 v[100:103], v[142:145], v[202:205], 0
	v_mfma_f32_16x16x32_bf16 v[72:75], v[150:153], v[202:205], 0
	v_mfma_f32_16x16x32_bf16 v[92:95], v[142:145], v[210:213], 0
	v_mfma_f32_16x16x32_bf16 v[64:67], v[150:153], v[210:213], 0
	v_mfma_f32_16x16x32_bf16 v[80:83], v[142:145], v[218:221], 0
	v_mfma_f32_16x16x32_bf16 v[56:59], v[150:153], v[218:221], 0
	v_mfma_f32_16x16x32_bf16 v[104:107], v[146:149], v[198:201], v[104:107]
	v_mfma_f32_16x16x32_bf16 v[76:79], v[154:157], v[198:201], v[76:79]
	v_mfma_f32_16x16x32_bf16 v[100:103], v[146:149], v[206:209], v[100:103]
	v_mfma_f32_16x16x32_bf16 v[72:75], v[154:157], v[206:209], v[72:75]
	v_mfma_f32_16x16x32_bf16 v[92:95], v[146:149], v[214:217], v[92:95]
	v_mfma_f32_16x16x32_bf16 v[64:67], v[154:157], v[214:217], v[64:67]
	v_mfma_f32_16x16x32_bf16 v[80:83], v[146:149], v[224:227], v[80:83]
	v_mfma_f32_16x16x32_bf16 v[56:59], v[154:157], v[224:227], v[56:59]
	s_setprio 0
	s_setprio 1
	v_mfma_f32_16x16x32_bf16 v[44:47], v[158:161], v[194:197], 0
	v_mfma_f32_16x16x32_bf16 v[12:15], v[166:169], v[194:197], 0
	v_mfma_f32_16x16x32_bf16 v[36:39], v[158:161], v[202:205], 0
	v_mfma_f32_16x16x32_bf16 v[8:11], v[166:169], v[202:205], 0
	v_mfma_f32_16x16x32_bf16 v[28:31], v[158:161], v[210:213], 0
	v_mfma_f32_16x16x32_bf16 v[4:7], v[166:169], v[210:213], 0
	v_mfma_f32_16x16x32_bf16 v[20:23], v[158:161], v[218:221], 0
	v_mfma_f32_16x16x32_bf16 v[0:3], v[166:169], v[218:221], 0
	v_mfma_f32_16x16x32_bf16 v[44:47], v[162:165], v[198:201], v[44:47]
	v_mfma_f32_16x16x32_bf16 v[12:15], v[190:193], v[198:201], v[12:15]
	v_mfma_f32_16x16x32_bf16 v[36:39], v[162:165], v[206:209], v[36:39]
	v_mfma_f32_16x16x32_bf16 v[8:11], v[190:193], v[206:209], v[8:11]
	v_mfma_f32_16x16x32_bf16 v[28:31], v[162:165], v[214:217], v[28:31]
	v_mfma_f32_16x16x32_bf16 v[4:7], v[190:193], v[214:217], v[4:7]
	v_mfma_f32_16x16x32_bf16 v[20:23], v[162:165], v[224:227], v[20:23]
	v_mfma_f32_16x16x32_bf16 v[0:3], v[190:193], v[224:227], v[0:3]
	s_setprio 0
	s_barrier
; #define PG8_STAGE(bufoff, gbase, voff) do { _Pragma("unroll") for (int _i = 0; _i < 2; ++_i) \
;         __builtin_amdgcn_global_load_lds((const unsigned*)((const char*)(gbase) + (voff)[_i]), (PG8_LAS unsigned*)(lds + (bufoff) + ldsw + _i * 8192), 16, 0, 0); } while (0)
; #define PG8_LDA(dst, b, h) do { _Pragma("unroll") for (int m = 0; m < 4; ++m) _Pragma("unroll") for (int k = 0; k < 2; ++k) dst[m][k] = *(const PG8_LAS bf16x8*)(lds + PG8_SA(b, h) + aoff + m * 2048 + k * 1024); } while (0)
; #define PG8_LDB(dst, b, h) do { _Pragma("unroll") for (int n = 0; n < 2; ++n) _Pragma("unroll") for (int k = 0; k < 2; ++k) dst[n][k] = *(const PG8_LAS bf16x8*)(lds + PG8_SB(b, h) + boff + n * 2048 + k * 1024); } while (0)
; #define PG8_MMA(ai, bj, At, Bt) do { __builtin_amdgcn_s_setprio(1); _Pragma("unroll") for (int m = 0; m < 4; ++m) _Pragma("unroll") for (int n = 0; n < 2; ++n) _Pragma("unroll") for (int k = 0; k < 2; ++k) \
;         acc[ai][bj][m][n] = __builtin_amdgcn_mfma_f32_16x16x32_bf16(Bt[n][k], At[m][k], acc[ai][bj][m][n], 0, 0, 0); __builtin_amdgcn_s_setprio(0); } while (0)
; #define PG8_WAIT_V(n) asm volatile("s_waitcnt vmcnt(" #n ")" ::: "memory")
; #define PG8_WAIT_L(n) asm volatile("s_waitcnt lgkmcnt(" #n ")" ::: "memory")
; #define PG8_BAR __builtin_amdgcn_s_barrier()
; #define PG8_SCHED __builtin_amdgcn_sched_barrier(0)
; template <class Epi, class Sched, bool ALIGN_EPI = false, bool SP2 = false>
; __device__ __forceinline__ void gemm_phase(PG8_LAS unsigned char* lds, const Gemm g, const Sched& S, const Epi& E) {
;     ...
;             PG8_LDB(B0, 1, 0); PG8_LDB(B1, 1, 1); PG8_SCHED; PG8_LDA(At, 1, 0); PG8_STAGE(PG8_SA(0, 1), a2 + hstep, voffA);
;             PG8_WAIT_V(8); PG8_WAIT_L(0); PG8_BAR; PG8_MMA(0, 0, At, B0); PG8_MMA(0, 1, At, B1); PG8_BAR; PG8_SCHED;
;             PG8_LDA(At, 1, 1); PG8_STAGE(PG8_SB(1, 0), b3, voffB); PG8_STAGE(PG8_SB(1, 1), b3 + hstep, voffB); PG8_STAGE(PG8_SA(1, 0), a3, voffA);
;             PG8_WAIT_V(8); PG8_WAIT_L(0); PG8_BAR; PG8_MMA(1, 0, At, B0); PG8_MMA(1, 1, At, B1); PG8_BAR; PG8_SCHED;
	ds_read_b128 v[142:145], v182
	ds_read_b128 v[146:149], v183
	ds_read_b128 v[150:153], v184
	ds_read_b128 v[154:157], v185
	ds_read_b128 v[158:161], v186
	ds_read_b128 v[162:165], v187
	ds_read_b128 v[166:169], v188
	ds_read_b128 v[190:193], v189
	s_add_u32 s20, s36, 0xb0000
	s_addc_u32 s21, s37, 0
	s_mov_b32 m0, s47
	v_lshl_add_u64 v[240:241], s[20:21], 0, v[128:129]
	ds_read_b128 v[194:197], v172 offset:32768
	ds_read_b128 v[198:201], v172 offset:33792
	ds_read_b128 v[202:205], v172 offset:34816
	ds_read_b128 v[206:209], v172 offset:35840
	ds_read_b128 v[210:213], v172 offset:36864
	ds_read_b128 v[214:217], v172 offset:37888
	ds_read_b128 v[218:221], v172 offset:38912
	ds_read_b128 v[224:227], v172 offset:39936
	global_load_lds_dwordx4 v[240:241], off
	v_lshl_add_u64 v[240:241], s[20:21], 0, v[130:131]
	s_mov_b32 m0, s50
	s_nop 0
	global_load_lds_dwordx4 v[240:241], off
	s_waitcnt vmcnt(8)
	s_waitcnt lgkmcnt(0)
	s_barrier
	s_setprio 1
	s_waitcnt lgkmcnt(0)
	v_mfma_f32_16x16x32_bf16 v[124:127], v[142:145], v[194:197], v[124:127]
	v_mfma_f32_16x16x32_bf16 v[108:111], v[150:153], v[194:197], v[108:111]
	v_mfma_f32_16x16x32_bf16 v[120:123], v[142:145], v[202:205], v[120:123]
	v_mfma_f32_16x16x32_bf16 v[96:99], v[150:153], v[202:205], v[96:99]
	v_mfma_f32_16x16x32_bf16 v[116:119], v[142:145], v[210:213], v[116:119]
	v_mfma_f32_16x16x32_bf16 v[88:91], v[150:153], v[210:213], v[88:91]
	v_mfma_f32_16x16x32_bf16 v[112:115], v[142:145], v[218:221], v[112:115]
	v_mfma_f32_16x16x32_bf16 v[84:87], v[150:153], v[218:221], v[84:87]
	v_mfma_f32_16x16x32_bf16 v[124:127], v[146:149], v[198:201], v[124:127]
	v_mfma_f32_16x16x32_bf16 v[108:111], v[154:157], v[198:201], v[108:111]
	v_mfma_f32_16x16x32_bf16 v[120:123], v[146:149], v[206:209], v[120:123]
	v_mfma_f32_16x16x32_bf16 v[96:99], v[154:157], v[206:209], v[96:99]
	v_mfma_f32_16x16x32_bf16 v[116:119], v[146:149], v[214:217], v[116:119]
	v_mfma_f32_16x16x32_bf16 v[88:91], v[154:157], v[214:217], v[88:91]
	v_mfma_f32_16x16x32_bf16 v[112:115], v[146:149], v[224:227], v[112:115]
	v_mfma_f32_16x16x32_bf16 v[84:87], v[154:157], v[224:227], v[84:87]
	s_setprio 0
	s_setprio 1
	v_mfma_f32_16x16x32_bf16 v[68:71], v[158:161], v[194:197], v[68:71]
	v_mfma_f32_16x16x32_bf16 v[40:43], v[166:169], v[194:197], v[40:43]
	v_mfma_f32_16x16x32_bf16 v[60:63], v[158:161], v[202:205], v[60:63]
	v_mfma_f32_16x16x32_bf16 v[32:35], v[166:169], v[202:205], v[32:35]
	v_mfma_f32_16x16x32_bf16 v[52:55], v[158:161], v[210:213], v[52:55]
	v_mfma_f32_16x16x32_bf16 v[24:27], v[166:169], v[210:213], v[24:27]
	v_mfma_f32_16x16x32_bf16 v[48:51], v[158:161], v[218:221], v[48:51]
	v_mfma_f32_16x16x32_bf16 v[16:19], v[166:169], v[218:221], v[16:19]
	v_mfma_f32_16x16x32_bf16 v[68:71], v[162:165], v[198:201], v[68:71]
	v_mfma_f32_16x16x32_bf16 v[40:43], v[190:193], v[198:201], v[40:43]
	v_mfma_f32_16x16x32_bf16 v[60:63], v[162:165], v[206:209], v[60:63]
	v_mfma_f32_16x16x32_bf16 v[32:35], v[190:193], v[206:209], v[32:35]
	v_mfma_f32_16x16x32_bf16 v[52:55], v[162:165], v[214:217], v[52:55]
	v_mfma_f32_16x16x32_bf16 v[24:27], v[190:193], v[214:217], v[24:27]
	v_mfma_f32_16x16x32_bf16 v[48:51], v[162:165], v[224:227], v[48:51]
	v_mfma_f32_16x16x32_bf16 v[16:19], v[190:193], v[224:227], v[16:19]
	s_setprio 0
	s_barrier
	s_mov_b32 m0, s54
	v_lshl_add_u64 v[170:171], v[170:171], 0, s[10:11]
	s_add_u32 s20, s24, 0xb0080
	ds_read_b128 v[194:197], v172 offset:49152
	ds_read_b128 v[198:201], v172 offset:50176
	ds_read_b128 v[202:205], v172 offset:51200
	ds_read_b128 v[206:209], v172 offset:52224
	ds_read_b128 v[210:213], v172 offset:53248
	ds_read_b128 v[214:217], v172 offset:54272
	ds_read_b128 v[218:221], v172 offset:55296
	ds_read_b128 v[224:227], v172 offset:56320
	global_load_lds_dwordx4 v[170:171], off
	v_lshl_add_u64 v[170:171], v[228:229], 0, s[10:11]
	s_mov_b32 m0, s55
	s_addc_u32 s21, s25, 0
	global_load_lds_dwordx4 v[170:171], off
	v_lshl_add_u64 v[170:171], s[20:21], 0, v[128:129]
	s_mov_b32 m0, s58
	s_nop 0
	global_load_lds_dwordx4 v[170:171], off
	v_lshl_add_u64 v[170:171], s[20:21], 0, v[130:131]
	s_mov_b32 m0, s59
	s_nop 0
	global_load_lds_dwordx4 v[170:171], off
	v_lshl_add_u64 v[170:171], v[236:237], 0, s[10:11]
	s_mov_b32 m0, s56
	s_nop 0
	global_load_lds_dwordx4 v[170:171], off
	v_lshl_add_u64 v[170:171], v[238:239], 0, s[10:11]
	s_mov_b32 m0, s57
	s_nop 0
	global_load_lds_dwordx4 v[170:171], off
	s_waitcnt vmcnt(8)
	s_waitcnt lgkmcnt(0)
	s_barrier
	s_setprio 1
	s_waitcnt lgkmcnt(0)
	v_mfma_f32_16x16x32_bf16 v[104:107], v[142:145], v[194:197], v[104:107]
	v_mfma_f32_16x16x32_bf16 v[76:79], v[150:153], v[194:197], v[76:79]
	v_mfma_f32_16x16x32_bf16 v[100:103], v[142:145], v[202:205], v[100:103]
	v_mfma_f32_16x16x32_bf16 v[72:75], v[150:153], v[202:205], v[72:75]
	v_mfma_f32_16x16x32_bf16 v[92:95], v[142:145], v[210:213], v[92:95]
	v_mfma_f32_16x16x32_bf16 v[64:67], v[150:153], v[210:213], v[64:67]
	v_mfma_f32_16x16x32_bf16 v[80:83], v[142:145], v[218:221], v[80:83]
	v_mfma_f32_16x16x32_bf16 v[56:59], v[150:153], v[218:221], v[56:59]
	v_mfma_f32_16x16x32_bf16 v[104:107], v[146:149], v[198:201], v[104:107]
	v_mfma_f32_16x16x32_bf16 v[76:79], v[154:157], v[198:201], v[76:79]
	v_mfma_f32_16x16x32_bf16 v[100:103], v[146:149], v[206:209], v[100:103]
	v_mfma_f32_16x16x32_bf16 v[72:75], v[154:157], v[206:209], v[72:75]
	v_mfma_f32_16x16x32_bf16 v[92:95], v[146:149], v[214:217], v[92:95]
	v_mfma_f32_16x16x32_bf16 v[64:67], v[154:157], v[214:217], v[64:67]
	v_mfma_f32_16x16x32_bf16 v[80:83], v[146:149], v[224:227], v[80:83]
	v_mfma_f32_16x16x32_bf16 v[56:59], v[154:157], v[224:227], v[56:59]
	s_setprio 0
	s_setprio 1
	v_mfma_f32_16x16x32_bf16 v[44:47], v[158:161], v[194:197], v[44:47]
	v_mfma_f32_16x16x32_bf16 v[12:15], v[166:169], v[194:197], v[12:15]
	v_mfma_f32_16x16x32_bf16 v[36:39], v[158:161], v[202:205], v[36:39]
	v_mfma_f32_16x16x32_bf16 v[8:11], v[166:169], v[202:205], v[8:11]
	v_mfma_f32_16x16x32_bf16 v[28:31], v[158:161], v[210:213], v[28:31]
	v_mfma_f32_16x16x32_bf16 v[4:7], v[166:169], v[210:213], v[4:7]
	v_mfma_f32_16x16x32_bf16 v[20:23], v[158:161], v[218:221], v[20:23]
	v_mfma_f32_16x16x32_bf16 v[0:3], v[166:169], v[218:221], v[0:3]
	v_mfma_f32_16x16x32_bf16 v[44:47], v[162:165], v[198:201], v[44:47]
	v_mfma_f32_16x16x32_bf16 v[12:15], v[190:193], v[198:201], v[12:15]
	v_mfma_f32_16x16x32_bf16 v[36:39], v[162:165], v[206:209], v[36:39]
	v_mfma_f32_16x16x32_bf16 v[8:11], v[190:193], v[206:209], v[8:11]
	v_mfma_f32_16x16x32_bf16 v[28:31], v[162:165], v[214:217], v[28:31]
	v_mfma_f32_16x16x32_bf16 v[4:7], v[190:193], v[214:217], v[4:7]
	v_mfma_f32_16x16x32_bf16 v[20:23], v[162:165], v[224:227], v[20:23]
	v_mfma_f32_16x16x32_bf16 v[0:3], v[190:193], v[224:227], v[0:3]
	s_setprio 0
	s_barrier
	s_add_i32 s73, s73, 2
	s_add_u32 s33, s33, 0x100
	s_addc_u32 s72, s72, 0
	s_mov_b64 s[20:21], s[22:23]
